# s_setprio flips moved off the barrier-to-first-MFMA and last-MFMA-to-barrier paths in the GEMM loops; on top of v36
# speedup vs baseline: 1.0076x; 1.0027x over previous
; #define PG8_STAGEX(rs, bufoff, soff, voff) do { _Pragma("unroll") for (int _i = 0; _i < 2; ++_i) \
;         __builtin_amdgcn_raw_ptr_buffer_load_lds(rs, (LAS unsigned*)(lds + (bufoff) + ldsw + _i * 8192), 16, (voff)[_i], (soff), 0, 0); } while (0)
; #define PG8_LDA(dst, b, h) do { _Pragma("unroll") for (int m = 0; m < 4; ++m) _Pragma("unroll") for (int k = 0; k < 2; ++k) dst[m][k] = *(const LAS bf16x8*)(lds + PG8_SA(b, h) + aoff + m * 2048 + k * 1024); } while (0)
; #define PG8_LDB(dst, b, h) do { _Pragma("unroll") for (int n = 0; n < 2; ++n) _Pragma("unroll") for (int k = 0; k < 2; ++k) dst[n][k] = *(const LAS bf16x8*)(lds + PG8_SB(b, h) + boff + n * 2048 + k * 1024); } while (0)
; #define PG8_WAIT_V(n) asm volatile("s_waitcnt vmcnt(" #n ")" ::: "memory")
; #define PG8_WAIT_L(n) asm volatile("s_waitcnt lgkmcnt(" #n ")" ::: "memory")
; #define PG8_BAR __builtin_amdgcn_s_barrier()
; #define PG8_SCHED __builtin_amdgcn_sched_barrier(0)
;     ...
;             PG8_LDB(B0, 0, 0); PG8_LDB(B1, 0, 1); PG8_SCHED; PG8_LDA(At, 0, 0); PG8_STAGEX(rsA, PG8_SA(1, 1), a1 + hstepA, voffA);
;             PG8_WAIT_V(8); PG8_WAIT_L(0); PG8_BAR; PG8_MMA(0, 0, At, B0); PG8_MMA(0, 1, At, B1); PG8_BAR; PG8_SCHED;
;             PG8_LDA(At, 0, 1); PG8_STAGEX(rsB, PG8_SB(0, 0), b2, voffB); PG8_STAGEX(rsB, PG8_SB(0, 1), b2 + hstepB, voffB); PG8_STAGEX(rsA, PG8_SA(0, 0), a2, voffA);
;             PG8_WAIT_V(8); PG8_WAIT_L(0); PG8_BAR; PG8_MMA(1, 0, At, B0); PG8_MMA(1, 1, At, B1); PG8_BAR; PG8_SCHED;
.LBB0_223:
	v_add_u32_e32 v102, 0x10000, v172
	v_add_u32_e32 v146, 0x14000, v172
	ds_read_b128 v[82:85], v102
	ds_read_b128 v[86:89], v102 offset:1024
	ds_read_b128 v[98:101], v102 offset:2048
	ds_read_b128 v[102:105], v102 offset:3072
	ds_read_b128 v[150:153], v146
	ds_read_b128 v[154:157], v146 offset:1024
	ds_read_b128 v[182:185], v146 offset:2048
	ds_read_b128 v[186:189], v146 offset:3072
	s_add_i32 s42, s50, 0xfff80080
	s_cmp_eq_u32 s52, 28
	s_cselect_b32 s55, s30, s42
	s_cselect_b32 s54, s31, s51
	s_or_b32 s53, s55, 0x80
	s_mov_b32 m0, s22
	ds_read_b128 v[190:193], v173
	ds_read_b128 v[194:197], v173 offset:1024
	ds_read_b128 v[198:201], v173 offset:2048
	ds_read_b128 v[202:205], v173 offset:3072
	ds_read_b128 v[206:209], v173 offset:4096
	ds_read_b128 v[210:213], v173 offset:5120
	ds_read_b128 v[214:217], v173 offset:6144
	ds_read_b128 v[218:221], v173 offset:7168
	buffer_load_dwordx4 v159, s[76:79], s50 offen lds
	s_mov_b32 m0, s23
	s_nop 0
	buffer_load_dwordx4 v163, s[76:79], s50 offen lds
	s_waitcnt vmcnt(8)
	s_waitcnt lgkmcnt(0)
	s_setprio 1
	s_barrier
	v_mfma_f32_16x16x32_bf16 v[142:145], v[82:85], v[190:193], v[142:145]
	v_mfma_f32_16x16x32_bf16 v[134:137], v[98:101], v[190:193], v[134:137]
	v_mfma_f32_16x16x32_bf16 v[126:129], v[82:85], v[198:201], v[126:129]
	v_mfma_f32_16x16x32_bf16 v[118:121], v[98:101], v[198:201], v[118:121]
	v_mfma_f32_16x16x32_bf16 v[110:113], v[82:85], v[206:209], v[110:113]
	v_mfma_f32_16x16x32_bf16 v[94:97], v[98:101], v[206:209], v[94:97]
	v_mfma_f32_16x16x32_bf16 v[78:81], v[82:85], v[214:217], v[78:81]
	v_mfma_f32_16x16x32_bf16 v[70:73], v[98:101], v[214:217], v[70:73]
	v_mfma_f32_16x16x32_bf16 v[142:145], v[86:89], v[194:197], v[142:145]
	v_mfma_f32_16x16x32_bf16 v[134:137], v[102:105], v[194:197], v[134:137]
	v_mfma_f32_16x16x32_bf16 v[126:129], v[86:89], v[202:205], v[126:129]
	v_mfma_f32_16x16x32_bf16 v[118:121], v[102:105], v[202:205], v[118:121]
	v_mfma_f32_16x16x32_bf16 v[110:113], v[86:89], v[210:213], v[110:113]
	v_mfma_f32_16x16x32_bf16 v[94:97], v[102:105], v[210:213], v[94:97]
	v_mfma_f32_16x16x32_bf16 v[78:81], v[86:89], v[218:221], v[78:81]
	v_mfma_f32_16x16x32_bf16 v[70:73], v[102:105], v[218:221], v[70:73]
	v_mfma_f32_16x16x32_bf16 v[138:141], v[150:153], v[190:193], v[138:141]
	v_mfma_f32_16x16x32_bf16 v[130:133], v[182:185], v[190:193], v[130:133]
	v_mfma_f32_16x16x32_bf16 v[122:125], v[150:153], v[198:201], v[122:125]
	v_mfma_f32_16x16x32_bf16 v[114:117], v[182:185], v[198:201], v[114:117]
	v_mfma_f32_16x16x32_bf16 v[106:109], v[150:153], v[206:209], v[106:109]
	v_mfma_f32_16x16x32_bf16 v[90:93], v[182:185], v[206:209], v[90:93]
	v_mfma_f32_16x16x32_bf16 v[74:77], v[150:153], v[214:217], v[74:77]
	v_mfma_f32_16x16x32_bf16 v[66:69], v[182:185], v[214:217], v[66:69]
	v_mfma_f32_16x16x32_bf16 v[138:141], v[154:157], v[194:197], v[138:141]
	v_mfma_f32_16x16x32_bf16 v[130:133], v[186:189], v[194:197], v[130:133]
	v_mfma_f32_16x16x32_bf16 v[122:125], v[154:157], v[202:205], v[122:125]
	v_mfma_f32_16x16x32_bf16 v[114:117], v[186:189], v[202:205], v[114:117]
	v_mfma_f32_16x16x32_bf16 v[106:109], v[154:157], v[210:213], v[106:109]
	v_mfma_f32_16x16x32_bf16 v[90:93], v[186:189], v[210:213], v[90:93]
	v_mfma_f32_16x16x32_bf16 v[74:77], v[154:157], v[218:221], v[74:77]
	v_mfma_f32_16x16x32_bf16 v[66:69], v[186:189], v[218:221], v[66:69]
	s_barrier
	s_setprio 0
	s_mov_b32 m0, s9
	s_mov_b32 s42, s78
	s_mov_b32 s43, s79
	ds_read_b128 v[190:193], v173 offset:16384
	ds_read_b128 v[194:197], v173 offset:17408
	ds_read_b128 v[198:201], v173 offset:18432
	ds_read_b128 v[202:205], v173 offset:19456
	ds_read_b128 v[206:209], v173 offset:20480
	ds_read_b128 v[210:213], v173 offset:21504
	ds_read_b128 v[214:217], v173 offset:22528
	ds_read_b128 v[218:221], v173 offset:23552
	buffer_load_dwordx4 v161, s[40:43], s54 offen lds
	s_mov_b32 m0, s10
	s_add_i32 s56, s54, 0x80000
	buffer_load_dwordx4 v165, s[40:43], s54 offen lds
	s_mov_b32 m0, s11
	s_nop 0
	buffer_load_dwordx4 v161, s[40:43], s56 offen lds
	s_mov_b32 m0, s12
	s_nop 0
	buffer_load_dwordx4 v165, s[40:43], s56 offen lds
	s_mov_b32 m0, s8
	s_nop 0
	buffer_load_dwordx4 v159, s[76:79], s55 offen lds
	s_mov_b32 m0, s13
	s_nop 0
	buffer_load_dwordx4 v163, s[76:79], s55 offen lds
	s_waitcnt vmcnt(8)
	s_waitcnt lgkmcnt(0)
	s_setprio 1
	s_barrier
	v_mfma_f32_16x16x32_bf16 v[62:65], v[82:85], v[190:193], v[62:65]
	v_mfma_f32_16x16x32_bf16 v[54:57], v[98:101], v[190:193], v[54:57]
	v_mfma_f32_16x16x32_bf16 v[46:49], v[82:85], v[198:201], v[46:49]
	v_mfma_f32_16x16x32_bf16 v[38:41], v[98:101], v[198:201], v[38:41]
	v_mfma_f32_16x16x32_bf16 v[30:33], v[82:85], v[206:209], v[30:33]
	v_mfma_f32_16x16x32_bf16 v[22:25], v[98:101], v[206:209], v[22:25]
	v_mfma_f32_16x16x32_bf16 v[14:17], v[82:85], v[214:217], v[14:17]
	v_mfma_f32_16x16x32_bf16 v[6:9], v[98:101], v[214:217], v[6:9]
	v_mfma_f32_16x16x32_bf16 v[62:65], v[86:89], v[194:197], v[62:65]
	v_mfma_f32_16x16x32_bf16 v[54:57], v[102:105], v[194:197], v[54:57]
	v_mfma_f32_16x16x32_bf16 v[46:49], v[86:89], v[202:205], v[46:49]
	v_mfma_f32_16x16x32_bf16 v[38:41], v[102:105], v[202:205], v[38:41]
	v_mfma_f32_16x16x32_bf16 v[30:33], v[86:89], v[210:213], v[30:33]
	v_mfma_f32_16x16x32_bf16 v[22:25], v[102:105], v[210:213], v[22:25]
	v_mfma_f32_16x16x32_bf16 v[14:17], v[86:89], v[218:221], v[14:17]
	v_mfma_f32_16x16x32_bf16 v[6:9], v[102:105], v[218:221], v[6:9]
	v_mfma_f32_16x16x32_bf16 v[58:61], v[150:153], v[190:193], v[58:61]
	v_mfma_f32_16x16x32_bf16 v[50:53], v[182:185], v[190:193], v[50:53]
	v_mfma_f32_16x16x32_bf16 v[42:45], v[150:153], v[198:201], v[42:45]
	v_mfma_f32_16x16x32_bf16 v[34:37], v[182:185], v[198:201], v[34:37]
	v_mfma_f32_16x16x32_bf16 v[26:29], v[150:153], v[206:209], v[26:29]
	v_mfma_f32_16x16x32_bf16 v[18:21], v[182:185], v[206:209], v[18:21]
	v_mfma_f32_16x16x32_bf16 v[10:13], v[150:153], v[214:217], v[10:13]
	v_mfma_f32_16x16x32_bf16 v[2:5], v[182:185], v[214:217], v[2:5]
	v_mfma_f32_16x16x32_bf16 v[58:61], v[154:157], v[194:197], v[58:61]
	v_mfma_f32_16x16x32_bf16 v[50:53], v[186:189], v[194:197], v[50:53]
	v_mfma_f32_16x16x32_bf16 v[42:45], v[154:157], v[202:205], v[42:45]
	v_mfma_f32_16x16x32_bf16 v[34:37], v[186:189], v[202:205], v[34:37]
	v_mfma_f32_16x16x32_bf16 v[26:29], v[154:157], v[210:213], v[26:29]
	v_mfma_f32_16x16x32_bf16 v[18:21], v[186:189], v[210:213], v[18:21]
	v_mfma_f32_16x16x32_bf16 v[10:13], v[154:157], v[218:221], v[10:13]
	v_mfma_f32_16x16x32_bf16 v[2:5], v[186:189], v[218:221], v[2:5]
	s_barrier
; #define PG8_STAGEX(rs, bufoff, soff, voff) do { _Pragma("unroll") for (int _i = 0; _i < 2; ++_i) \
;         __builtin_amdgcn_raw_ptr_buffer_load_lds(rs, (LAS unsigned*)(lds + (bufoff) + ldsw + _i * 8192), 16, (voff)[_i], (soff), 0, 0); } while (0)
; #define PG8_LDA(dst, b, h) do { _Pragma("unroll") for (int m = 0; m < 4; ++m) _Pragma("unroll") for (int k = 0; k < 2; ++k) dst[m][k] = *(const LAS bf16x8*)(lds + PG8_SA(b, h) + aoff + m * 2048 + k * 1024); } while (0)
; #define PG8_LDB(dst, b, h) do { _Pragma("unroll") for (int n = 0; n < 2; ++n) _Pragma("unroll") for (int k = 0; k < 2; ++k) dst[n][k] = *(const LAS bf16x8*)(lds + PG8_SB(b, h) + boff + n * 2048 + k * 1024); } while (0)
; #define PG8_WAIT_V(n) asm volatile("s_waitcnt vmcnt(" #n ")" ::: "memory")
; #define PG8_WAIT_L(n) asm volatile("s_waitcnt lgkmcnt(" #n ")" ::: "memory")
; #define PG8_BAR __builtin_amdgcn_s_barrier()
; #define PG8_SCHED __builtin_amdgcn_sched_barrier(0)
;     ...
;             PG8_WAIT_V(8); PG8_WAIT_L(0); PG8_BAR; PG8_MMA(1, 0, At, B0); PG8_MMA(1, 1, At, B1); PG8_BAR; PG8_SCHED;
;             PG8_LDB(B0, 1, 0); PG8_LDB(B1, 1, 1); PG8_SCHED; PG8_LDA(At, 1, 0); PG8_STAGEX(rsA, PG8_SA(0, 1), a2 + hstepA, voffA);
;             PG8_WAIT_V(8); PG8_WAIT_L(0); PG8_BAR; PG8_MMA(0, 0, At, B0); PG8_MMA(0, 1, At, B1); PG8_BAR; PG8_SCHED;
;             PG8_LDA(At, 1, 1); PG8_STAGEX(rsB, PG8_SB(1, 0), b3, voffB); PG8_STAGEX(rsB, PG8_SB(1, 1), b3 + hstepB, voffB); PG8_STAGEX(rsA, PG8_SA(1, 0), a3, voffA);
;             PG8_WAIT_V(8); PG8_WAIT_L(0); PG8_BAR; PG8_MMA(1, 0, At, B0); PG8_MMA(1, 1, At, B1); PG8_BAR; PG8_SCHED;
;         }
	s_setprio 0
	v_add_u32_e32 v102, 0x18000, v172
	v_add_u32_e32 v146, 0x1c000, v172
	ds_read_b128 v[82:85], v102
	ds_read_b128 v[86:89], v102 offset:1024
	ds_read_b128 v[98:101], v102 offset:2048
	ds_read_b128 v[102:105], v102 offset:3072
	ds_read_b128 v[150:153], v146
	ds_read_b128 v[154:157], v146 offset:1024
	ds_read_b128 v[182:185], v146 offset:2048
	ds_read_b128 v[186:189], v146 offset:3072
	s_add_i32 s55, s55, 0x80000
	s_mov_b32 m0, s14
	ds_read_b128 v[190:193], v173 offset:32768
	ds_read_b128 v[194:197], v173 offset:33792
	ds_read_b128 v[198:201], v173 offset:34816
	ds_read_b128 v[202:205], v173 offset:35840
	ds_read_b128 v[206:209], v173 offset:36864
	ds_read_b128 v[210:213], v173 offset:37888
	ds_read_b128 v[214:217], v173 offset:38912
	ds_read_b128 v[218:221], v173 offset:39936
	buffer_load_dwordx4 v159, s[76:79], s55 offen lds
	s_mov_b32 m0, s15
	s_nop 0
	buffer_load_dwordx4 v163, s[76:79], s55 offen lds
	s_waitcnt vmcnt(8)
	s_waitcnt lgkmcnt(0)
	s_setprio 1
	s_barrier
	v_mfma_f32_16x16x32_bf16 v[142:145], v[82:85], v[190:193], v[142:145]
	v_mfma_f32_16x16x32_bf16 v[134:137], v[98:101], v[190:193], v[134:137]
	v_mfma_f32_16x16x32_bf16 v[126:129], v[82:85], v[198:201], v[126:129]
	v_mfma_f32_16x16x32_bf16 v[118:121], v[98:101], v[198:201], v[118:121]
	v_mfma_f32_16x16x32_bf16 v[110:113], v[82:85], v[206:209], v[110:113]
	v_mfma_f32_16x16x32_bf16 v[94:97], v[98:101], v[206:209], v[94:97]
	v_mfma_f32_16x16x32_bf16 v[78:81], v[82:85], v[214:217], v[78:81]
	v_mfma_f32_16x16x32_bf16 v[70:73], v[98:101], v[214:217], v[70:73]
	v_mfma_f32_16x16x32_bf16 v[142:145], v[86:89], v[194:197], v[142:145]
	v_mfma_f32_16x16x32_bf16 v[134:137], v[102:105], v[194:197], v[134:137]
	v_mfma_f32_16x16x32_bf16 v[126:129], v[86:89], v[202:205], v[126:129]
	v_mfma_f32_16x16x32_bf16 v[118:121], v[102:105], v[202:205], v[118:121]
	v_mfma_f32_16x16x32_bf16 v[110:113], v[86:89], v[210:213], v[110:113]
	v_mfma_f32_16x16x32_bf16 v[94:97], v[102:105], v[210:213], v[94:97]
	v_mfma_f32_16x16x32_bf16 v[78:81], v[86:89], v[218:221], v[78:81]
	v_mfma_f32_16x16x32_bf16 v[70:73], v[102:105], v[218:221], v[70:73]
	v_mfma_f32_16x16x32_bf16 v[138:141], v[150:153], v[190:193], v[138:141]
	v_mfma_f32_16x16x32_bf16 v[130:133], v[182:185], v[190:193], v[130:133]
	v_mfma_f32_16x16x32_bf16 v[122:125], v[150:153], v[198:201], v[122:125]
	v_mfma_f32_16x16x32_bf16 v[114:117], v[182:185], v[198:201], v[114:117]
	v_mfma_f32_16x16x32_bf16 v[106:109], v[150:153], v[206:209], v[106:109]
	v_mfma_f32_16x16x32_bf16 v[90:93], v[182:185], v[206:209], v[90:93]
	v_mfma_f32_16x16x32_bf16 v[74:77], v[150:153], v[214:217], v[74:77]
	v_mfma_f32_16x16x32_bf16 v[66:69], v[182:185], v[214:217], v[66:69]
	v_mfma_f32_16x16x32_bf16 v[138:141], v[154:157], v[194:197], v[138:141]
	v_mfma_f32_16x16x32_bf16 v[130:133], v[186:189], v[194:197], v[130:133]
	v_mfma_f32_16x16x32_bf16 v[122:125], v[154:157], v[202:205], v[122:125]
	v_mfma_f32_16x16x32_bf16 v[114:117], v[186:189], v[202:205], v[114:117]
	v_mfma_f32_16x16x32_bf16 v[106:109], v[154:157], v[210:213], v[106:109]
	v_mfma_f32_16x16x32_bf16 v[90:93], v[186:189], v[210:213], v[90:93]
	v_mfma_f32_16x16x32_bf16 v[74:77], v[154:157], v[218:221], v[74:77]
	v_mfma_f32_16x16x32_bf16 v[66:69], v[186:189], v[218:221], v[66:69]
	s_barrier
	s_setprio 0
	s_mov_b32 m0, s16
	s_or_b32 s55, s54, 0x80
	ds_read_b128 v[190:193], v173 offset:49152
	ds_read_b128 v[194:197], v173 offset:50176
	ds_read_b128 v[198:201], v173 offset:51200
	ds_read_b128 v[202:205], v173 offset:52224
	ds_read_b128 v[206:209], v173 offset:53248
	ds_read_b128 v[210:213], v173 offset:54272
	ds_read_b128 v[214:217], v173 offset:55296
	ds_read_b128 v[218:221], v173 offset:56320
	buffer_load_dwordx4 v161, s[40:43], s55 offen lds
	s_mov_b32 m0, s17
	s_add_i32 s54, s54, 0x80080
	buffer_load_dwordx4 v165, s[40:43], s55 offen lds
	s_mov_b32 m0, s20
	s_nop 0
	buffer_load_dwordx4 v161, s[40:43], s54 offen lds
	s_mov_b32 m0, s21
	s_nop 0
	buffer_load_dwordx4 v165, s[40:43], s54 offen lds
	s_mov_b32 m0, s18
	s_nop 0
	buffer_load_dwordx4 v159, s[76:79], s53 offen lds
	s_mov_b32 m0, s19
	s_nop 0
	buffer_load_dwordx4 v163, s[76:79], s53 offen lds
	s_waitcnt vmcnt(8)
	s_waitcnt lgkmcnt(0)
	s_setprio 1
	s_barrier
	v_mfma_f32_16x16x32_bf16 v[62:65], v[82:85], v[190:193], v[62:65]
	v_mfma_f32_16x16x32_bf16 v[54:57], v[98:101], v[190:193], v[54:57]
	v_mfma_f32_16x16x32_bf16 v[46:49], v[82:85], v[198:201], v[46:49]
	v_mfma_f32_16x16x32_bf16 v[38:41], v[98:101], v[198:201], v[38:41]
	v_mfma_f32_16x16x32_bf16 v[30:33], v[82:85], v[206:209], v[30:33]
	v_mfma_f32_16x16x32_bf16 v[22:25], v[98:101], v[206:209], v[22:25]
	v_mfma_f32_16x16x32_bf16 v[14:17], v[82:85], v[214:217], v[14:17]
	v_mfma_f32_16x16x32_bf16 v[6:9], v[98:101], v[214:217], v[6:9]
	v_mfma_f32_16x16x32_bf16 v[62:65], v[86:89], v[194:197], v[62:65]
	v_mfma_f32_16x16x32_bf16 v[54:57], v[102:105], v[194:197], v[54:57]
	v_mfma_f32_16x16x32_bf16 v[46:49], v[86:89], v[202:205], v[46:49]
	v_mfma_f32_16x16x32_bf16 v[38:41], v[102:105], v[202:205], v[38:41]
	v_mfma_f32_16x16x32_bf16 v[30:33], v[86:89], v[210:213], v[30:33]
	v_mfma_f32_16x16x32_bf16 v[22:25], v[102:105], v[210:213], v[22:25]
	v_mfma_f32_16x16x32_bf16 v[14:17], v[86:89], v[218:221], v[14:17]
	v_mfma_f32_16x16x32_bf16 v[6:9], v[102:105], v[218:221], v[6:9]
	v_mfma_f32_16x16x32_bf16 v[58:61], v[150:153], v[190:193], v[58:61]
	v_mfma_f32_16x16x32_bf16 v[50:53], v[182:185], v[190:193], v[50:53]
	v_mfma_f32_16x16x32_bf16 v[42:45], v[150:153], v[198:201], v[42:45]
	v_mfma_f32_16x16x32_bf16 v[34:37], v[182:185], v[198:201], v[34:37]
	v_mfma_f32_16x16x32_bf16 v[26:29], v[150:153], v[206:209], v[26:29]
	v_mfma_f32_16x16x32_bf16 v[18:21], v[182:185], v[206:209], v[18:21]
	v_mfma_f32_16x16x32_bf16 v[10:13], v[150:153], v[214:217], v[10:13]
	v_mfma_f32_16x16x32_bf16 v[2:5], v[182:185], v[214:217], v[2:5]
	v_mfma_f32_16x16x32_bf16 v[58:61], v[154:157], v[194:197], v[58:61]
	v_mfma_f32_16x16x32_bf16 v[50:53], v[186:189], v[194:197], v[50:53]
	v_mfma_f32_16x16x32_bf16 v[42:45], v[154:157], v[202:205], v[42:45]
	v_mfma_f32_16x16x32_bf16 v[34:37], v[186:189], v[202:205], v[34:37]
	v_mfma_f32_16x16x32_bf16 v[26:29], v[154:157], v[210:213], v[26:29]
	v_mfma_f32_16x16x32_bf16 v[18:21], v[186:189], v[210:213], v[18:21]
	v_mfma_f32_16x16x32_bf16 v[10:13], v[154:157], v[218:221], v[10:13]
	v_mfma_f32_16x16x32_bf16 v[2:5], v[186:189], v[218:221], v[2:5]
	s_barrier
	s_setprio 0
	s_add_i32 s52, s52, 2
	s_addk_i32 s50, 0x100
	s_addk_i32 s51, 0x100
	s_cmp_gt_u32 s52, 29
	s_cbranch_scc0 .LBB0_223
	s_and_b64 vcc, exec, s[46:47]
	s_cbranch_vccz .LBB0_226
	s_barrier

; #define PG8_STAGEX(rs, bufoff, soff, voff) do { _Pragma("unroll") for (int _i = 0; _i < 2; ++_i) \
;         __builtin_amdgcn_raw_ptr_buffer_load_lds(rs, (LAS unsigned*)(lds + (bufoff) + ldsw + _i * 8192), 16, (voff)[_i], (soff), 0, 0); } while (0)
; #define PG8_LDA(dst, b, h) do { _Pragma("unroll") for (int m = 0; m < 4; ++m) _Pragma("unroll") for (int k = 0; k < 2; ++k) dst[m][k] = *(const LAS bf16x8*)(lds + PG8_SA(b, h) + aoff + m * 2048 + k * 1024); } while (0)
; #define PG8_LDB(dst, b, h) do { _Pragma("unroll") for (int n = 0; n < 2; ++n) _Pragma("unroll") for (int k = 0; k < 2; ++k) dst[n][k] = *(const LAS bf16x8*)(lds + PG8_SB(b, h) + boff + n * 2048 + k * 1024); } while (0)
; #define PG8_WAIT_V(n) asm volatile("s_waitcnt vmcnt(" #n ")" ::: "memory")
; #define PG8_WAIT_L(n) asm volatile("s_waitcnt lgkmcnt(" #n ")" ::: "memory")
; #define PG8_BAR __builtin_amdgcn_s_barrier()
; #define PG8_SCHED __builtin_amdgcn_sched_barrier(0)
;     ...
;                 if (w0) { PG8_LDB(B0, 0, 0); PG8_LDB(B1, 0, 1); PG8_SCHED; PG8_LDA(At, 0, 0); }
;                 PG8_WAIT_L(0); PG8_BAR; if (w0) { PG8_MMA(0, 0, At, B0); PG8_MMA(0, 1, At, B1); } PG8_BAR; PG8_SCHED;
;                 PG8_STAGEX(rsB, PG8_SB(0, 0), b2, voffB); PG8_STAGEX(rsB, PG8_SB(0, 1), b2 + hstepB, voffB); PG8_STAGEX(rsA, PG8_SA(0, 0), a2, voffA);
;                 PG8_WAIT_V(6); PG8_BAR; PG8_BAR; PG8_SCHED;
.LBB0_240:
	v_add_u32_e32 v86, 0x10000, v72
	v_add_u32_e32 v102, 0x14000, v72
	ds_read_b128 v[74:77], v86
	ds_read_b128 v[78:81], v86 offset:1024
	ds_read_b128 v[82:85], v86 offset:2048
	ds_read_b128 v[86:89], v86 offset:3072
	ds_read_b128 v[90:93], v102
	ds_read_b128 v[94:97], v102 offset:1024
	ds_read_b128 v[98:101], v102 offset:2048
	ds_read_b128 v[102:105], v102 offset:3072
	s_cmp_lg_u32 s27, 28
	s_cselect_b32 s28, s26, 0
	s_add_i32 s29, s28, s17
	s_or_b32 s30, s29, 0x80
	s_add_i32 s28, s28, s11
	ds_read_b128 v[106:109], v73
	ds_read_b128 v[110:113], v73 offset:1024
	ds_read_b128 v[114:117], v73 offset:2048
	ds_read_b128 v[118:121], v73 offset:3072
	ds_read_b128 v[122:125], v73 offset:4096
	ds_read_b128 v[126:129], v73 offset:5120
	ds_read_b128 v[130:133], v73 offset:6144
	ds_read_b128 v[134:137], v73 offset:7168
	s_waitcnt lgkmcnt(0)
	s_setprio 1
	s_barrier
	v_mfma_f32_16x16x32_bf16 v[62:65], v[74:77], v[106:109], v[62:65]
	v_mfma_f32_16x16x32_bf16 v[58:61], v[82:85], v[106:109], v[58:61]
	v_mfma_f32_16x16x32_bf16 v[54:57], v[74:77], v[114:117], v[54:57]
	v_mfma_f32_16x16x32_bf16 v[38:41], v[82:85], v[114:117], v[38:41]
	v_mfma_f32_16x16x32_bf16 v[30:33], v[74:77], v[122:125], v[30:33]
	v_mfma_f32_16x16x32_bf16 v[22:25], v[82:85], v[122:125], v[22:25]
	v_mfma_f32_16x16x32_bf16 v[14:17], v[74:77], v[130:133], v[14:17]
	v_mfma_f32_16x16x32_bf16 v[6:9], v[82:85], v[130:133], v[6:9]
	v_mfma_f32_16x16x32_bf16 v[62:65], v[78:81], v[110:113], v[62:65]
	v_mfma_f32_16x16x32_bf16 v[58:61], v[86:89], v[110:113], v[58:61]
	v_mfma_f32_16x16x32_bf16 v[54:57], v[78:81], v[118:121], v[54:57]
	v_mfma_f32_16x16x32_bf16 v[38:41], v[86:89], v[118:121], v[38:41]
	v_mfma_f32_16x16x32_bf16 v[30:33], v[78:81], v[126:129], v[30:33]
	v_mfma_f32_16x16x32_bf16 v[22:25], v[86:89], v[126:129], v[22:25]
	v_mfma_f32_16x16x32_bf16 v[14:17], v[78:81], v[134:137], v[14:17]
	v_mfma_f32_16x16x32_bf16 v[6:9], v[86:89], v[134:137], v[6:9]
	v_mfma_f32_16x16x32_bf16 v[50:53], v[90:93], v[106:109], v[50:53]
	v_mfma_f32_16x16x32_bf16 v[46:49], v[98:101], v[106:109], v[46:49]
	v_mfma_f32_16x16x32_bf16 v[42:45], v[90:93], v[114:117], v[42:45]
	v_mfma_f32_16x16x32_bf16 v[34:37], v[98:101], v[114:117], v[34:37]
	v_mfma_f32_16x16x32_bf16 v[26:29], v[90:93], v[122:125], v[26:29]
	v_mfma_f32_16x16x32_bf16 v[18:21], v[98:101], v[122:125], v[18:21]
	v_mfma_f32_16x16x32_bf16 v[10:13], v[90:93], v[130:133], v[10:13]
	v_mfma_f32_16x16x32_bf16 v[2:5], v[98:101], v[130:133], v[2:5]
	v_mfma_f32_16x16x32_bf16 v[50:53], v[94:97], v[110:113], v[50:53]
	v_mfma_f32_16x16x32_bf16 v[46:49], v[102:105], v[110:113], v[46:49]
	v_mfma_f32_16x16x32_bf16 v[42:45], v[94:97], v[118:121], v[42:45]
	v_mfma_f32_16x16x32_bf16 v[34:37], v[102:105], v[118:121], v[34:37]
	v_mfma_f32_16x16x32_bf16 v[26:29], v[94:97], v[126:129], v[26:29]
	v_mfma_f32_16x16x32_bf16 v[18:21], v[102:105], v[126:129], v[18:21]
	v_mfma_f32_16x16x32_bf16 v[10:13], v[94:97], v[134:137], v[10:13]
	v_mfma_f32_16x16x32_bf16 v[2:5], v[102:105], v[134:137], v[2:5]
	s_barrier
	s_setprio 0
	s_mov_b32 m0, s13
	s_mov_b32 s42, s78
	s_mov_b32 s43, s79
	buffer_load_dwordx4 v67, s[40:43], s28 offen lds
	s_mov_b32 m0, s14
	s_add_i32 s31, s28, 0x80000
	buffer_load_dwordx4 v69, s[40:43], s28 offen lds
	s_mov_b32 m0, s15
	s_nop 0
	buffer_load_dwordx4 v67, s[40:43], s31 offen lds
	s_mov_b32 m0, s16
	s_nop 0
	buffer_load_dwordx4 v69, s[40:43], s31 offen lds
	s_mov_b32 m0, s12
	s_nop 0
	buffer_load_dwordx4 v66, s[76:79], s29 offen lds
	s_mov_b32 m0, s18
	s_nop 0
	buffer_load_dwordx4 v68, s[76:79], s29 offen lds
	s_waitcnt vmcnt(6)
	s_barrier
	s_barrier
; #define PG8_STAGEX(rs, bufoff, soff, voff) do { _Pragma("unroll") for (int _i = 0; _i < 2; ++_i) \
;         __builtin_amdgcn_raw_ptr_buffer_load_lds(rs, (LAS unsigned*)(lds + (bufoff) + ldsw + _i * 8192), 16, (voff)[_i], (soff), 0, 0); } while (0)
; #define PG8_LDA(dst, b, h) do { _Pragma("unroll") for (int m = 0; m < 4; ++m) _Pragma("unroll") for (int k = 0; k < 2; ++k) dst[m][k] = *(const LAS bf16x8*)(lds + PG8_SA(b, h) + aoff + m * 2048 + k * 1024); } while (0)
; #define PG8_LDB(dst, b, h) do { _Pragma("unroll") for (int n = 0; n < 2; ++n) _Pragma("unroll") for (int k = 0; k < 2; ++k) dst[n][k] = *(const LAS bf16x8*)(lds + PG8_SB(b, h) + boff + n * 2048 + k * 1024); } while (0)
; #define PG8_WAIT_V(n) asm volatile("s_waitcnt vmcnt(" #n ")" ::: "memory")
; #define PG8_WAIT_L(n) asm volatile("s_waitcnt lgkmcnt(" #n ")" ::: "memory")
; #define PG8_BAR __builtin_amdgcn_s_barrier()
; #define PG8_SCHED __builtin_amdgcn_sched_barrier(0)
;     ...
;                 if (w0) { PG8_LDB(B0, 1, 0); PG8_LDB(B1, 1, 1); PG8_SCHED; PG8_LDA(At, 1, 0); }
;                 PG8_WAIT_L(0); PG8_BAR; if (w0) { PG8_MMA(0, 0, At, B0); PG8_MMA(0, 1, At, B1); } PG8_BAR; PG8_SCHED;
;                 PG8_STAGEX(rsB, PG8_SB(1, 0), b3, voffB); PG8_STAGEX(rsB, PG8_SB(1, 1), b3 + hstepB, voffB); PG8_STAGEX(rsA, PG8_SA(1, 0), a3, voffA);
;                 PG8_WAIT_V(6); PG8_BAR; PG8_BAR; PG8_SCHED;
;             }
	v_add_u32_e32 v86, 0x18000, v72
	v_add_u32_e32 v102, 0x1c000, v72
	ds_read_b128 v[74:77], v86
	ds_read_b128 v[78:81], v86 offset:1024
	ds_read_b128 v[82:85], v86 offset:2048
	ds_read_b128 v[86:89], v86 offset:3072
	ds_read_b128 v[90:93], v102
	ds_read_b128 v[94:97], v102 offset:1024
	ds_read_b128 v[98:101], v102 offset:2048
	ds_read_b128 v[102:105], v102 offset:3072
	ds_read_b128 v[106:109], v73 offset:32768
	ds_read_b128 v[110:113], v73 offset:33792
	ds_read_b128 v[114:117], v73 offset:34816
	ds_read_b128 v[118:121], v73 offset:35840
	ds_read_b128 v[122:125], v73 offset:36864
	ds_read_b128 v[126:129], v73 offset:37888
	ds_read_b128 v[130:133], v73 offset:38912
	ds_read_b128 v[134:137], v73 offset:39936
	s_waitcnt lgkmcnt(0)
	s_setprio 1
	s_barrier
	v_mfma_f32_16x16x32_bf16 v[62:65], v[74:77], v[106:109], v[62:65]
	v_mfma_f32_16x16x32_bf16 v[58:61], v[82:85], v[106:109], v[58:61]
	v_mfma_f32_16x16x32_bf16 v[54:57], v[74:77], v[114:117], v[54:57]
	v_mfma_f32_16x16x32_bf16 v[38:41], v[82:85], v[114:117], v[38:41]
	v_mfma_f32_16x16x32_bf16 v[30:33], v[74:77], v[122:125], v[30:33]
	v_mfma_f32_16x16x32_bf16 v[22:25], v[82:85], v[122:125], v[22:25]
	v_mfma_f32_16x16x32_bf16 v[14:17], v[74:77], v[130:133], v[14:17]
	v_mfma_f32_16x16x32_bf16 v[6:9], v[82:85], v[130:133], v[6:9]
	v_mfma_f32_16x16x32_bf16 v[62:65], v[78:81], v[110:113], v[62:65]
	v_mfma_f32_16x16x32_bf16 v[58:61], v[86:89], v[110:113], v[58:61]
	v_mfma_f32_16x16x32_bf16 v[54:57], v[78:81], v[118:121], v[54:57]
	v_mfma_f32_16x16x32_bf16 v[38:41], v[86:89], v[118:121], v[38:41]
	v_mfma_f32_16x16x32_bf16 v[30:33], v[78:81], v[126:129], v[30:33]
	v_mfma_f32_16x16x32_bf16 v[22:25], v[86:89], v[126:129], v[22:25]
	v_mfma_f32_16x16x32_bf16 v[14:17], v[78:81], v[134:137], v[14:17]
	v_mfma_f32_16x16x32_bf16 v[6:9], v[86:89], v[134:137], v[6:9]
	v_mfma_f32_16x16x32_bf16 v[50:53], v[90:93], v[106:109], v[50:53]
	s_or_b32 s29, s28, 0x80
	v_mfma_f32_16x16x32_bf16 v[46:49], v[98:101], v[106:109], v[46:49]
	v_mfma_f32_16x16x32_bf16 v[42:45], v[90:93], v[114:117], v[42:45]
	v_mfma_f32_16x16x32_bf16 v[34:37], v[98:101], v[114:117], v[34:37]
	v_mfma_f32_16x16x32_bf16 v[26:29], v[90:93], v[122:125], v[26:29]
	v_mfma_f32_16x16x32_bf16 v[18:21], v[98:101], v[122:125], v[18:21]
	v_mfma_f32_16x16x32_bf16 v[10:13], v[90:93], v[130:133], v[10:13]
	v_mfma_f32_16x16x32_bf16 v[2:5], v[98:101], v[130:133], v[2:5]
	v_mfma_f32_16x16x32_bf16 v[50:53], v[94:97], v[110:113], v[50:53]
	v_mfma_f32_16x16x32_bf16 v[46:49], v[102:105], v[110:113], v[46:49]
	v_mfma_f32_16x16x32_bf16 v[42:45], v[94:97], v[118:121], v[42:45]
	v_mfma_f32_16x16x32_bf16 v[34:37], v[102:105], v[118:121], v[34:37]
	v_mfma_f32_16x16x32_bf16 v[26:29], v[94:97], v[126:129], v[26:29]
	v_mfma_f32_16x16x32_bf16 v[18:21], v[102:105], v[126:129], v[18:21]
	v_mfma_f32_16x16x32_bf16 v[10:13], v[94:97], v[134:137], v[10:13]
	v_mfma_f32_16x16x32_bf16 v[2:5], v[102:105], v[134:137], v[2:5]
	s_barrier
	s_setprio 0
	s_mov_b32 m0, s20
	s_add_i32 s28, s28, 0x80080
	buffer_load_dwordx4 v67, s[40:43], s29 offen lds
	s_mov_b32 m0, s21
	s_nop 0
	buffer_load_dwordx4 v69, s[40:43], s29 offen lds
	s_mov_b32 m0, s24
	s_nop 0
	buffer_load_dwordx4 v67, s[40:43], s28 offen lds
	s_mov_b32 m0, s25
	s_nop 0
	buffer_load_dwordx4 v69, s[40:43], s28 offen lds
	s_mov_b32 m0, s22
	s_nop 0
	buffer_load_dwordx4 v66, s[76:79], s30 offen lds
	s_mov_b32 m0, s23
	s_nop 0
	buffer_load_dwordx4 v68, s[76:79], s30 offen lds
	s_waitcnt vmcnt(6)
	s_barrier
	s_barrier
	s_addk_i32 s26, 0x100
	s_add_i32 s27, s27, 2
	s_cmp_gt_u32 s27, 29
	s_cbranch_scc0 .LBB0_240
	s_cmpk_lt_u32 s8, 0x100
	s_cbranch_scc0 .LBB0_243
	s_barrier

; #define PG8_STAGEX(rs, bufoff, soff, voff) do { _Pragma("unroll") for (int _i = 0; _i < 2; ++_i) \
;         __builtin_amdgcn_raw_ptr_buffer_load_lds(rs, (LAS unsigned*)(lds + (bufoff) + ldsw + _i * 8192), 16, (voff)[_i], (soff), 0, 0); } while (0)
; #define PG8_LDA(dst, b, h) do { _Pragma("unroll") for (int m = 0; m < 4; ++m) _Pragma("unroll") for (int k = 0; k < 2; ++k) dst[m][k] = *(const LAS bf16x8*)(lds + PG8_SA(b, h) + aoff + m * 2048 + k * 1024); } while (0)
; #define PG8_LDB(dst, b, h) do { _Pragma("unroll") for (int n = 0; n < 2; ++n) _Pragma("unroll") for (int k = 0; k < 2; ++k) dst[n][k] = *(const LAS bf16x8*)(lds + PG8_SB(b, h) + boff + n * 2048 + k * 1024); } while (0)
; #define PG8_WAIT_V(n) asm volatile("s_waitcnt vmcnt(" #n ")" ::: "memory")
; #define PG8_WAIT_L(n) asm volatile("s_waitcnt lgkmcnt(" #n ")" ::: "memory")
; #define PG8_BAR __builtin_amdgcn_s_barrier()
; #define PG8_SCHED __builtin_amdgcn_sched_barrier(0)
;     ...
;             PG8_LDB(B0, 0, 0); PG8_LDB(B1, 0, 1); PG8_SCHED; PG8_LDA(At, 0, 0); PG8_STAGEX(rsA, PG8_SA(1, 1), a1 + hstepA, voffA);
;             PG8_WAIT_V(8); PG8_WAIT_L(0); PG8_BAR; PG8_MMA(0, 0, At, B0); PG8_MMA(0, 1, At, B1); PG8_BAR; PG8_SCHED;
;             PG8_LDA(At, 0, 1); PG8_STAGEX(rsB, PG8_SB(0, 0), b2, voffB); PG8_STAGEX(rsB, PG8_SB(0, 1), b2 + hstepB, voffB); PG8_STAGEX(rsA, PG8_SA(0, 0), a2, voffA);
;             PG8_WAIT_V(8); PG8_WAIT_L(0); PG8_BAR; PG8_MMA(1, 0, At, B0); PG8_MMA(1, 1, At, B1); PG8_BAR; PG8_SCHED;
.LBB0_323:
	v_add_u32_e32 v118, 0x10000, v210
	v_add_u32_e32 v160, 0x14000, v210
	ds_read_b128 v[106:109], v118
	ds_read_b128 v[110:113], v118 offset:1024
	ds_read_b128 v[114:117], v118 offset:2048
	ds_read_b128 v[118:121], v118 offset:3072
	ds_read_b128 v[122:125], v160
	ds_read_b128 v[134:137], v160 offset:1024
	ds_read_b128 v[156:159], v160 offset:2048
	ds_read_b128 v[160:163], v160 offset:3072
	s_add_i32 s42, s51, 0xffea8080
	s_cmpk_eq_i32 s58, 0x52
	s_cselect_b32 s61, s30, s42
	s_cselect_b32 s60, s31, s57
	s_or_b32 s59, s61, 0x80
	s_mov_b32 m0, s68
	ds_read_b128 v[164:167], v211
	ds_read_b128 v[168:171], v211 offset:1024
	ds_read_b128 v[182:185], v211 offset:2048
	ds_read_b128 v[186:189], v211 offset:3072
	ds_read_b128 v[190:193], v211 offset:4096
	ds_read_b128 v[194:197], v211 offset:5120
	ds_read_b128 v[198:201], v211 offset:6144
	ds_read_b128 v[202:205], v211 offset:7168
	buffer_load_dwordx4 v178, s[76:79], s51 offen lds
	s_mov_b32 m0, s69
	s_nop 0
	buffer_load_dwordx4 v206, s[76:79], s51 offen lds
	s_waitcnt vmcnt(8)
	s_waitcnt lgkmcnt(0)
	s_setprio 1
	s_barrier
	v_mfma_f32_16x16x32_bf16 v[150:153], v[106:109], v[164:167], v[150:153]
	v_mfma_f32_16x16x32_bf16 v[146:149], v[114:117], v[164:167], v[146:149]
	v_mfma_f32_16x16x32_bf16 v[142:145], v[106:109], v[182:185], v[142:145]
	v_mfma_f32_16x16x32_bf16 v[138:141], v[114:117], v[182:185], v[138:141]
	v_mfma_f32_16x16x32_bf16 v[130:133], v[106:109], v[190:193], v[130:133]
	v_mfma_f32_16x16x32_bf16 v[126:129], v[114:117], v[190:193], v[126:129]
	v_mfma_f32_16x16x32_bf16 v[102:105], v[106:109], v[198:201], v[102:105]
	v_mfma_f32_16x16x32_bf16 v[98:101], v[114:117], v[198:201], v[98:101]
	v_mfma_f32_16x16x32_bf16 v[150:153], v[110:113], v[168:171], v[150:153]
	v_mfma_f32_16x16x32_bf16 v[146:149], v[118:121], v[168:171], v[146:149]
	v_mfma_f32_16x16x32_bf16 v[142:145], v[110:113], v[186:189], v[142:145]
	v_mfma_f32_16x16x32_bf16 v[138:141], v[118:121], v[186:189], v[138:141]
	v_mfma_f32_16x16x32_bf16 v[130:133], v[110:113], v[194:197], v[130:133]
	v_mfma_f32_16x16x32_bf16 v[126:129], v[118:121], v[194:197], v[126:129]
	v_mfma_f32_16x16x32_bf16 v[102:105], v[110:113], v[202:205], v[102:105]
	v_mfma_f32_16x16x32_bf16 v[98:101], v[118:121], v[202:205], v[98:101]
	v_mfma_f32_16x16x32_bf16 v[62:65], v[122:125], v[164:167], v[62:65]
	v_mfma_f32_16x16x32_bf16 v[58:61], v[156:159], v[164:167], v[58:61]
	v_mfma_f32_16x16x32_bf16 v[54:57], v[122:125], v[182:185], v[54:57]
	v_mfma_f32_16x16x32_bf16 v[50:53], v[156:159], v[182:185], v[50:53]
	v_mfma_f32_16x16x32_bf16 v[46:49], v[122:125], v[190:193], v[46:49]
	v_mfma_f32_16x16x32_bf16 v[42:45], v[156:159], v[190:193], v[42:45]
	v_mfma_f32_16x16x32_bf16 v[38:41], v[122:125], v[198:201], v[38:41]
	v_mfma_f32_16x16x32_bf16 v[34:37], v[156:159], v[198:201], v[34:37]
	v_mfma_f32_16x16x32_bf16 v[62:65], v[134:137], v[168:171], v[62:65]
	v_mfma_f32_16x16x32_bf16 v[58:61], v[160:163], v[168:171], v[58:61]
	v_mfma_f32_16x16x32_bf16 v[54:57], v[134:137], v[186:189], v[54:57]
	v_mfma_f32_16x16x32_bf16 v[50:53], v[160:163], v[186:189], v[50:53]
	v_mfma_f32_16x16x32_bf16 v[46:49], v[134:137], v[194:197], v[46:49]
	v_mfma_f32_16x16x32_bf16 v[42:45], v[160:163], v[194:197], v[42:45]
	v_mfma_f32_16x16x32_bf16 v[38:41], v[134:137], v[202:205], v[38:41]
	v_mfma_f32_16x16x32_bf16 v[34:37], v[160:163], v[202:205], v[34:37]
	s_barrier
	s_setprio 0
	s_mov_b32 m0, s15
	s_mov_b32 s42, s78
	s_mov_b32 s43, s79
	ds_read_b128 v[164:167], v211 offset:16384
	ds_read_b128 v[168:171], v211 offset:17408
	ds_read_b128 v[182:185], v211 offset:18432
	ds_read_b128 v[186:189], v211 offset:19456
	ds_read_b128 v[190:193], v211 offset:20480
	ds_read_b128 v[194:197], v211 offset:21504
	ds_read_b128 v[198:201], v211 offset:22528
	ds_read_b128 v[202:205], v211 offset:23552
	buffer_load_dwordx4 v179, s[40:43], s60 offen lds
	s_mov_b32 m0, s16
	s_add_i32 s62, s60, 0x158000
	buffer_load_dwordx4 v207, s[40:43], s60 offen lds
	s_mov_b32 m0, s17
	s_nop 0
	buffer_load_dwordx4 v179, s[40:43], s62 offen lds
	s_mov_b32 m0, s18
	s_nop 0
	buffer_load_dwordx4 v207, s[40:43], s62 offen lds
	s_mov_b32 m0, s14
	s_nop 0
	buffer_load_dwordx4 v178, s[76:79], s61 offen lds
	s_mov_b32 m0, s19
	s_nop 0
	buffer_load_dwordx4 v206, s[76:79], s61 offen lds
	s_waitcnt vmcnt(8)
	s_waitcnt lgkmcnt(0)
	s_setprio 1
	s_barrier
	v_mfma_f32_16x16x32_bf16 v[94:97], v[106:109], v[164:167], v[94:97]
	v_mfma_f32_16x16x32_bf16 v[90:93], v[114:117], v[164:167], v[90:93]
	v_mfma_f32_16x16x32_bf16 v[86:89], v[106:109], v[182:185], v[86:89]
	v_mfma_f32_16x16x32_bf16 v[82:85], v[114:117], v[182:185], v[82:85]
	v_mfma_f32_16x16x32_bf16 v[78:81], v[106:109], v[190:193], v[78:81]
	v_mfma_f32_16x16x32_bf16 v[74:77], v[114:117], v[190:193], v[74:77]
	v_mfma_f32_16x16x32_bf16 v[70:73], v[106:109], v[198:201], v[70:73]
	v_mfma_f32_16x16x32_bf16 v[66:69], v[114:117], v[198:201], v[66:69]
	v_mfma_f32_16x16x32_bf16 v[94:97], v[110:113], v[168:171], v[94:97]
	v_mfma_f32_16x16x32_bf16 v[90:93], v[118:121], v[168:171], v[90:93]
	v_mfma_f32_16x16x32_bf16 v[86:89], v[110:113], v[186:189], v[86:89]
	v_mfma_f32_16x16x32_bf16 v[82:85], v[118:121], v[186:189], v[82:85]
	v_mfma_f32_16x16x32_bf16 v[78:81], v[110:113], v[194:197], v[78:81]
	v_mfma_f32_16x16x32_bf16 v[74:77], v[118:121], v[194:197], v[74:77]
	v_mfma_f32_16x16x32_bf16 v[70:73], v[110:113], v[202:205], v[70:73]
	v_mfma_f32_16x16x32_bf16 v[66:69], v[118:121], v[202:205], v[66:69]
	v_mfma_f32_16x16x32_bf16 v[30:33], v[122:125], v[164:167], v[30:33]
	v_mfma_f32_16x16x32_bf16 v[26:29], v[156:159], v[164:167], v[26:29]
	v_mfma_f32_16x16x32_bf16 v[22:25], v[122:125], v[182:185], v[22:25]
	v_mfma_f32_16x16x32_bf16 v[18:21], v[156:159], v[182:185], v[18:21]
	v_mfma_f32_16x16x32_bf16 v[14:17], v[122:125], v[190:193], v[14:17]
	v_mfma_f32_16x16x32_bf16 v[10:13], v[156:159], v[190:193], v[10:13]
	v_mfma_f32_16x16x32_bf16 v[6:9], v[122:125], v[198:201], v[6:9]
	v_mfma_f32_16x16x32_bf16 v[2:5], v[156:159], v[198:201], v[2:5]
	v_mfma_f32_16x16x32_bf16 v[30:33], v[134:137], v[168:171], v[30:33]
	v_mfma_f32_16x16x32_bf16 v[26:29], v[160:163], v[168:171], v[26:29]
	v_mfma_f32_16x16x32_bf16 v[22:25], v[134:137], v[186:189], v[22:25]
	v_mfma_f32_16x16x32_bf16 v[18:21], v[160:163], v[186:189], v[18:21]
	v_mfma_f32_16x16x32_bf16 v[14:17], v[134:137], v[194:197], v[14:17]
	v_mfma_f32_16x16x32_bf16 v[10:13], v[160:163], v[194:197], v[10:13]
	v_mfma_f32_16x16x32_bf16 v[6:9], v[134:137], v[202:205], v[6:9]
	v_mfma_f32_16x16x32_bf16 v[2:5], v[160:163], v[202:205], v[2:5]
	s_barrier
; #define PG8_STAGEX(rs, bufoff, soff, voff) do { _Pragma("unroll") for (int _i = 0; _i < 2; ++_i) \
;         __builtin_amdgcn_raw_ptr_buffer_load_lds(rs, (LAS unsigned*)(lds + (bufoff) + ldsw + _i * 8192), 16, (voff)[_i], (soff), 0, 0); } while (0)
; #define PG8_LDA(dst, b, h) do { _Pragma("unroll") for (int m = 0; m < 4; ++m) _Pragma("unroll") for (int k = 0; k < 2; ++k) dst[m][k] = *(const LAS bf16x8*)(lds + PG8_SA(b, h) + aoff + m * 2048 + k * 1024); } while (0)
; #define PG8_LDB(dst, b, h) do { _Pragma("unroll") for (int n = 0; n < 2; ++n) _Pragma("unroll") for (int k = 0; k < 2; ++k) dst[n][k] = *(const LAS bf16x8*)(lds + PG8_SB(b, h) + boff + n * 2048 + k * 1024); } while (0)
; #define PG8_WAIT_V(n) asm volatile("s_waitcnt vmcnt(" #n ")" ::: "memory")
; #define PG8_WAIT_L(n) asm volatile("s_waitcnt lgkmcnt(" #n ")" ::: "memory")
; #define PG8_BAR __builtin_amdgcn_s_barrier()
; #define PG8_SCHED __builtin_amdgcn_sched_barrier(0)
;     ...
;             PG8_WAIT_V(8); PG8_WAIT_L(0); PG8_BAR; PG8_MMA(1, 0, At, B0); PG8_MMA(1, 1, At, B1); PG8_BAR; PG8_SCHED;
;             PG8_LDB(B0, 1, 0); PG8_LDB(B1, 1, 1); PG8_SCHED; PG8_LDA(At, 1, 0); PG8_STAGEX(rsA, PG8_SA(0, 1), a2 + hstepA, voffA);
;             PG8_WAIT_V(8); PG8_WAIT_L(0); PG8_BAR; PG8_MMA(0, 0, At, B0); PG8_MMA(0, 1, At, B1); PG8_BAR; PG8_SCHED;
;             PG8_LDA(At, 1, 1); PG8_STAGEX(rsB, PG8_SB(1, 0), b3, voffB); PG8_STAGEX(rsB, PG8_SB(1, 1), b3 + hstepB, voffB); PG8_STAGEX(rsA, PG8_SA(1, 0), a3, voffA);
;             PG8_WAIT_V(8); PG8_WAIT_L(0); PG8_BAR; PG8_MMA(1, 0, At, B0); PG8_MMA(1, 1, At, B1); PG8_BAR; PG8_SCHED;
;         }
	s_setprio 0
	v_add_u32_e32 v118, 0x18000, v210
	v_add_u32_e32 v160, 0x1c000, v210
	ds_read_b128 v[106:109], v118
	ds_read_b128 v[110:113], v118 offset:1024
	ds_read_b128 v[114:117], v118 offset:2048
	ds_read_b128 v[118:121], v118 offset:3072
	ds_read_b128 v[122:125], v160
	ds_read_b128 v[134:137], v160 offset:1024
	ds_read_b128 v[156:159], v160 offset:2048
	ds_read_b128 v[160:163], v160 offset:3072
	s_add_i32 s61, s61, 0x158000
	s_mov_b32 m0, s20
	ds_read_b128 v[164:167], v211 offset:32768
	ds_read_b128 v[168:171], v211 offset:33792
	ds_read_b128 v[182:185], v211 offset:34816
	ds_read_b128 v[186:189], v211 offset:35840
	ds_read_b128 v[190:193], v211 offset:36864
	ds_read_b128 v[194:197], v211 offset:37888
	ds_read_b128 v[198:201], v211 offset:38912
	ds_read_b128 v[202:205], v211 offset:39936
	buffer_load_dwordx4 v178, s[76:79], s61 offen lds
	s_mov_b32 m0, s21
	s_nop 0
	buffer_load_dwordx4 v206, s[76:79], s61 offen lds
	s_waitcnt vmcnt(8)
	s_waitcnt lgkmcnt(0)
	s_setprio 1
	s_barrier
	v_mfma_f32_16x16x32_bf16 v[150:153], v[106:109], v[164:167], v[150:153]
	v_mfma_f32_16x16x32_bf16 v[146:149], v[114:117], v[164:167], v[146:149]
	v_mfma_f32_16x16x32_bf16 v[142:145], v[106:109], v[182:185], v[142:145]
	v_mfma_f32_16x16x32_bf16 v[138:141], v[114:117], v[182:185], v[138:141]
	v_mfma_f32_16x16x32_bf16 v[130:133], v[106:109], v[190:193], v[130:133]
	v_mfma_f32_16x16x32_bf16 v[126:129], v[114:117], v[190:193], v[126:129]
	v_mfma_f32_16x16x32_bf16 v[102:105], v[106:109], v[198:201], v[102:105]
	v_mfma_f32_16x16x32_bf16 v[98:101], v[114:117], v[198:201], v[98:101]
	v_mfma_f32_16x16x32_bf16 v[150:153], v[110:113], v[168:171], v[150:153]
	v_mfma_f32_16x16x32_bf16 v[146:149], v[118:121], v[168:171], v[146:149]
	v_mfma_f32_16x16x32_bf16 v[142:145], v[110:113], v[186:189], v[142:145]
	v_mfma_f32_16x16x32_bf16 v[138:141], v[118:121], v[186:189], v[138:141]
	v_mfma_f32_16x16x32_bf16 v[130:133], v[110:113], v[194:197], v[130:133]
	v_mfma_f32_16x16x32_bf16 v[126:129], v[118:121], v[194:197], v[126:129]
	v_mfma_f32_16x16x32_bf16 v[102:105], v[110:113], v[202:205], v[102:105]
	v_mfma_f32_16x16x32_bf16 v[98:101], v[118:121], v[202:205], v[98:101]
	v_mfma_f32_16x16x32_bf16 v[62:65], v[122:125], v[164:167], v[62:65]
	v_mfma_f32_16x16x32_bf16 v[58:61], v[156:159], v[164:167], v[58:61]
	v_mfma_f32_16x16x32_bf16 v[54:57], v[122:125], v[182:185], v[54:57]
	v_mfma_f32_16x16x32_bf16 v[50:53], v[156:159], v[182:185], v[50:53]
	v_mfma_f32_16x16x32_bf16 v[46:49], v[122:125], v[190:193], v[46:49]
	v_mfma_f32_16x16x32_bf16 v[42:45], v[156:159], v[190:193], v[42:45]
	v_mfma_f32_16x16x32_bf16 v[38:41], v[122:125], v[198:201], v[38:41]
	v_mfma_f32_16x16x32_bf16 v[34:37], v[156:159], v[198:201], v[34:37]
	v_mfma_f32_16x16x32_bf16 v[62:65], v[134:137], v[168:171], v[62:65]
	v_mfma_f32_16x16x32_bf16 v[58:61], v[160:163], v[168:171], v[58:61]
	v_mfma_f32_16x16x32_bf16 v[54:57], v[134:137], v[186:189], v[54:57]
	v_mfma_f32_16x16x32_bf16 v[50:53], v[160:163], v[186:189], v[50:53]
	v_mfma_f32_16x16x32_bf16 v[46:49], v[134:137], v[194:197], v[46:49]
	v_mfma_f32_16x16x32_bf16 v[42:45], v[160:163], v[194:197], v[42:45]
	v_mfma_f32_16x16x32_bf16 v[38:41], v[134:137], v[202:205], v[38:41]
	v_mfma_f32_16x16x32_bf16 v[34:37], v[160:163], v[202:205], v[34:37]
	s_barrier
	s_setprio 0
	s_mov_b32 m0, s28
	s_or_b32 s61, s60, 0x80
	ds_read_b128 v[164:167], v211 offset:49152
	ds_read_b128 v[168:171], v211 offset:50176
	ds_read_b128 v[182:185], v211 offset:51200
	ds_read_b128 v[186:189], v211 offset:52224
	ds_read_b128 v[190:193], v211 offset:53248
	ds_read_b128 v[194:197], v211 offset:54272
	ds_read_b128 v[198:201], v211 offset:55296
	ds_read_b128 v[202:205], v211 offset:56320
	buffer_load_dwordx4 v179, s[40:43], s61 offen lds
	s_mov_b32 m0, s29
	s_add_i32 s60, s60, 0x158080
	buffer_load_dwordx4 v207, s[40:43], s61 offen lds
	s_mov_b32 m0, s66
	s_nop 0
	buffer_load_dwordx4 v179, s[40:43], s60 offen lds
	s_mov_b32 m0, s67
	s_nop 0
	buffer_load_dwordx4 v207, s[40:43], s60 offen lds
	s_mov_b32 m0, s54
	s_nop 0
	buffer_load_dwordx4 v178, s[76:79], s59 offen lds
	s_mov_b32 m0, s55
	s_nop 0
	buffer_load_dwordx4 v206, s[76:79], s59 offen lds
	s_waitcnt vmcnt(8)
	s_waitcnt lgkmcnt(0)
	s_setprio 1
	s_barrier
	v_mfma_f32_16x16x32_bf16 v[94:97], v[106:109], v[164:167], v[94:97]
	v_mfma_f32_16x16x32_bf16 v[90:93], v[114:117], v[164:167], v[90:93]
	v_mfma_f32_16x16x32_bf16 v[86:89], v[106:109], v[182:185], v[86:89]
	v_mfma_f32_16x16x32_bf16 v[82:85], v[114:117], v[182:185], v[82:85]
	v_mfma_f32_16x16x32_bf16 v[78:81], v[106:109], v[190:193], v[78:81]
	v_mfma_f32_16x16x32_bf16 v[74:77], v[114:117], v[190:193], v[74:77]
	v_mfma_f32_16x16x32_bf16 v[70:73], v[106:109], v[198:201], v[70:73]
	v_mfma_f32_16x16x32_bf16 v[66:69], v[114:117], v[198:201], v[66:69]
	v_mfma_f32_16x16x32_bf16 v[94:97], v[110:113], v[168:171], v[94:97]
	v_mfma_f32_16x16x32_bf16 v[90:93], v[118:121], v[168:171], v[90:93]
	v_mfma_f32_16x16x32_bf16 v[86:89], v[110:113], v[186:189], v[86:89]
	v_mfma_f32_16x16x32_bf16 v[82:85], v[118:121], v[186:189], v[82:85]
	v_mfma_f32_16x16x32_bf16 v[78:81], v[110:113], v[194:197], v[78:81]
	v_mfma_f32_16x16x32_bf16 v[74:77], v[118:121], v[194:197], v[74:77]
	v_mfma_f32_16x16x32_bf16 v[70:73], v[110:113], v[202:205], v[70:73]
	v_mfma_f32_16x16x32_bf16 v[66:69], v[118:121], v[202:205], v[66:69]
	v_mfma_f32_16x16x32_bf16 v[30:33], v[122:125], v[164:167], v[30:33]
	v_mfma_f32_16x16x32_bf16 v[26:29], v[156:159], v[164:167], v[26:29]
	v_mfma_f32_16x16x32_bf16 v[22:25], v[122:125], v[182:185], v[22:25]
	v_mfma_f32_16x16x32_bf16 v[18:21], v[156:159], v[182:185], v[18:21]
	v_mfma_f32_16x16x32_bf16 v[14:17], v[122:125], v[190:193], v[14:17]
	v_mfma_f32_16x16x32_bf16 v[10:13], v[156:159], v[190:193], v[10:13]
	v_mfma_f32_16x16x32_bf16 v[6:9], v[122:125], v[198:201], v[6:9]
	v_mfma_f32_16x16x32_bf16 v[2:5], v[156:159], v[198:201], v[2:5]
	v_mfma_f32_16x16x32_bf16 v[30:33], v[134:137], v[168:171], v[30:33]
	v_mfma_f32_16x16x32_bf16 v[26:29], v[160:163], v[168:171], v[26:29]
	v_mfma_f32_16x16x32_bf16 v[22:25], v[134:137], v[186:189], v[22:25]
	v_mfma_f32_16x16x32_bf16 v[18:21], v[160:163], v[186:189], v[18:21]
	v_mfma_f32_16x16x32_bf16 v[14:17], v[134:137], v[194:197], v[14:17]
	v_mfma_f32_16x16x32_bf16 v[10:13], v[160:163], v[194:197], v[10:13]
	v_mfma_f32_16x16x32_bf16 v[6:9], v[134:137], v[202:205], v[6:9]
	v_mfma_f32_16x16x32_bf16 v[2:5], v[160:163], v[202:205], v[2:5]
	s_barrier
	s_setprio 0
	s_add_i32 s58, s58, 2
	s_addk_i32 s51, 0x100
	s_addk_i32 s57, 0x100
	s_cmpk_gt_u32 s58, 0x53
	s_cbranch_scc0 .LBB0_323
	s_and_b64 vcc, exec, s[48:49]
	s_cbranch_vccz .LBB0_326
	s_barrier

; #define PG8_STAGEX(rs, bufoff, soff, voff) do { _Pragma("unroll") for (int _i = 0; _i < 2; ++_i) \
;         __builtin_amdgcn_raw_ptr_buffer_load_lds(rs, (LAS unsigned*)(lds + (bufoff) + ldsw + _i * 8192), 16, (voff)[_i], (soff), 0, 0); } while (0)
; #define PG8_LDA(dst, b, h) do { _Pragma("unroll") for (int m = 0; m < 4; ++m) _Pragma("unroll") for (int k = 0; k < 2; ++k) dst[m][k] = *(const LAS bf16x8*)(lds + PG8_SA(b, h) + aoff + m * 2048 + k * 1024); } while (0)
; #define PG8_LDB(dst, b, h) do { _Pragma("unroll") for (int n = 0; n < 2; ++n) _Pragma("unroll") for (int k = 0; k < 2; ++k) dst[n][k] = *(const LAS bf16x8*)(lds + PG8_SB(b, h) + boff + n * 2048 + k * 1024); } while (0)
; #define PG8_WAIT_V(n) asm volatile("s_waitcnt vmcnt(" #n ")" ::: "memory")
; #define PG8_WAIT_L(n) asm volatile("s_waitcnt lgkmcnt(" #n ")" ::: "memory")
; #define PG8_BAR __builtin_amdgcn_s_barrier()
; #define PG8_SCHED __builtin_amdgcn_sched_barrier(0)
;     ...
;             PG8_LDB(B0, 0, 0); PG8_LDB(B1, 0, 1); PG8_SCHED; PG8_LDA(At, 0, 0); PG8_STAGEX(rsA, PG8_SA(1, 1), a1 + hstepA, voffA);
;             PG8_WAIT_V(8); PG8_WAIT_L(0); PG8_BAR; PG8_MMA(0, 0, At, B0); PG8_MMA(0, 1, At, B1); PG8_BAR; PG8_SCHED;
;             PG8_LDA(At, 0, 1); PG8_STAGEX(rsB, PG8_SB(0, 0), b2, voffB); PG8_STAGEX(rsB, PG8_SB(0, 1), b2 + hstepB, voffB); PG8_STAGEX(rsA, PG8_SA(0, 0), a2, voffA);
;             PG8_WAIT_V(8); PG8_WAIT_L(0); PG8_BAR; PG8_MMA(1, 0, At, B0); PG8_MMA(1, 1, At, B1); PG8_BAR; PG8_SCHED;
.LBB0_437:
	v_add_u32_e32 v142, 0x10000, v220
	v_add_u32_e32 v158, 0x14000, v220
	ds_read_b128 v[130:133], v142
	ds_read_b128 v[134:137], v142 offset:1024
	ds_read_b128 v[138:141], v142 offset:2048
	ds_read_b128 v[142:145], v142 offset:3072
	ds_read_b128 v[146:149], v158
	ds_read_b128 v[150:153], v158 offset:1024
	ds_read_b128 v[154:157], v158 offset:2048
	ds_read_b128 v[158:161], v158 offset:3072
	s_add_i32 s30, s7, 0xfff80080
	s_cmp_eq_u32 s29, 28
	s_cselect_b32 s50, s2, s30
	s_cselect_b32 s31, s5, s28
	s_or_b32 s30, s50, 0x80
	s_mov_b32 m0, s20
	ds_read_b128 v[162:165], v221
	ds_read_b128 v[170:173], v221 offset:1024
	ds_read_b128 v[182:185], v221 offset:2048
	ds_read_b128 v[186:189], v221 offset:3072
	ds_read_b128 v[190:193], v221 offset:4096
	ds_read_b128 v[194:197], v221 offset:5120
	ds_read_b128 v[198:201], v221 offset:6144
	ds_read_b128 v[202:205], v221 offset:7168
	buffer_load_dwordx4 v178, s[76:79], s7 offen lds
	s_mov_b32 m0, s22
	s_nop 0
	buffer_load_dwordx4 v210, s[76:79], s7 offen lds
	s_waitcnt vmcnt(8)
	s_waitcnt lgkmcnt(0)
	s_setprio 1
	s_barrier
	v_mfma_f32_16x16x32_bf16 v[126:129], v[130:133], v[162:165], v[126:129]
	v_mfma_f32_16x16x32_bf16 v[110:113], v[138:141], v[162:165], v[110:113]
	v_mfma_f32_16x16x32_bf16 v[118:121], v[130:133], v[182:185], v[118:121]
	v_mfma_f32_16x16x32_bf16 v[102:105], v[138:141], v[182:185], v[102:105]
	v_mfma_f32_16x16x32_bf16 v[114:117], v[130:133], v[190:193], v[114:117]
	v_mfma_f32_16x16x32_bf16 v[98:101], v[138:141], v[190:193], v[98:101]
	v_mfma_f32_16x16x32_bf16 v[122:125], v[130:133], v[198:201], v[122:125]
	v_mfma_f32_16x16x32_bf16 v[106:109], v[138:141], v[198:201], v[106:109]
	v_mfma_f32_16x16x32_bf16 v[126:129], v[134:137], v[170:173], v[126:129]
	v_mfma_f32_16x16x32_bf16 v[110:113], v[142:145], v[170:173], v[110:113]
	v_mfma_f32_16x16x32_bf16 v[118:121], v[134:137], v[186:189], v[118:121]
	v_mfma_f32_16x16x32_bf16 v[102:105], v[142:145], v[186:189], v[102:105]
	v_mfma_f32_16x16x32_bf16 v[114:117], v[134:137], v[194:197], v[114:117]
	v_mfma_f32_16x16x32_bf16 v[98:101], v[142:145], v[194:197], v[98:101]
	v_mfma_f32_16x16x32_bf16 v[122:125], v[134:137], v[202:205], v[122:125]
	v_mfma_f32_16x16x32_bf16 v[106:109], v[142:145], v[202:205], v[106:109]
	v_mfma_f32_16x16x32_bf16 v[62:65], v[146:149], v[162:165], v[62:65]
	v_mfma_f32_16x16x32_bf16 v[46:49], v[154:157], v[162:165], v[46:49]
	v_mfma_f32_16x16x32_bf16 v[54:57], v[146:149], v[182:185], v[54:57]
	v_mfma_f32_16x16x32_bf16 v[38:41], v[154:157], v[182:185], v[38:41]
	v_mfma_f32_16x16x32_bf16 v[50:53], v[146:149], v[190:193], v[50:53]
	v_mfma_f32_16x16x32_bf16 v[34:37], v[154:157], v[190:193], v[34:37]
	v_mfma_f32_16x16x32_bf16 v[58:61], v[146:149], v[198:201], v[58:61]
	v_mfma_f32_16x16x32_bf16 v[42:45], v[154:157], v[198:201], v[42:45]
	v_mfma_f32_16x16x32_bf16 v[62:65], v[150:153], v[170:173], v[62:65]
	v_mfma_f32_16x16x32_bf16 v[46:49], v[158:161], v[170:173], v[46:49]
	v_mfma_f32_16x16x32_bf16 v[54:57], v[150:153], v[186:189], v[54:57]
	v_mfma_f32_16x16x32_bf16 v[38:41], v[158:161], v[186:189], v[38:41]
	v_mfma_f32_16x16x32_bf16 v[50:53], v[150:153], v[194:197], v[50:53]
	v_mfma_f32_16x16x32_bf16 v[34:37], v[158:161], v[194:197], v[34:37]
	v_mfma_f32_16x16x32_bf16 v[58:61], v[150:153], v[202:205], v[58:61]
	v_mfma_f32_16x16x32_bf16 v[42:45], v[158:161], v[202:205], v[42:45]
	s_barrier
	s_setprio 0
	s_mov_b32 m0, s90
	s_mov_b32 s58, s78
	s_mov_b32 s59, s79
	ds_read_b128 v[162:165], v221 offset:16384
	ds_read_b128 v[170:173], v221 offset:17408
	ds_read_b128 v[182:185], v221 offset:18432
	ds_read_b128 v[186:189], v221 offset:19456
	ds_read_b128 v[190:193], v221 offset:20480
	ds_read_b128 v[194:197], v221 offset:21504
	ds_read_b128 v[198:201], v221 offset:22528
	ds_read_b128 v[202:205], v221 offset:23552
	buffer_load_dwordx4 v179, s[56:59], s31 offen lds
	s_mov_b32 m0, s91
	s_add_i32 s51, s31, 0x80000
	buffer_load_dwordx4 v211, s[56:59], s31 offen lds
	s_mov_b32 m0, s9
	s_nop 0
	buffer_load_dwordx4 v179, s[56:59], s51 offen lds
	s_mov_b32 m0, s10
	s_nop 0
	buffer_load_dwordx4 v211, s[56:59], s51 offen lds
	s_mov_b32 m0, s89
	s_nop 0
	buffer_load_dwordx4 v178, s[76:79], s50 offen lds
	s_mov_b32 m0, s11
	s_nop 0
	buffer_load_dwordx4 v210, s[76:79], s50 offen lds
	s_waitcnt vmcnt(8)
	s_waitcnt lgkmcnt(0)
	s_setprio 1
	s_barrier
	v_mfma_f32_16x16x32_bf16 v[94:97], v[130:133], v[162:165], v[94:97]
	v_mfma_f32_16x16x32_bf16 v[78:81], v[138:141], v[162:165], v[78:81]
	v_mfma_f32_16x16x32_bf16 v[86:89], v[130:133], v[182:185], v[86:89]
	v_mfma_f32_16x16x32_bf16 v[70:73], v[138:141], v[182:185], v[70:73]
	v_mfma_f32_16x16x32_bf16 v[82:85], v[130:133], v[190:193], v[82:85]
	v_mfma_f32_16x16x32_bf16 v[66:69], v[138:141], v[190:193], v[66:69]
	v_mfma_f32_16x16x32_bf16 v[90:93], v[130:133], v[198:201], v[90:93]
	v_mfma_f32_16x16x32_bf16 v[74:77], v[138:141], v[198:201], v[74:77]
	v_mfma_f32_16x16x32_bf16 v[94:97], v[134:137], v[170:173], v[94:97]
	v_mfma_f32_16x16x32_bf16 v[78:81], v[142:145], v[170:173], v[78:81]
	v_mfma_f32_16x16x32_bf16 v[86:89], v[134:137], v[186:189], v[86:89]
	v_mfma_f32_16x16x32_bf16 v[70:73], v[142:145], v[186:189], v[70:73]
	v_mfma_f32_16x16x32_bf16 v[82:85], v[134:137], v[194:197], v[82:85]
	v_mfma_f32_16x16x32_bf16 v[66:69], v[142:145], v[194:197], v[66:69]
	v_mfma_f32_16x16x32_bf16 v[90:93], v[134:137], v[202:205], v[90:93]
	v_mfma_f32_16x16x32_bf16 v[74:77], v[142:145], v[202:205], v[74:77]
	v_mfma_f32_16x16x32_bf16 v[30:33], v[146:149], v[162:165], v[30:33]
	v_mfma_f32_16x16x32_bf16 v[14:17], v[154:157], v[162:165], v[14:17]
	v_mfma_f32_16x16x32_bf16 v[22:25], v[146:149], v[182:185], v[22:25]
	v_mfma_f32_16x16x32_bf16 v[10:13], v[154:157], v[182:185], v[10:13]
	v_mfma_f32_16x16x32_bf16 v[18:21], v[146:149], v[190:193], v[18:21]
	v_mfma_f32_16x16x32_bf16 v[2:5], v[154:157], v[190:193], v[2:5]
	v_mfma_f32_16x16x32_bf16 v[26:29], v[146:149], v[198:201], v[26:29]
	v_mfma_f32_16x16x32_bf16 v[6:9], v[154:157], v[198:201], v[6:9]
	v_mfma_f32_16x16x32_bf16 v[30:33], v[150:153], v[170:173], v[30:33]
	v_mfma_f32_16x16x32_bf16 v[14:17], v[158:161], v[170:173], v[14:17]
	v_mfma_f32_16x16x32_bf16 v[22:25], v[150:153], v[186:189], v[22:25]
	v_mfma_f32_16x16x32_bf16 v[10:13], v[158:161], v[186:189], v[10:13]
	v_mfma_f32_16x16x32_bf16 v[18:21], v[150:153], v[194:197], v[18:21]
	v_mfma_f32_16x16x32_bf16 v[2:5], v[158:161], v[194:197], v[2:5]
	v_mfma_f32_16x16x32_bf16 v[26:29], v[150:153], v[202:205], v[26:29]
	v_mfma_f32_16x16x32_bf16 v[6:9], v[158:161], v[202:205], v[6:9]
	s_barrier
; #define PG8_STAGEX(rs, bufoff, soff, voff) do { _Pragma("unroll") for (int _i = 0; _i < 2; ++_i) \
;         __builtin_amdgcn_raw_ptr_buffer_load_lds(rs, (LAS unsigned*)(lds + (bufoff) + ldsw + _i * 8192), 16, (voff)[_i], (soff), 0, 0); } while (0)
; #define PG8_LDA(dst, b, h) do { _Pragma("unroll") for (int m = 0; m < 4; ++m) _Pragma("unroll") for (int k = 0; k < 2; ++k) dst[m][k] = *(const LAS bf16x8*)(lds + PG8_SA(b, h) + aoff + m * 2048 + k * 1024); } while (0)
; #define PG8_LDB(dst, b, h) do { _Pragma("unroll") for (int n = 0; n < 2; ++n) _Pragma("unroll") for (int k = 0; k < 2; ++k) dst[n][k] = *(const LAS bf16x8*)(lds + PG8_SB(b, h) + boff + n * 2048 + k * 1024); } while (0)
; #define PG8_WAIT_V(n) asm volatile("s_waitcnt vmcnt(" #n ")" ::: "memory")
; #define PG8_WAIT_L(n) asm volatile("s_waitcnt lgkmcnt(" #n ")" ::: "memory")
; #define PG8_BAR __builtin_amdgcn_s_barrier()
; #define PG8_SCHED __builtin_amdgcn_sched_barrier(0)
;     ...
;             PG8_WAIT_V(8); PG8_WAIT_L(0); PG8_BAR; PG8_MMA(1, 0, At, B0); PG8_MMA(1, 1, At, B1); PG8_BAR; PG8_SCHED;
;             PG8_LDB(B0, 1, 0); PG8_LDB(B1, 1, 1); PG8_SCHED; PG8_LDA(At, 1, 0); PG8_STAGEX(rsA, PG8_SA(0, 1), a2 + hstepA, voffA);
;             PG8_WAIT_V(8); PG8_WAIT_L(0); PG8_BAR; PG8_MMA(0, 0, At, B0); PG8_MMA(0, 1, At, B1); PG8_BAR; PG8_SCHED;
;             PG8_LDA(At, 1, 1); PG8_STAGEX(rsB, PG8_SB(1, 0), b3, voffB); PG8_STAGEX(rsB, PG8_SB(1, 1), b3 + hstepB, voffB); PG8_STAGEX(rsA, PG8_SA(1, 0), a3, voffA);
;             PG8_WAIT_V(8); PG8_WAIT_L(0); PG8_BAR; PG8_MMA(1, 0, At, B0); PG8_MMA(1, 1, At, B1); PG8_BAR; PG8_SCHED;
;         }
;     ...
;         if (wr == 0) PG8_BAR;
	s_setprio 0
	v_add_u32_e32 v142, 0x18000, v220
	v_add_u32_e32 v158, 0x1c000, v220
	ds_read_b128 v[130:133], v142
	ds_read_b128 v[134:137], v142 offset:1024
	ds_read_b128 v[138:141], v142 offset:2048
	ds_read_b128 v[142:145], v142 offset:3072
	ds_read_b128 v[146:149], v158
	ds_read_b128 v[150:153], v158 offset:1024
	ds_read_b128 v[154:157], v158 offset:2048
	ds_read_b128 v[158:161], v158 offset:3072
	s_add_i32 s50, s50, 0x80000
	s_mov_b32 m0, s74
	ds_read_b128 v[162:165], v221 offset:32768
	ds_read_b128 v[170:173], v221 offset:33792
	ds_read_b128 v[182:185], v221 offset:34816
	ds_read_b128 v[186:189], v221 offset:35840
	ds_read_b128 v[190:193], v221 offset:36864
	ds_read_b128 v[194:197], v221 offset:37888
	ds_read_b128 v[198:201], v221 offset:38912
	ds_read_b128 v[202:205], v221 offset:39936
	buffer_load_dwordx4 v178, s[76:79], s50 offen lds
	s_mov_b32 m0, s12
	s_nop 0
	buffer_load_dwordx4 v210, s[76:79], s50 offen lds
	s_waitcnt vmcnt(8)
	s_waitcnt lgkmcnt(0)
	s_setprio 1
	s_barrier
	v_mfma_f32_16x16x32_bf16 v[126:129], v[130:133], v[162:165], v[126:129]
	v_mfma_f32_16x16x32_bf16 v[110:113], v[138:141], v[162:165], v[110:113]
	v_mfma_f32_16x16x32_bf16 v[118:121], v[130:133], v[182:185], v[118:121]
	v_mfma_f32_16x16x32_bf16 v[102:105], v[138:141], v[182:185], v[102:105]
	v_mfma_f32_16x16x32_bf16 v[114:117], v[130:133], v[190:193], v[114:117]
	v_mfma_f32_16x16x32_bf16 v[98:101], v[138:141], v[190:193], v[98:101]
	v_mfma_f32_16x16x32_bf16 v[122:125], v[130:133], v[198:201], v[122:125]
	v_mfma_f32_16x16x32_bf16 v[106:109], v[138:141], v[198:201], v[106:109]
	v_mfma_f32_16x16x32_bf16 v[126:129], v[134:137], v[170:173], v[126:129]
	v_mfma_f32_16x16x32_bf16 v[110:113], v[142:145], v[170:173], v[110:113]
	v_mfma_f32_16x16x32_bf16 v[118:121], v[134:137], v[186:189], v[118:121]
	v_mfma_f32_16x16x32_bf16 v[102:105], v[142:145], v[186:189], v[102:105]
	v_mfma_f32_16x16x32_bf16 v[114:117], v[134:137], v[194:197], v[114:117]
	v_mfma_f32_16x16x32_bf16 v[98:101], v[142:145], v[194:197], v[98:101]
	v_mfma_f32_16x16x32_bf16 v[122:125], v[134:137], v[202:205], v[122:125]
	v_mfma_f32_16x16x32_bf16 v[106:109], v[142:145], v[202:205], v[106:109]
	v_mfma_f32_16x16x32_bf16 v[62:65], v[146:149], v[162:165], v[62:65]
	v_mfma_f32_16x16x32_bf16 v[46:49], v[154:157], v[162:165], v[46:49]
	v_mfma_f32_16x16x32_bf16 v[54:57], v[146:149], v[182:185], v[54:57]
	v_mfma_f32_16x16x32_bf16 v[38:41], v[154:157], v[182:185], v[38:41]
	v_mfma_f32_16x16x32_bf16 v[50:53], v[146:149], v[190:193], v[50:53]
	v_mfma_f32_16x16x32_bf16 v[34:37], v[154:157], v[190:193], v[34:37]
	v_mfma_f32_16x16x32_bf16 v[58:61], v[146:149], v[198:201], v[58:61]
	v_mfma_f32_16x16x32_bf16 v[42:45], v[154:157], v[198:201], v[42:45]
	v_mfma_f32_16x16x32_bf16 v[62:65], v[150:153], v[170:173], v[62:65]
	v_mfma_f32_16x16x32_bf16 v[46:49], v[158:161], v[170:173], v[46:49]
	v_mfma_f32_16x16x32_bf16 v[54:57], v[150:153], v[186:189], v[54:57]
	v_mfma_f32_16x16x32_bf16 v[38:41], v[158:161], v[186:189], v[38:41]
	v_mfma_f32_16x16x32_bf16 v[50:53], v[150:153], v[194:197], v[50:53]
	v_mfma_f32_16x16x32_bf16 v[34:37], v[158:161], v[194:197], v[34:37]
	v_mfma_f32_16x16x32_bf16 v[58:61], v[150:153], v[202:205], v[58:61]
	v_mfma_f32_16x16x32_bf16 v[42:45], v[158:161], v[202:205], v[42:45]
	s_barrier
	s_setprio 0
	s_mov_b32 m0, s13
	s_or_b32 s50, s31, 0x80
	ds_read_b128 v[162:165], v221 offset:49152
	ds_read_b128 v[170:173], v221 offset:50176
	ds_read_b128 v[182:185], v221 offset:51200
	ds_read_b128 v[186:189], v221 offset:52224
	ds_read_b128 v[190:193], v221 offset:53248
	ds_read_b128 v[194:197], v221 offset:54272
	ds_read_b128 v[198:201], v221 offset:55296
	ds_read_b128 v[202:205], v221 offset:56320
	buffer_load_dwordx4 v179, s[56:59], s50 offen lds
	s_mov_b32 m0, s14
	s_add_i32 s31, s31, 0x80080
	buffer_load_dwordx4 v211, s[56:59], s50 offen lds
	s_mov_b32 m0, s17
	s_nop 0
	buffer_load_dwordx4 v179, s[56:59], s31 offen lds
	s_mov_b32 m0, s18
	s_nop 0
	buffer_load_dwordx4 v211, s[56:59], s31 offen lds
	s_mov_b32 m0, s15
	s_nop 0
	buffer_load_dwordx4 v178, s[76:79], s30 offen lds
	s_mov_b32 m0, s16
	s_nop 0
	buffer_load_dwordx4 v210, s[76:79], s30 offen lds
	s_waitcnt vmcnt(8)
	s_waitcnt lgkmcnt(0)
	s_setprio 1
	s_barrier
	v_mfma_f32_16x16x32_bf16 v[94:97], v[130:133], v[162:165], v[94:97]
	v_mfma_f32_16x16x32_bf16 v[78:81], v[138:141], v[162:165], v[78:81]
	v_mfma_f32_16x16x32_bf16 v[86:89], v[130:133], v[182:185], v[86:89]
	v_mfma_f32_16x16x32_bf16 v[70:73], v[138:141], v[182:185], v[70:73]
	v_mfma_f32_16x16x32_bf16 v[82:85], v[130:133], v[190:193], v[82:85]
	v_mfma_f32_16x16x32_bf16 v[66:69], v[138:141], v[190:193], v[66:69]
	v_mfma_f32_16x16x32_bf16 v[90:93], v[130:133], v[198:201], v[90:93]
	v_mfma_f32_16x16x32_bf16 v[74:77], v[138:141], v[198:201], v[74:77]
	v_mfma_f32_16x16x32_bf16 v[94:97], v[134:137], v[170:173], v[94:97]
	v_mfma_f32_16x16x32_bf16 v[78:81], v[142:145], v[170:173], v[78:81]
	v_mfma_f32_16x16x32_bf16 v[86:89], v[134:137], v[186:189], v[86:89]
	v_mfma_f32_16x16x32_bf16 v[70:73], v[142:145], v[186:189], v[70:73]
	v_mfma_f32_16x16x32_bf16 v[82:85], v[134:137], v[194:197], v[82:85]
	v_mfma_f32_16x16x32_bf16 v[66:69], v[142:145], v[194:197], v[66:69]
	v_mfma_f32_16x16x32_bf16 v[90:93], v[134:137], v[202:205], v[90:93]
	v_mfma_f32_16x16x32_bf16 v[74:77], v[142:145], v[202:205], v[74:77]
	v_mfma_f32_16x16x32_bf16 v[30:33], v[146:149], v[162:165], v[30:33]
	v_mfma_f32_16x16x32_bf16 v[14:17], v[154:157], v[162:165], v[14:17]
	v_mfma_f32_16x16x32_bf16 v[22:25], v[146:149], v[182:185], v[22:25]
	v_mfma_f32_16x16x32_bf16 v[10:13], v[154:157], v[182:185], v[10:13]
	v_mfma_f32_16x16x32_bf16 v[18:21], v[146:149], v[190:193], v[18:21]
	v_mfma_f32_16x16x32_bf16 v[2:5], v[154:157], v[190:193], v[2:5]
	v_mfma_f32_16x16x32_bf16 v[26:29], v[146:149], v[198:201], v[26:29]
	v_mfma_f32_16x16x32_bf16 v[6:9], v[154:157], v[198:201], v[6:9]
	v_mfma_f32_16x16x32_bf16 v[30:33], v[150:153], v[170:173], v[30:33]
	v_mfma_f32_16x16x32_bf16 v[14:17], v[158:161], v[170:173], v[14:17]
	v_mfma_f32_16x16x32_bf16 v[22:25], v[150:153], v[186:189], v[22:25]
	v_mfma_f32_16x16x32_bf16 v[10:13], v[158:161], v[186:189], v[10:13]
	v_mfma_f32_16x16x32_bf16 v[18:21], v[150:153], v[194:197], v[18:21]
	v_mfma_f32_16x16x32_bf16 v[2:5], v[158:161], v[194:197], v[2:5]
	v_mfma_f32_16x16x32_bf16 v[26:29], v[150:153], v[202:205], v[26:29]
	v_mfma_f32_16x16x32_bf16 v[6:9], v[158:161], v[202:205], v[6:9]
	s_barrier
	s_setprio 0
	s_add_i32 s29, s29, 2
	s_addk_i32 s7, 0x100
	s_addk_i32 s28, 0x100
	s_cmp_gt_u32 s29, 29
	s_cbranch_scc0 .LBB0_437
	s_and_b64 vcc, exec, s[84:85]
	s_cbranch_vccz .LBB0_440
	s_barrier

; #define PG8_STAGEX(rs, bufoff, soff, voff) do { _Pragma("unroll") for (int _i = 0; _i < 2; ++_i) \
;         __builtin_amdgcn_raw_ptr_buffer_load_lds(rs, (LAS unsigned*)(lds + (bufoff) + ldsw + _i * 8192), 16, (voff)[_i], (soff), 0, 0); } while (0)
; #define PG8_LDA(dst, b, h) do { _Pragma("unroll") for (int m = 0; m < 4; ++m) _Pragma("unroll") for (int k = 0; k < 2; ++k) dst[m][k] = *(const LAS bf16x8*)(lds + PG8_SA(b, h) + aoff + m * 2048 + k * 1024); } while (0)
; #define PG8_LDB(dst, b, h) do { _Pragma("unroll") for (int n = 0; n < 2; ++n) _Pragma("unroll") for (int k = 0; k < 2; ++k) dst[n][k] = *(const LAS bf16x8*)(lds + PG8_SB(b, h) + boff + n * 2048 + k * 1024); } while (0)
; #define PG8_WAIT_V(n) asm volatile("s_waitcnt vmcnt(" #n ")" ::: "memory")
; #define PG8_WAIT_L(n) asm volatile("s_waitcnt lgkmcnt(" #n ")" ::: "memory")
; #define PG8_BAR __builtin_amdgcn_s_barrier()
; #define PG8_SCHED __builtin_amdgcn_sched_barrier(0)
;     ...
;             for (int t = 0; t < nt; t += 2) {
;                 const bool last = (t == nt - 2);
;                 const unsigned a1 = cA + (unsigned)(t + 1) * kstep;
;                 const unsigned a2 = last ? nA : cA + (unsigned)(t + 2) * kstep, b2 = last ? nB : cB + (unsigned)(t + 2) * kstep;
;                 const unsigned a3 = a2 + kstep, b3 = b2 + kstep;
;                 if (w0) { PG8_LDB(B0, 0, 0); PG8_LDB(B1, 0, 1); PG8_SCHED; PG8_LDA(At, 0, 0); }
;                 PG8_WAIT_L(0); PG8_BAR; if (w0) { PG8_MMA(0, 0, At, B0); PG8_MMA(0, 1, At, B1); } PG8_BAR; PG8_SCHED;
;                 PG8_STAGEX(rsB, PG8_SB(0, 0), b2, voffB); PG8_STAGEX(rsB, PG8_SB(0, 1), b2 + hstepB, voffB); PG8_STAGEX(rsA, PG8_SA(0, 0), a2, voffA);
;                 PG8_WAIT_V(6); PG8_BAR; PG8_BAR; PG8_SCHED;
.LBB0_542:
	v_add_u32_e32 v73, 0x10000, v71
	ds_read_b128 v[74:77], v73
	ds_read_b128 v[78:81], v73 offset:1024
	ds_read_b128 v[82:85], v73 offset:2048
	ds_read_b128 v[86:89], v73 offset:3072
	v_add_u32_e32 v73, 0x14000, v71
	ds_read_b128 v[90:93], v73
	ds_read_b128 v[94:97], v73 offset:1024
	ds_read_b128 v[98:101], v73 offset:2048
	ds_read_b128 v[110:113], v73 offset:3072
	s_cmp_lg_u32 s26, 28
	s_cselect_b32 s27, s25, 0
	s_add_i32 s28, s27, s17
	s_or_b32 s29, s28, 0x80
	s_add_i32 s27, s27, s10
	ds_read_b128 v[114:117], v72
	ds_read_b128 v[118:121], v72 offset:1024
	ds_read_b128 v[122:125], v72 offset:2048
	ds_read_b128 v[126:129], v72 offset:3072
	ds_read_b128 v[130:133], v72 offset:4096
	ds_read_b128 v[134:137], v72 offset:5120
	ds_read_b128 v[138:141], v72 offset:6144
	ds_read_b128 v[142:145], v72 offset:7168
	s_waitcnt lgkmcnt(0)
	s_setprio 1
	s_barrier
	v_mfma_f32_16x16x32_bf16 v[62:65], v[74:77], v[114:117], v[62:65]
	v_mfma_f32_16x16x32_bf16 v[46:49], v[82:85], v[114:117], v[46:49]
	v_mfma_f32_16x16x32_bf16 v[54:57], v[74:77], v[122:125], v[54:57]
	v_mfma_f32_16x16x32_bf16 v[38:41], v[82:85], v[122:125], v[38:41]
	v_mfma_f32_16x16x32_bf16 v[50:53], v[74:77], v[130:133], v[50:53]
	v_mfma_f32_16x16x32_bf16 v[34:37], v[82:85], v[130:133], v[34:37]
	v_mfma_f32_16x16x32_bf16 v[58:61], v[74:77], v[138:141], v[58:61]
	v_mfma_f32_16x16x32_bf16 v[42:45], v[82:85], v[138:141], v[42:45]
	v_mfma_f32_16x16x32_bf16 v[62:65], v[78:81], v[118:121], v[62:65]
	v_mfma_f32_16x16x32_bf16 v[46:49], v[86:89], v[118:121], v[46:49]
	v_mfma_f32_16x16x32_bf16 v[54:57], v[78:81], v[126:129], v[54:57]
	v_mfma_f32_16x16x32_bf16 v[38:41], v[86:89], v[126:129], v[38:41]
	v_mfma_f32_16x16x32_bf16 v[50:53], v[78:81], v[134:137], v[50:53]
	v_mfma_f32_16x16x32_bf16 v[34:37], v[86:89], v[134:137], v[34:37]
	v_mfma_f32_16x16x32_bf16 v[58:61], v[78:81], v[142:145], v[58:61]
	v_mfma_f32_16x16x32_bf16 v[42:45], v[86:89], v[142:145], v[42:45]
	v_mfma_f32_16x16x32_bf16 v[30:33], v[90:93], v[114:117], v[30:33]
	v_mfma_f32_16x16x32_bf16 v[14:17], v[98:101], v[114:117], v[14:17]
	v_mfma_f32_16x16x32_bf16 v[22:25], v[90:93], v[122:125], v[22:25]
	v_mfma_f32_16x16x32_bf16 v[10:13], v[98:101], v[122:125], v[10:13]
	v_mfma_f32_16x16x32_bf16 v[18:21], v[90:93], v[130:133], v[18:21]
	v_mfma_f32_16x16x32_bf16 v[2:5], v[98:101], v[130:133], v[2:5]
	v_mfma_f32_16x16x32_bf16 v[26:29], v[90:93], v[138:141], v[26:29]
	v_mfma_f32_16x16x32_bf16 v[6:9], v[98:101], v[138:141], v[6:9]
	v_mfma_f32_16x16x32_bf16 v[30:33], v[94:97], v[118:121], v[30:33]
	v_mfma_f32_16x16x32_bf16 v[14:17], v[110:113], v[118:121], v[14:17]
	v_mfma_f32_16x16x32_bf16 v[22:25], v[94:97], v[126:129], v[22:25]
	v_mfma_f32_16x16x32_bf16 v[10:13], v[110:113], v[126:129], v[10:13]
	v_mfma_f32_16x16x32_bf16 v[18:21], v[94:97], v[134:137], v[18:21]
	v_mfma_f32_16x16x32_bf16 v[2:5], v[110:113], v[134:137], v[2:5]
	v_mfma_f32_16x16x32_bf16 v[26:29], v[94:97], v[142:145], v[26:29]
	v_mfma_f32_16x16x32_bf16 v[6:9], v[110:113], v[142:145], v[6:9]
	s_barrier
	s_setprio 0
	s_mov_b32 m0, s12
	s_mov_b32 s58, s78
	s_mov_b32 s59, s79
	buffer_load_dwordx4 v67, s[56:59], s27 offen lds
	s_mov_b32 m0, s13
	s_add_i32 s30, s27, 0x80000
	buffer_load_dwordx4 v69, s[56:59], s27 offen lds
	s_mov_b32 m0, s14
	s_nop 0
	buffer_load_dwordx4 v67, s[56:59], s30 offen lds
	s_mov_b32 m0, s15
	s_nop 0
	buffer_load_dwordx4 v69, s[56:59], s30 offen lds
	s_mov_b32 m0, s11
	s_nop 0
	buffer_load_dwordx4 v66, s[76:79], s28 offen lds
	s_mov_b32 m0, s18
	s_nop 0
	buffer_load_dwordx4 v68, s[76:79], s28 offen lds
	s_waitcnt vmcnt(6)
	s_barrier
	s_barrier
; #define PG8_STAGEX(rs, bufoff, soff, voff) do { _Pragma("unroll") for (int _i = 0; _i < 2; ++_i) \
;         __builtin_amdgcn_raw_ptr_buffer_load_lds(rs, (LAS unsigned*)(lds + (bufoff) + ldsw + _i * 8192), 16, (voff)[_i], (soff), 0, 0); } while (0)
; #define PG8_LDA(dst, b, h) do { _Pragma("unroll") for (int m = 0; m < 4; ++m) _Pragma("unroll") for (int k = 0; k < 2; ++k) dst[m][k] = *(const LAS bf16x8*)(lds + PG8_SA(b, h) + aoff + m * 2048 + k * 1024); } while (0)
; #define PG8_LDB(dst, b, h) do { _Pragma("unroll") for (int n = 0; n < 2; ++n) _Pragma("unroll") for (int k = 0; k < 2; ++k) dst[n][k] = *(const LAS bf16x8*)(lds + PG8_SB(b, h) + boff + n * 2048 + k * 1024); } while (0)
; #define PG8_WAIT_V(n) asm volatile("s_waitcnt vmcnt(" #n ")" ::: "memory")
; #define PG8_WAIT_L(n) asm volatile("s_waitcnt lgkmcnt(" #n ")" ::: "memory")
; #define PG8_BAR __builtin_amdgcn_s_barrier()
; #define PG8_SCHED __builtin_amdgcn_sched_barrier(0)
;     ...
;                 if (w0) { PG8_LDB(B0, 1, 0); PG8_LDB(B1, 1, 1); PG8_SCHED; PG8_LDA(At, 1, 0); }
;                 PG8_WAIT_L(0); PG8_BAR; if (w0) { PG8_MMA(0, 0, At, B0); PG8_MMA(0, 1, At, B1); } PG8_BAR; PG8_SCHED;
;                 PG8_STAGEX(rsB, PG8_SB(1, 0), b3, voffB); PG8_STAGEX(rsB, PG8_SB(1, 1), b3 + hstepB, voffB); PG8_STAGEX(rsA, PG8_SA(1, 0), a3, voffA);
;                 PG8_WAIT_V(6); PG8_BAR; PG8_BAR; PG8_SCHED;
;             }
;         }
;         if (wr == 0) PG8_BAR;
	v_add_u32_e32 v73, 0x18000, v71
	ds_read_b128 v[74:77], v73
	ds_read_b128 v[78:81], v73 offset:1024
	ds_read_b128 v[82:85], v73 offset:2048
	ds_read_b128 v[86:89], v73 offset:3072
	v_add_u32_e32 v73, 0x1c000, v71
	ds_read_b128 v[90:93], v73
	ds_read_b128 v[94:97], v73 offset:1024
	ds_read_b128 v[98:101], v73 offset:2048
	ds_read_b128 v[110:113], v73 offset:3072
	ds_read_b128 v[114:117], v72 offset:32768
	ds_read_b128 v[118:121], v72 offset:33792
	ds_read_b128 v[122:125], v72 offset:34816
	ds_read_b128 v[126:129], v72 offset:35840
	ds_read_b128 v[130:133], v72 offset:36864
	ds_read_b128 v[134:137], v72 offset:37888
	ds_read_b128 v[138:141], v72 offset:38912
	ds_read_b128 v[142:145], v72 offset:39936
	s_waitcnt lgkmcnt(0)
	s_setprio 1
	s_barrier
	v_mfma_f32_16x16x32_bf16 v[62:65], v[74:77], v[114:117], v[62:65]
	v_mfma_f32_16x16x32_bf16 v[46:49], v[82:85], v[114:117], v[46:49]
	v_mfma_f32_16x16x32_bf16 v[54:57], v[74:77], v[122:125], v[54:57]
	v_mfma_f32_16x16x32_bf16 v[38:41], v[82:85], v[122:125], v[38:41]
	v_mfma_f32_16x16x32_bf16 v[50:53], v[74:77], v[130:133], v[50:53]
	v_mfma_f32_16x16x32_bf16 v[34:37], v[82:85], v[130:133], v[34:37]
	v_mfma_f32_16x16x32_bf16 v[58:61], v[74:77], v[138:141], v[58:61]
	v_mfma_f32_16x16x32_bf16 v[42:45], v[82:85], v[138:141], v[42:45]
	v_mfma_f32_16x16x32_bf16 v[62:65], v[78:81], v[118:121], v[62:65]
	v_mfma_f32_16x16x32_bf16 v[46:49], v[86:89], v[118:121], v[46:49]
	v_mfma_f32_16x16x32_bf16 v[54:57], v[78:81], v[126:129], v[54:57]
	v_mfma_f32_16x16x32_bf16 v[38:41], v[86:89], v[126:129], v[38:41]
	v_mfma_f32_16x16x32_bf16 v[50:53], v[78:81], v[134:137], v[50:53]
	v_mfma_f32_16x16x32_bf16 v[34:37], v[86:89], v[134:137], v[34:37]
	v_mfma_f32_16x16x32_bf16 v[58:61], v[78:81], v[142:145], v[58:61]
	v_mfma_f32_16x16x32_bf16 v[42:45], v[86:89], v[142:145], v[42:45]
	v_mfma_f32_16x16x32_bf16 v[30:33], v[90:93], v[114:117], v[30:33]
	s_or_b32 s28, s27, 0x80
	v_mfma_f32_16x16x32_bf16 v[14:17], v[98:101], v[114:117], v[14:17]
	v_mfma_f32_16x16x32_bf16 v[22:25], v[90:93], v[122:125], v[22:25]
	v_mfma_f32_16x16x32_bf16 v[10:13], v[98:101], v[122:125], v[10:13]
	v_mfma_f32_16x16x32_bf16 v[18:21], v[90:93], v[130:133], v[18:21]
	v_mfma_f32_16x16x32_bf16 v[2:5], v[98:101], v[130:133], v[2:5]
	v_mfma_f32_16x16x32_bf16 v[26:29], v[90:93], v[138:141], v[26:29]
	v_mfma_f32_16x16x32_bf16 v[6:9], v[98:101], v[138:141], v[6:9]
	v_mfma_f32_16x16x32_bf16 v[30:33], v[94:97], v[118:121], v[30:33]
	v_mfma_f32_16x16x32_bf16 v[14:17], v[110:113], v[118:121], v[14:17]
	v_mfma_f32_16x16x32_bf16 v[22:25], v[94:97], v[126:129], v[22:25]
	v_mfma_f32_16x16x32_bf16 v[10:13], v[110:113], v[126:129], v[10:13]
	v_mfma_f32_16x16x32_bf16 v[18:21], v[94:97], v[134:137], v[18:21]
	v_mfma_f32_16x16x32_bf16 v[2:5], v[110:113], v[134:137], v[2:5]
	v_mfma_f32_16x16x32_bf16 v[26:29], v[94:97], v[142:145], v[26:29]
	v_mfma_f32_16x16x32_bf16 v[6:9], v[110:113], v[142:145], v[6:9]
	s_barrier
	s_setprio 0
	s_mov_b32 m0, s19
	s_add_i32 s27, s27, 0x80080
	buffer_load_dwordx4 v67, s[56:59], s28 offen lds
	s_mov_b32 m0, s20
	s_nop 0
	buffer_load_dwordx4 v69, s[56:59], s28 offen lds
	s_mov_b32 m0, s23
	s_nop 0
	buffer_load_dwordx4 v67, s[56:59], s27 offen lds
	s_mov_b32 m0, s24
	s_nop 0
	buffer_load_dwordx4 v69, s[56:59], s27 offen lds
	s_mov_b32 m0, s21
	s_nop 0
	buffer_load_dwordx4 v66, s[76:79], s29 offen lds
	s_mov_b32 m0, s22
	s_nop 0
	buffer_load_dwordx4 v68, s[76:79], s29 offen lds
	s_waitcnt vmcnt(6)
	s_barrier
	s_barrier
	s_addk_i32 s25, 0x100
	s_add_i32 s26, s26, 2
	s_cmp_gt_u32 s26, 29
	s_cbranch_scc0 .LBB0_542
	s_cmpk_lt_u32 s1, 0x100
	s_cbranch_scc0 .LBB0_545
	s_barrier

; #define PG8_STAGEX(rs, bufoff, soff, voff) do { _Pragma("unroll") for (int _i = 0; _i < 2; ++_i) \
;         __builtin_amdgcn_raw_ptr_buffer_load_lds(rs, (LAS unsigned*)(lds + (bufoff) + ldsw + _i * 8192), 16, (voff)[_i], (soff), 0, 0); } while (0)
; #define PG8_LDA(dst, b, h) do { _Pragma("unroll") for (int m = 0; m < 4; ++m) _Pragma("unroll") for (int k = 0; k < 2; ++k) dst[m][k] = *(const LAS bf16x8*)(lds + PG8_SA(b, h) + aoff + m * 2048 + k * 1024); } while (0)
; #define PG8_LDB(dst, b, h) do { _Pragma("unroll") for (int n = 0; n < 2; ++n) _Pragma("unroll") for (int k = 0; k < 2; ++k) dst[n][k] = *(const LAS bf16x8*)(lds + PG8_SB(b, h) + boff + n * 2048 + k * 1024); } while (0)
; #define PG8_WAIT_V(n) asm volatile("s_waitcnt vmcnt(" #n ")" ::: "memory")
; #define PG8_WAIT_L(n) asm volatile("s_waitcnt lgkmcnt(" #n ")" ::: "memory")
; #define PG8_BAR __builtin_amdgcn_s_barrier()
; #define PG8_SCHED __builtin_amdgcn_sched_barrier(0)
;     ...
;             const bool last = (t == nt - 2);
;             const unsigned a1 = cA + (unsigned)(t + 1) * kstep;
;             const unsigned a2 = last ? nA : cA + (unsigned)(t + 2) * kstep, b2 = last ? nB : cB + (unsigned)(t + 2) * kstep;
;             const unsigned a3 = a2 + kstep, b3 = b2 + kstep;
;             PG8_LDB(B0, 0, 0); PG8_LDB(B1, 0, 1); PG8_SCHED; PG8_LDA(At, 0, 0); PG8_STAGEX(rsA, PG8_SA(1, 1), a1 + hstepA, voffA);
;             PG8_WAIT_V(8); PG8_WAIT_L(0); PG8_BAR; PG8_MMA(0, 0, At, B0); PG8_MMA(0, 1, At, B1); PG8_BAR; PG8_SCHED;
;             PG8_LDA(At, 0, 1); PG8_STAGEX(rsB, PG8_SB(0, 0), b2, voffB); PG8_STAGEX(rsB, PG8_SB(0, 1), b2 + hstepB, voffB); PG8_STAGEX(rsA, PG8_SA(0, 0), a2, voffA);
;             PG8_WAIT_V(8); PG8_WAIT_L(0); PG8_BAR; PG8_MMA(1, 0, At, B0); PG8_MMA(1, 1, At, B1); PG8_BAR; PG8_SCHED;
.LBB0_788:
	v_add_u32_e32 v150, 0x10000, v153
	ds_read_b128 v[138:141], v150
	ds_read_b128 v[142:145], v150 offset:1024
	ds_read_b128 v[146:149], v150 offset:2048
	ds_read_b128 v[156:159], v150 offset:3072
	v_add_u32_e32 v150, 0x14000, v153
	ds_read_b128 v[160:163], v150
	ds_read_b128 v[164:167], v150 offset:1024
	ds_read_b128 v[182:185], v150 offset:2048
	ds_read_b128 v[186:189], v150 offset:3072
	s_add_i32 s48, s31, 0xfffc0080
	s_cmp_eq_u32 s55, s47
	s_cselect_b32 s50, s7, s48
	s_cselect_b32 s49, s30, s46
	s_add_i32 s48, s50, 0x80
	s_mov_b32 m0, s35
	ds_read_b128 v[190:193], v154
	ds_read_b128 v[194:197], v154 offset:1024
	ds_read_b128 v[198:201], v154 offset:2048
	ds_read_b128 v[202:205], v154 offset:3072
	ds_read_b128 v[206:209], v154 offset:4096
	ds_read_b128 v[210:213], v154 offset:5120
	ds_read_b128 v[214:217], v154 offset:6144
	ds_read_b128 v[218:221], v154 offset:7168
	buffer_load_dwordx4 v130, s[76:79], s31 offen lds
	s_mov_b32 m0, s82
	s_nop 0
	buffer_load_dwordx4 v134, s[76:79], s31 offen lds
	s_waitcnt vmcnt(8)
	s_waitcnt lgkmcnt(0)
	s_setprio 1
	s_barrier
	v_mfma_f32_16x16x32_bf16 v[126:129], v[190:193], v[138:141], v[126:129]
	v_mfma_f32_16x16x32_bf16 v[62:65], v[190:193], v[146:149], v[62:65]
	v_mfma_f32_16x16x32_bf16 v[118:121], v[198:201], v[138:141], v[118:121]
	v_mfma_f32_16x16x32_bf16 v[54:57], v[198:201], v[146:149], v[54:57]
	v_mfma_f32_16x16x32_bf16 v[110:113], v[206:209], v[138:141], v[110:113]
	v_mfma_f32_16x16x32_bf16 v[46:49], v[206:209], v[146:149], v[46:49]
	v_mfma_f32_16x16x32_bf16 v[102:105], v[214:217], v[138:141], v[102:105]
	v_mfma_f32_16x16x32_bf16 v[38:41], v[214:217], v[146:149], v[38:41]
	v_mfma_f32_16x16x32_bf16 v[126:129], v[194:197], v[142:145], v[126:129]
	v_mfma_f32_16x16x32_bf16 v[62:65], v[194:197], v[156:159], v[62:65]
	v_mfma_f32_16x16x32_bf16 v[118:121], v[202:205], v[142:145], v[118:121]
	v_mfma_f32_16x16x32_bf16 v[54:57], v[202:205], v[156:159], v[54:57]
	v_mfma_f32_16x16x32_bf16 v[110:113], v[210:213], v[142:145], v[110:113]
	v_mfma_f32_16x16x32_bf16 v[46:49], v[210:213], v[156:159], v[46:49]
	v_mfma_f32_16x16x32_bf16 v[102:105], v[218:221], v[142:145], v[102:105]
	v_mfma_f32_16x16x32_bf16 v[38:41], v[218:221], v[156:159], v[38:41]
	v_mfma_f32_16x16x32_bf16 v[122:125], v[190:193], v[160:163], v[122:125]
	v_mfma_f32_16x16x32_bf16 v[58:61], v[190:193], v[182:185], v[58:61]
	v_mfma_f32_16x16x32_bf16 v[114:117], v[198:201], v[160:163], v[114:117]
	v_mfma_f32_16x16x32_bf16 v[50:53], v[198:201], v[182:185], v[50:53]
	v_mfma_f32_16x16x32_bf16 v[106:109], v[206:209], v[160:163], v[106:109]
	v_mfma_f32_16x16x32_bf16 v[42:45], v[206:209], v[182:185], v[42:45]
	v_mfma_f32_16x16x32_bf16 v[98:101], v[214:217], v[160:163], v[98:101]
	v_mfma_f32_16x16x32_bf16 v[34:37], v[214:217], v[182:185], v[34:37]
	v_mfma_f32_16x16x32_bf16 v[122:125], v[194:197], v[164:167], v[122:125]
	v_mfma_f32_16x16x32_bf16 v[58:61], v[194:197], v[186:189], v[58:61]
	v_mfma_f32_16x16x32_bf16 v[114:117], v[202:205], v[164:167], v[114:117]
	v_mfma_f32_16x16x32_bf16 v[50:53], v[202:205], v[186:189], v[50:53]
	v_mfma_f32_16x16x32_bf16 v[106:109], v[210:213], v[164:167], v[106:109]
	v_mfma_f32_16x16x32_bf16 v[42:45], v[210:213], v[186:189], v[42:45]
	v_mfma_f32_16x16x32_bf16 v[98:101], v[218:221], v[164:167], v[98:101]
	v_mfma_f32_16x16x32_bf16 v[34:37], v[218:221], v[186:189], v[34:37]
	s_barrier
	s_setprio 0
	s_mov_b32 m0, s15
	s_mov_b32 s86, s78
	s_mov_b32 s87, s79
	ds_read_b128 v[190:193], v154 offset:16384
	ds_read_b128 v[194:197], v154 offset:17408
	ds_read_b128 v[198:201], v154 offset:18432
	ds_read_b128 v[202:205], v154 offset:19456
	ds_read_b128 v[206:209], v154 offset:20480
	ds_read_b128 v[210:213], v154 offset:21504
	ds_read_b128 v[214:217], v154 offset:22528
	ds_read_b128 v[218:221], v154 offset:23552
	buffer_load_dwordx4 v132, s[84:87], s49 offen lds
	s_mov_b32 m0, s16
	s_add_i32 s51, s49, 0x8000
	buffer_load_dwordx4 v136, s[84:87], s49 offen lds
	s_mov_b32 m0, s17
	s_nop 0
	buffer_load_dwordx4 v132, s[84:87], s51 offen lds
	s_mov_b32 m0, s18
	s_nop 0
	buffer_load_dwordx4 v136, s[84:87], s51 offen lds
	s_mov_b32 m0, s14
	s_nop 0
	buffer_load_dwordx4 v130, s[76:79], s50 offen lds
	s_mov_b32 m0, s19
	s_nop 0
	buffer_load_dwordx4 v134, s[76:79], s50 offen lds
	s_waitcnt vmcnt(8)
	s_waitcnt lgkmcnt(0)
	s_setprio 1
	s_barrier
	v_mfma_f32_16x16x32_bf16 v[94:97], v[190:193], v[138:141], v[94:97]
	v_mfma_f32_16x16x32_bf16 v[30:33], v[190:193], v[146:149], v[30:33]
	v_mfma_f32_16x16x32_bf16 v[86:89], v[198:201], v[138:141], v[86:89]
	v_mfma_f32_16x16x32_bf16 v[22:25], v[198:201], v[146:149], v[22:25]
	v_mfma_f32_16x16x32_bf16 v[78:81], v[206:209], v[138:141], v[78:81]
	v_mfma_f32_16x16x32_bf16 v[14:17], v[206:209], v[146:149], v[14:17]
	v_mfma_f32_16x16x32_bf16 v[70:73], v[214:217], v[138:141], v[70:73]
	v_mfma_f32_16x16x32_bf16 v[6:9], v[214:217], v[146:149], v[6:9]
	v_mfma_f32_16x16x32_bf16 v[94:97], v[194:197], v[142:145], v[94:97]
	v_mfma_f32_16x16x32_bf16 v[30:33], v[194:197], v[156:159], v[30:33]
	v_mfma_f32_16x16x32_bf16 v[86:89], v[202:205], v[142:145], v[86:89]
	v_mfma_f32_16x16x32_bf16 v[22:25], v[202:205], v[156:159], v[22:25]
	v_mfma_f32_16x16x32_bf16 v[78:81], v[210:213], v[142:145], v[78:81]
	v_mfma_f32_16x16x32_bf16 v[14:17], v[210:213], v[156:159], v[14:17]
	v_mfma_f32_16x16x32_bf16 v[70:73], v[218:221], v[142:145], v[70:73]
	v_mfma_f32_16x16x32_bf16 v[6:9], v[218:221], v[156:159], v[6:9]
	v_mfma_f32_16x16x32_bf16 v[90:93], v[190:193], v[160:163], v[90:93]
	v_mfma_f32_16x16x32_bf16 v[26:29], v[190:193], v[182:185], v[26:29]
	v_mfma_f32_16x16x32_bf16 v[82:85], v[198:201], v[160:163], v[82:85]
	v_mfma_f32_16x16x32_bf16 v[18:21], v[198:201], v[182:185], v[18:21]
	v_mfma_f32_16x16x32_bf16 v[74:77], v[206:209], v[160:163], v[74:77]
	v_mfma_f32_16x16x32_bf16 v[10:13], v[206:209], v[182:185], v[10:13]
	v_mfma_f32_16x16x32_bf16 v[66:69], v[214:217], v[160:163], v[66:69]
	v_mfma_f32_16x16x32_bf16 v[2:5], v[214:217], v[182:185], v[2:5]
	v_mfma_f32_16x16x32_bf16 v[90:93], v[194:197], v[164:167], v[90:93]
	v_mfma_f32_16x16x32_bf16 v[26:29], v[194:197], v[186:189], v[26:29]
	v_mfma_f32_16x16x32_bf16 v[82:85], v[202:205], v[164:167], v[82:85]
	v_mfma_f32_16x16x32_bf16 v[18:21], v[202:205], v[186:189], v[18:21]
	v_mfma_f32_16x16x32_bf16 v[74:77], v[210:213], v[164:167], v[74:77]
	v_mfma_f32_16x16x32_bf16 v[10:13], v[210:213], v[186:189], v[10:13]
	v_mfma_f32_16x16x32_bf16 v[66:69], v[218:221], v[164:167], v[66:69]
	v_mfma_f32_16x16x32_bf16 v[2:5], v[218:221], v[186:189], v[2:5]
	s_barrier
; #define PG8_STAGEX(rs, bufoff, soff, voff) do { _Pragma("unroll") for (int _i = 0; _i < 2; ++_i) \
;         __builtin_amdgcn_raw_ptr_buffer_load_lds(rs, (LAS unsigned*)(lds + (bufoff) + ldsw + _i * 8192), 16, (voff)[_i], (soff), 0, 0); } while (0)
; #define PG8_LDA(dst, b, h) do { _Pragma("unroll") for (int m = 0; m < 4; ++m) _Pragma("unroll") for (int k = 0; k < 2; ++k) dst[m][k] = *(const LAS bf16x8*)(lds + PG8_SA(b, h) + aoff + m * 2048 + k * 1024); } while (0)
; #define PG8_LDB(dst, b, h) do { _Pragma("unroll") for (int n = 0; n < 2; ++n) _Pragma("unroll") for (int k = 0; k < 2; ++k) dst[n][k] = *(const LAS bf16x8*)(lds + PG8_SB(b, h) + boff + n * 2048 + k * 1024); } while (0)
; #define PG8_WAIT_V(n) asm volatile("s_waitcnt vmcnt(" #n ")" ::: "memory")
; #define PG8_WAIT_L(n) asm volatile("s_waitcnt lgkmcnt(" #n ")" ::: "memory")
; #define PG8_BAR __builtin_amdgcn_s_barrier()
; #define PG8_SCHED __builtin_amdgcn_sched_barrier(0)
;     ...
;             PG8_WAIT_V(8); PG8_WAIT_L(0); PG8_BAR; PG8_MMA(1, 0, At, B0); PG8_MMA(1, 1, At, B1); PG8_BAR; PG8_SCHED;
;             PG8_LDB(B0, 1, 0); PG8_LDB(B1, 1, 1); PG8_SCHED; PG8_LDA(At, 1, 0); PG8_STAGEX(rsA, PG8_SA(0, 1), a2 + hstepA, voffA);
;             PG8_WAIT_V(8); PG8_WAIT_L(0); PG8_BAR; PG8_MMA(0, 0, At, B0); PG8_MMA(0, 1, At, B1); PG8_BAR; PG8_SCHED;
;             PG8_LDA(At, 1, 1); PG8_STAGEX(rsB, PG8_SB(1, 0), b3, voffB); PG8_STAGEX(rsB, PG8_SB(1, 1), b3 + hstepB, voffB); PG8_STAGEX(rsA, PG8_SA(1, 0), a3, voffA);
;             PG8_WAIT_V(8); PG8_WAIT_L(0); PG8_BAR; PG8_MMA(1, 0, At, B0); PG8_MMA(1, 1, At, B1); PG8_BAR; PG8_SCHED;
;         }
;     ...
;         if (wr == 0) PG8_BAR;
	s_setprio 0
	v_add_u32_e32 v150, 0x18000, v153
	ds_read_b128 v[138:141], v150
	ds_read_b128 v[142:145], v150 offset:1024
	ds_read_b128 v[146:149], v150 offset:2048
	ds_read_b128 v[156:159], v150 offset:3072
	v_add_u32_e32 v150, 0x1c000, v153
	ds_read_b128 v[160:163], v150
	ds_read_b128 v[164:167], v150 offset:1024
	ds_read_b128 v[182:185], v150 offset:2048
	ds_read_b128 v[186:189], v150 offset:3072
	s_add_i32 s50, s50, 0x40000
	s_mov_b32 m0, s20
	ds_read_b128 v[190:193], v154 offset:32768
	ds_read_b128 v[194:197], v154 offset:33792
	ds_read_b128 v[198:201], v154 offset:34816
	ds_read_b128 v[202:205], v154 offset:35840
	ds_read_b128 v[206:209], v154 offset:36864
	ds_read_b128 v[210:213], v154 offset:37888
	ds_read_b128 v[214:217], v154 offset:38912
	ds_read_b128 v[218:221], v154 offset:39936
	buffer_load_dwordx4 v130, s[76:79], s50 offen lds
	s_mov_b32 m0, s21
	s_nop 0
	buffer_load_dwordx4 v134, s[76:79], s50 offen lds
	s_waitcnt vmcnt(8)
	s_waitcnt lgkmcnt(0)
	s_setprio 1
	s_barrier
	v_mfma_f32_16x16x32_bf16 v[126:129], v[190:193], v[138:141], v[126:129]
	v_mfma_f32_16x16x32_bf16 v[62:65], v[190:193], v[146:149], v[62:65]
	v_mfma_f32_16x16x32_bf16 v[118:121], v[198:201], v[138:141], v[118:121]
	v_mfma_f32_16x16x32_bf16 v[54:57], v[198:201], v[146:149], v[54:57]
	v_mfma_f32_16x16x32_bf16 v[110:113], v[206:209], v[138:141], v[110:113]
	v_mfma_f32_16x16x32_bf16 v[46:49], v[206:209], v[146:149], v[46:49]
	v_mfma_f32_16x16x32_bf16 v[102:105], v[214:217], v[138:141], v[102:105]
	v_mfma_f32_16x16x32_bf16 v[38:41], v[214:217], v[146:149], v[38:41]
	v_mfma_f32_16x16x32_bf16 v[126:129], v[194:197], v[142:145], v[126:129]
	v_mfma_f32_16x16x32_bf16 v[62:65], v[194:197], v[156:159], v[62:65]
	v_mfma_f32_16x16x32_bf16 v[118:121], v[202:205], v[142:145], v[118:121]
	v_mfma_f32_16x16x32_bf16 v[54:57], v[202:205], v[156:159], v[54:57]
	v_mfma_f32_16x16x32_bf16 v[110:113], v[210:213], v[142:145], v[110:113]
	v_mfma_f32_16x16x32_bf16 v[46:49], v[210:213], v[156:159], v[46:49]
	v_mfma_f32_16x16x32_bf16 v[102:105], v[218:221], v[142:145], v[102:105]
	v_mfma_f32_16x16x32_bf16 v[38:41], v[218:221], v[156:159], v[38:41]
	v_mfma_f32_16x16x32_bf16 v[122:125], v[190:193], v[160:163], v[122:125]
	v_mfma_f32_16x16x32_bf16 v[58:61], v[190:193], v[182:185], v[58:61]
	v_mfma_f32_16x16x32_bf16 v[114:117], v[198:201], v[160:163], v[114:117]
	v_mfma_f32_16x16x32_bf16 v[50:53], v[198:201], v[182:185], v[50:53]
	v_mfma_f32_16x16x32_bf16 v[106:109], v[206:209], v[160:163], v[106:109]
	v_mfma_f32_16x16x32_bf16 v[42:45], v[206:209], v[182:185], v[42:45]
	v_mfma_f32_16x16x32_bf16 v[98:101], v[214:217], v[160:163], v[98:101]
	v_mfma_f32_16x16x32_bf16 v[34:37], v[214:217], v[182:185], v[34:37]
	v_mfma_f32_16x16x32_bf16 v[122:125], v[194:197], v[164:167], v[122:125]
	v_mfma_f32_16x16x32_bf16 v[58:61], v[194:197], v[186:189], v[58:61]
	v_mfma_f32_16x16x32_bf16 v[114:117], v[202:205], v[164:167], v[114:117]
	v_mfma_f32_16x16x32_bf16 v[50:53], v[202:205], v[186:189], v[50:53]
	v_mfma_f32_16x16x32_bf16 v[106:109], v[210:213], v[164:167], v[106:109]
	v_mfma_f32_16x16x32_bf16 v[42:45], v[210:213], v[186:189], v[42:45]
	v_mfma_f32_16x16x32_bf16 v[98:101], v[218:221], v[164:167], v[98:101]
	v_mfma_f32_16x16x32_bf16 v[34:37], v[218:221], v[186:189], v[34:37]
	s_barrier
	s_setprio 0
	s_mov_b32 m0, s93
	s_or_b32 s50, s49, 0x80
	ds_read_b128 v[190:193], v154 offset:49152
	ds_read_b128 v[194:197], v154 offset:50176
	ds_read_b128 v[198:201], v154 offset:51200
	ds_read_b128 v[202:205], v154 offset:52224
	ds_read_b128 v[206:209], v154 offset:53248
	ds_read_b128 v[210:213], v154 offset:54272
	ds_read_b128 v[214:217], v154 offset:55296
	ds_read_b128 v[218:221], v154 offset:56320
	buffer_load_dwordx4 v132, s[84:87], s50 offen lds
	s_mov_b32 m0, s94
	s_add_i32 s49, s49, 0x8080
	buffer_load_dwordx4 v136, s[84:87], s50 offen lds
	s_mov_b32 m0, s9
	s_nop 0
	buffer_load_dwordx4 v132, s[84:87], s49 offen lds
	s_mov_b32 m0, s54
	s_nop 0
	buffer_load_dwordx4 v136, s[84:87], s49 offen lds
	s_mov_b32 m0, s95
	s_nop 0
	buffer_load_dwordx4 v130, s[76:79], s48 offen lds
	s_mov_b32 m0, s97
	s_nop 0
	buffer_load_dwordx4 v134, s[76:79], s48 offen lds
	s_waitcnt vmcnt(8)
	s_waitcnt lgkmcnt(0)
	s_setprio 1
	s_barrier
	v_mfma_f32_16x16x32_bf16 v[94:97], v[190:193], v[138:141], v[94:97]
	v_mfma_f32_16x16x32_bf16 v[30:33], v[190:193], v[146:149], v[30:33]
	v_mfma_f32_16x16x32_bf16 v[86:89], v[198:201], v[138:141], v[86:89]
	v_mfma_f32_16x16x32_bf16 v[22:25], v[198:201], v[146:149], v[22:25]
	v_mfma_f32_16x16x32_bf16 v[78:81], v[206:209], v[138:141], v[78:81]
	v_mfma_f32_16x16x32_bf16 v[14:17], v[206:209], v[146:149], v[14:17]
	v_mfma_f32_16x16x32_bf16 v[70:73], v[214:217], v[138:141], v[70:73]
	v_mfma_f32_16x16x32_bf16 v[6:9], v[214:217], v[146:149], v[6:9]
	v_mfma_f32_16x16x32_bf16 v[94:97], v[194:197], v[142:145], v[94:97]
	v_mfma_f32_16x16x32_bf16 v[30:33], v[194:197], v[156:159], v[30:33]
	v_mfma_f32_16x16x32_bf16 v[86:89], v[202:205], v[142:145], v[86:89]
	v_mfma_f32_16x16x32_bf16 v[22:25], v[202:205], v[156:159], v[22:25]
	v_mfma_f32_16x16x32_bf16 v[78:81], v[210:213], v[142:145], v[78:81]
	v_mfma_f32_16x16x32_bf16 v[14:17], v[210:213], v[156:159], v[14:17]
	v_mfma_f32_16x16x32_bf16 v[70:73], v[218:221], v[142:145], v[70:73]
	v_mfma_f32_16x16x32_bf16 v[6:9], v[218:221], v[156:159], v[6:9]
	v_mfma_f32_16x16x32_bf16 v[90:93], v[190:193], v[160:163], v[90:93]
	v_mfma_f32_16x16x32_bf16 v[26:29], v[190:193], v[182:185], v[26:29]
	v_mfma_f32_16x16x32_bf16 v[82:85], v[198:201], v[160:163], v[82:85]
	v_mfma_f32_16x16x32_bf16 v[18:21], v[198:201], v[182:185], v[18:21]
	v_mfma_f32_16x16x32_bf16 v[74:77], v[206:209], v[160:163], v[74:77]
	v_mfma_f32_16x16x32_bf16 v[10:13], v[206:209], v[182:185], v[10:13]
	v_mfma_f32_16x16x32_bf16 v[66:69], v[214:217], v[160:163], v[66:69]
	v_mfma_f32_16x16x32_bf16 v[2:5], v[214:217], v[182:185], v[2:5]
	v_mfma_f32_16x16x32_bf16 v[90:93], v[194:197], v[164:167], v[90:93]
	v_mfma_f32_16x16x32_bf16 v[26:29], v[194:197], v[186:189], v[26:29]
	v_mfma_f32_16x16x32_bf16 v[82:85], v[202:205], v[164:167], v[82:85]
	v_mfma_f32_16x16x32_bf16 v[18:21], v[202:205], v[186:189], v[18:21]
	v_mfma_f32_16x16x32_bf16 v[74:77], v[210:213], v[164:167], v[74:77]
	v_mfma_f32_16x16x32_bf16 v[10:13], v[210:213], v[186:189], v[10:13]
	v_mfma_f32_16x16x32_bf16 v[66:69], v[218:221], v[164:167], v[66:69]
	v_mfma_f32_16x16x32_bf16 v[2:5], v[218:221], v[186:189], v[2:5]
	s_barrier
	s_setprio 0
	s_add_i32 s47, s47, 2
	s_addk_i32 s31, 0x100
	s_addk_i32 s46, 0x100
	s_cmp_ge_i32 s47, s34
	s_cbranch_scc0 .LBB0_788
	s_mov_b32 s61, s96
	s_and_b64 vcc, exec, s[62:63]
	s_cbranch_vccz .LBB0_791

; #define PG8_STAGEX(rs, bufoff, soff, voff) do { _Pragma("unroll") for (int _i = 0; _i < 2; ++_i) \
;         __builtin_amdgcn_raw_ptr_buffer_load_lds(rs, (LAS unsigned*)(lds + (bufoff) + ldsw + _i * 8192), 16, (voff)[_i], (soff), 0, 0); } while (0)
; #define PG8_LDA(dst, b, h) do { _Pragma("unroll") for (int m = 0; m < 4; ++m) _Pragma("unroll") for (int k = 0; k < 2; ++k) dst[m][k] = *(const LAS bf16x8*)(lds + PG8_SA(b, h) + aoff + m * 2048 + k * 1024); } while (0)
; #define PG8_LDB(dst, b, h) do { _Pragma("unroll") for (int n = 0; n < 2; ++n) _Pragma("unroll") for (int k = 0; k < 2; ++k) dst[n][k] = *(const LAS bf16x8*)(lds + PG8_SB(b, h) + boff + n * 2048 + k * 1024); } while (0)
; #define PG8_WAIT_V(n) asm volatile("s_waitcnt vmcnt(" #n ")" ::: "memory")
; #define PG8_WAIT_L(n) asm volatile("s_waitcnt lgkmcnt(" #n ")" ::: "memory")
; #define PG8_BAR __builtin_amdgcn_s_barrier()
; #define PG8_SCHED __builtin_amdgcn_sched_barrier(0)
;     ...
;             const bool last = (t == nt - 2);
;             const unsigned a1 = cA + (unsigned)(t + 1) * kstep;
;             const unsigned a2 = last ? nA : cA + (unsigned)(t + 2) * kstep, b2 = last ? nB : cB + (unsigned)(t + 2) * kstep;
;             const unsigned a3 = a2 + kstep, b3 = b2 + kstep;
;             PG8_LDB(B0, 0, 0); PG8_LDB(B1, 0, 1); PG8_SCHED; PG8_LDA(At, 0, 0); PG8_STAGEX(rsA, PG8_SA(1, 1), a1 + hstepA, voffA);
;             PG8_WAIT_V(8); PG8_WAIT_L(0); PG8_BAR; PG8_MMA(0, 0, At, B0); PG8_MMA(0, 1, At, B1); PG8_BAR; PG8_SCHED;
;             PG8_LDA(At, 0, 1); PG8_STAGEX(rsB, PG8_SB(0, 0), b2, voffB); PG8_STAGEX(rsB, PG8_SB(0, 1), b2 + hstepB, voffB); PG8_STAGEX(rsA, PG8_SA(0, 0), a2, voffA);
;             PG8_WAIT_V(8); PG8_WAIT_L(0); PG8_BAR; PG8_MMA(1, 0, At, B0); PG8_MMA(1, 1, At, B1); PG8_BAR; PG8_SCHED;
.LBB0_1274:
	v_add_u32_e32 v142, 0x10000, v157
	v_add_u32_e32 v159, 0x14000, v157
	ds_read_b128 v[130:133], v142
	ds_read_b128 v[134:137], v142 offset:1024
	ds_read_b128 v[138:141], v142 offset:2048
	ds_read_b128 v[142:145], v142 offset:3072
	ds_read_b128 v[146:149], v159
	ds_read_b128 v[164:167], v159 offset:1024
	ds_read_b128 v[168:171], v159 offset:2048
	ds_read_b128 v[182:185], v159 offset:3072
	s_add_i32 s42, s62, 0xfff80080
	s_cmp_eq_u32 s67, 28
	s_cselect_b32 s70, s30, s42
	s_cselect_b32 s69, s31, s63
	s_or_b32 s68, s70, 0x80
	s_mov_b32 m0, s29
	ds_read_b128 v[186:189], v158
	ds_read_b128 v[190:193], v158 offset:1024
	ds_read_b128 v[194:197], v158 offset:2048
	ds_read_b128 v[198:201], v158 offset:3072
	ds_read_b128 v[202:205], v158 offset:4096
	ds_read_b128 v[206:209], v158 offset:5120
	ds_read_b128 v[210:213], v158 offset:6144
	ds_read_b128 v[214:217], v158 offset:7168
	buffer_load_dwordx4 v150, s[76:79], s62 offen lds
	s_mov_b32 m0, s35
	s_nop 0
	buffer_load_dwordx4 v152, s[76:79], s62 offen lds
	s_waitcnt vmcnt(8)
	s_waitcnt lgkmcnt(0)
	s_setprio 1
	s_barrier
	v_mfma_f32_16x16x32_bf16 v[126:129], v[130:133], v[186:189], v[126:129]
	v_mfma_f32_16x16x32_bf16 v[122:125], v[138:141], v[186:189], v[122:125]
	v_mfma_f32_16x16x32_bf16 v[118:121], v[130:133], v[194:197], v[118:121]
	v_mfma_f32_16x16x32_bf16 v[114:117], v[138:141], v[194:197], v[114:117]
	v_mfma_f32_16x16x32_bf16 v[110:113], v[130:133], v[202:205], v[110:113]
	v_mfma_f32_16x16x32_bf16 v[106:109], v[138:141], v[202:205], v[106:109]
	v_mfma_f32_16x16x32_bf16 v[102:105], v[130:133], v[210:213], v[102:105]
	v_mfma_f32_16x16x32_bf16 v[98:101], v[138:141], v[210:213], v[98:101]
	v_mfma_f32_16x16x32_bf16 v[126:129], v[134:137], v[190:193], v[126:129]
	v_mfma_f32_16x16x32_bf16 v[122:125], v[142:145], v[190:193], v[122:125]
	v_mfma_f32_16x16x32_bf16 v[118:121], v[134:137], v[198:201], v[118:121]
	v_mfma_f32_16x16x32_bf16 v[114:117], v[142:145], v[198:201], v[114:117]
	v_mfma_f32_16x16x32_bf16 v[110:113], v[134:137], v[206:209], v[110:113]
	v_mfma_f32_16x16x32_bf16 v[106:109], v[142:145], v[206:209], v[106:109]
	v_mfma_f32_16x16x32_bf16 v[102:105], v[134:137], v[214:217], v[102:105]
	v_mfma_f32_16x16x32_bf16 v[98:101], v[142:145], v[214:217], v[98:101]
	v_mfma_f32_16x16x32_bf16 v[62:65], v[146:149], v[186:189], v[62:65]
	v_mfma_f32_16x16x32_bf16 v[58:61], v[168:171], v[186:189], v[58:61]
	v_mfma_f32_16x16x32_bf16 v[54:57], v[146:149], v[194:197], v[54:57]
	v_mfma_f32_16x16x32_bf16 v[50:53], v[168:171], v[194:197], v[50:53]
	v_mfma_f32_16x16x32_bf16 v[46:49], v[146:149], v[202:205], v[46:49]
	v_mfma_f32_16x16x32_bf16 v[42:45], v[168:171], v[202:205], v[42:45]
	v_mfma_f32_16x16x32_bf16 v[38:41], v[146:149], v[210:213], v[38:41]
	v_mfma_f32_16x16x32_bf16 v[34:37], v[168:171], v[210:213], v[34:37]
	v_mfma_f32_16x16x32_bf16 v[62:65], v[164:167], v[190:193], v[62:65]
	v_mfma_f32_16x16x32_bf16 v[58:61], v[182:185], v[190:193], v[58:61]
	v_mfma_f32_16x16x32_bf16 v[54:57], v[164:167], v[198:201], v[54:57]
	v_mfma_f32_16x16x32_bf16 v[50:53], v[182:185], v[198:201], v[50:53]
	v_mfma_f32_16x16x32_bf16 v[46:49], v[164:167], v[206:209], v[46:49]
	v_mfma_f32_16x16x32_bf16 v[42:45], v[182:185], v[206:209], v[42:45]
	v_mfma_f32_16x16x32_bf16 v[38:41], v[164:167], v[214:217], v[38:41]
	v_mfma_f32_16x16x32_bf16 v[34:37], v[182:185], v[214:217], v[34:37]
	s_barrier
	s_setprio 0
	s_mov_b32 m0, s16
	s_mov_b32 s42, s78
	s_mov_b32 s43, s79
	ds_read_b128 v[186:189], v158 offset:16384
	ds_read_b128 v[190:193], v158 offset:17408
	ds_read_b128 v[194:197], v158 offset:18432
	ds_read_b128 v[198:201], v158 offset:19456
	ds_read_b128 v[202:205], v158 offset:20480
	ds_read_b128 v[206:209], v158 offset:21504
	ds_read_b128 v[210:213], v158 offset:22528
	ds_read_b128 v[214:217], v158 offset:23552
	buffer_load_dwordx4 v151, s[40:43], s69 offen lds
	s_mov_b32 m0, s17
	s_add_i32 s71, s69, 0x80000
	buffer_load_dwordx4 v153, s[40:43], s69 offen lds
	s_mov_b32 m0, s18
	s_nop 0
	buffer_load_dwordx4 v151, s[40:43], s71 offen lds
	s_mov_b32 m0, s19
	s_nop 0
	buffer_load_dwordx4 v153, s[40:43], s71 offen lds
	s_mov_b32 m0, s15
	s_nop 0
	buffer_load_dwordx4 v150, s[76:79], s70 offen lds
	s_mov_b32 m0, s20
	s_nop 0
	buffer_load_dwordx4 v152, s[76:79], s70 offen lds
	s_waitcnt vmcnt(8)
	s_waitcnt lgkmcnt(0)
	s_setprio 1
	s_barrier
	v_mfma_f32_16x16x32_bf16 v[94:97], v[130:133], v[186:189], v[94:97]
	v_mfma_f32_16x16x32_bf16 v[90:93], v[138:141], v[186:189], v[90:93]
	v_mfma_f32_16x16x32_bf16 v[86:89], v[130:133], v[194:197], v[86:89]
	v_mfma_f32_16x16x32_bf16 v[82:85], v[138:141], v[194:197], v[82:85]
	v_mfma_f32_16x16x32_bf16 v[78:81], v[130:133], v[202:205], v[78:81]
	v_mfma_f32_16x16x32_bf16 v[74:77], v[138:141], v[202:205], v[74:77]
	v_mfma_f32_16x16x32_bf16 v[70:73], v[130:133], v[210:213], v[70:73]
	v_mfma_f32_16x16x32_bf16 v[66:69], v[138:141], v[210:213], v[66:69]
	v_mfma_f32_16x16x32_bf16 v[94:97], v[134:137], v[190:193], v[94:97]
	v_mfma_f32_16x16x32_bf16 v[90:93], v[142:145], v[190:193], v[90:93]
	v_mfma_f32_16x16x32_bf16 v[86:89], v[134:137], v[198:201], v[86:89]
	v_mfma_f32_16x16x32_bf16 v[82:85], v[142:145], v[198:201], v[82:85]
	v_mfma_f32_16x16x32_bf16 v[78:81], v[134:137], v[206:209], v[78:81]
	v_mfma_f32_16x16x32_bf16 v[74:77], v[142:145], v[206:209], v[74:77]
	v_mfma_f32_16x16x32_bf16 v[70:73], v[134:137], v[214:217], v[70:73]
	v_mfma_f32_16x16x32_bf16 v[66:69], v[142:145], v[214:217], v[66:69]
	v_mfma_f32_16x16x32_bf16 v[30:33], v[146:149], v[186:189], v[30:33]
	v_mfma_f32_16x16x32_bf16 v[26:29], v[168:171], v[186:189], v[26:29]
	v_mfma_f32_16x16x32_bf16 v[22:25], v[146:149], v[194:197], v[22:25]
	v_mfma_f32_16x16x32_bf16 v[18:21], v[168:171], v[194:197], v[18:21]
	v_mfma_f32_16x16x32_bf16 v[14:17], v[146:149], v[202:205], v[14:17]
	v_mfma_f32_16x16x32_bf16 v[10:13], v[168:171], v[202:205], v[10:13]
	v_mfma_f32_16x16x32_bf16 v[6:9], v[146:149], v[210:213], v[6:9]
	v_mfma_f32_16x16x32_bf16 v[2:5], v[168:171], v[210:213], v[2:5]
	v_mfma_f32_16x16x32_bf16 v[30:33], v[164:167], v[190:193], v[30:33]
	v_mfma_f32_16x16x32_bf16 v[26:29], v[182:185], v[190:193], v[26:29]
	v_mfma_f32_16x16x32_bf16 v[22:25], v[164:167], v[198:201], v[22:25]
	v_mfma_f32_16x16x32_bf16 v[18:21], v[182:185], v[198:201], v[18:21]
	v_mfma_f32_16x16x32_bf16 v[14:17], v[164:167], v[206:209], v[14:17]
	v_mfma_f32_16x16x32_bf16 v[10:13], v[182:185], v[206:209], v[10:13]
	v_mfma_f32_16x16x32_bf16 v[6:9], v[164:167], v[214:217], v[6:9]
	v_mfma_f32_16x16x32_bf16 v[2:5], v[182:185], v[214:217], v[2:5]
	s_barrier
; #define PG8_STAGEX(rs, bufoff, soff, voff) do { _Pragma("unroll") for (int _i = 0; _i < 2; ++_i) \
;         __builtin_amdgcn_raw_ptr_buffer_load_lds(rs, (LAS unsigned*)(lds + (bufoff) + ldsw + _i * 8192), 16, (voff)[_i], (soff), 0, 0); } while (0)
; #define PG8_LDA(dst, b, h) do { _Pragma("unroll") for (int m = 0; m < 4; ++m) _Pragma("unroll") for (int k = 0; k < 2; ++k) dst[m][k] = *(const LAS bf16x8*)(lds + PG8_SA(b, h) + aoff + m * 2048 + k * 1024); } while (0)
; #define PG8_LDB(dst, b, h) do { _Pragma("unroll") for (int n = 0; n < 2; ++n) _Pragma("unroll") for (int k = 0; k < 2; ++k) dst[n][k] = *(const LAS bf16x8*)(lds + PG8_SB(b, h) + boff + n * 2048 + k * 1024); } while (0)
; #define PG8_WAIT_V(n) asm volatile("s_waitcnt vmcnt(" #n ")" ::: "memory")
; #define PG8_WAIT_L(n) asm volatile("s_waitcnt lgkmcnt(" #n ")" ::: "memory")
; #define PG8_BAR __builtin_amdgcn_s_barrier()
; #define PG8_SCHED __builtin_amdgcn_sched_barrier(0)
;     ...
;             PG8_WAIT_V(8); PG8_WAIT_L(0); PG8_BAR; PG8_MMA(1, 0, At, B0); PG8_MMA(1, 1, At, B1); PG8_BAR; PG8_SCHED;
;             PG8_LDB(B0, 1, 0); PG8_LDB(B1, 1, 1); PG8_SCHED; PG8_LDA(At, 1, 0); PG8_STAGEX(rsA, PG8_SA(0, 1), a2 + hstepA, voffA);
;             PG8_WAIT_V(8); PG8_WAIT_L(0); PG8_BAR; PG8_MMA(0, 0, At, B0); PG8_MMA(0, 1, At, B1); PG8_BAR; PG8_SCHED;
;             PG8_LDA(At, 1, 1); PG8_STAGEX(rsB, PG8_SB(1, 0), b3, voffB); PG8_STAGEX(rsB, PG8_SB(1, 1), b3 + hstepB, voffB); PG8_STAGEX(rsA, PG8_SA(1, 0), a3, voffA);
;             PG8_WAIT_V(8); PG8_WAIT_L(0); PG8_BAR; PG8_MMA(1, 0, At, B0); PG8_MMA(1, 1, At, B1); PG8_BAR; PG8_SCHED;
;         }
;     ...
;         if (wr == 0) PG8_BAR;
	s_setprio 0
	v_add_u32_e32 v142, 0x18000, v157
	v_add_u32_e32 v159, 0x1c000, v157
	ds_read_b128 v[130:133], v142
	ds_read_b128 v[134:137], v142 offset:1024
	ds_read_b128 v[138:141], v142 offset:2048
	ds_read_b128 v[142:145], v142 offset:3072
	ds_read_b128 v[146:149], v159
	ds_read_b128 v[164:167], v159 offset:1024
	ds_read_b128 v[168:171], v159 offset:2048
	ds_read_b128 v[182:185], v159 offset:3072
	s_add_i32 s70, s70, 0x80000
	s_mov_b32 m0, s21
	ds_read_b128 v[186:189], v158 offset:32768
	ds_read_b128 v[190:193], v158 offset:33792
	ds_read_b128 v[194:197], v158 offset:34816
	ds_read_b128 v[198:201], v158 offset:35840
	ds_read_b128 v[202:205], v158 offset:36864
	ds_read_b128 v[206:209], v158 offset:37888
	ds_read_b128 v[210:213], v158 offset:38912
	ds_read_b128 v[214:217], v158 offset:39936
	buffer_load_dwordx4 v150, s[76:79], s70 offen lds
	s_mov_b32 m0, s22
	s_nop 0
	buffer_load_dwordx4 v152, s[76:79], s70 offen lds
	s_waitcnt vmcnt(8)
	s_waitcnt lgkmcnt(0)
	s_setprio 1
	s_barrier
	v_mfma_f32_16x16x32_bf16 v[126:129], v[130:133], v[186:189], v[126:129]
	v_mfma_f32_16x16x32_bf16 v[122:125], v[138:141], v[186:189], v[122:125]
	v_mfma_f32_16x16x32_bf16 v[118:121], v[130:133], v[194:197], v[118:121]
	v_mfma_f32_16x16x32_bf16 v[114:117], v[138:141], v[194:197], v[114:117]
	v_mfma_f32_16x16x32_bf16 v[110:113], v[130:133], v[202:205], v[110:113]
	v_mfma_f32_16x16x32_bf16 v[106:109], v[138:141], v[202:205], v[106:109]
	v_mfma_f32_16x16x32_bf16 v[102:105], v[130:133], v[210:213], v[102:105]
	v_mfma_f32_16x16x32_bf16 v[98:101], v[138:141], v[210:213], v[98:101]
	v_mfma_f32_16x16x32_bf16 v[126:129], v[134:137], v[190:193], v[126:129]
	v_mfma_f32_16x16x32_bf16 v[122:125], v[142:145], v[190:193], v[122:125]
	v_mfma_f32_16x16x32_bf16 v[118:121], v[134:137], v[198:201], v[118:121]
	v_mfma_f32_16x16x32_bf16 v[114:117], v[142:145], v[198:201], v[114:117]
	v_mfma_f32_16x16x32_bf16 v[110:113], v[134:137], v[206:209], v[110:113]
	v_mfma_f32_16x16x32_bf16 v[106:109], v[142:145], v[206:209], v[106:109]
	v_mfma_f32_16x16x32_bf16 v[102:105], v[134:137], v[214:217], v[102:105]
	v_mfma_f32_16x16x32_bf16 v[98:101], v[142:145], v[214:217], v[98:101]
	v_mfma_f32_16x16x32_bf16 v[62:65], v[146:149], v[186:189], v[62:65]
	v_mfma_f32_16x16x32_bf16 v[58:61], v[168:171], v[186:189], v[58:61]
	v_mfma_f32_16x16x32_bf16 v[54:57], v[146:149], v[194:197], v[54:57]
	v_mfma_f32_16x16x32_bf16 v[50:53], v[168:171], v[194:197], v[50:53]
	v_mfma_f32_16x16x32_bf16 v[46:49], v[146:149], v[202:205], v[46:49]
	v_mfma_f32_16x16x32_bf16 v[42:45], v[168:171], v[202:205], v[42:45]
	v_mfma_f32_16x16x32_bf16 v[38:41], v[146:149], v[210:213], v[38:41]
	v_mfma_f32_16x16x32_bf16 v[34:37], v[168:171], v[210:213], v[34:37]
	v_mfma_f32_16x16x32_bf16 v[62:65], v[164:167], v[190:193], v[62:65]
	v_mfma_f32_16x16x32_bf16 v[58:61], v[182:185], v[190:193], v[58:61]
	v_mfma_f32_16x16x32_bf16 v[54:57], v[164:167], v[198:201], v[54:57]
	v_mfma_f32_16x16x32_bf16 v[50:53], v[182:185], v[198:201], v[50:53]
	v_mfma_f32_16x16x32_bf16 v[46:49], v[164:167], v[206:209], v[46:49]
	v_mfma_f32_16x16x32_bf16 v[42:45], v[182:185], v[206:209], v[42:45]
	v_mfma_f32_16x16x32_bf16 v[38:41], v[164:167], v[214:217], v[38:41]
	v_mfma_f32_16x16x32_bf16 v[34:37], v[182:185], v[214:217], v[34:37]
	s_barrier
	s_setprio 0
	s_mov_b32 m0, s23
	s_or_b32 s70, s69, 0x80
	ds_read_b128 v[186:189], v158 offset:49152
	ds_read_b128 v[190:193], v158 offset:50176
	ds_read_b128 v[194:197], v158 offset:51200
	ds_read_b128 v[198:201], v158 offset:52224
	ds_read_b128 v[202:205], v158 offset:53248
	ds_read_b128 v[206:209], v158 offset:54272
	ds_read_b128 v[210:213], v158 offset:55296
	ds_read_b128 v[214:217], v158 offset:56320
	buffer_load_dwordx4 v151, s[40:43], s70 offen lds
	s_mov_b32 m0, s24
	s_add_i32 s69, s69, 0x80080
	buffer_load_dwordx4 v153, s[40:43], s70 offen lds
	s_mov_b32 m0, s27
	s_nop 0
	buffer_load_dwordx4 v151, s[40:43], s69 offen lds
	s_mov_b32 m0, s28
	s_nop 0
	buffer_load_dwordx4 v153, s[40:43], s69 offen lds
	s_mov_b32 m0, s25
	s_nop 0
	buffer_load_dwordx4 v150, s[76:79], s68 offen lds
	s_mov_b32 m0, s26
	s_nop 0
	buffer_load_dwordx4 v152, s[76:79], s68 offen lds
	s_waitcnt vmcnt(8)
	s_waitcnt lgkmcnt(0)
	s_setprio 1
	s_barrier
	v_mfma_f32_16x16x32_bf16 v[94:97], v[130:133], v[186:189], v[94:97]
	v_mfma_f32_16x16x32_bf16 v[90:93], v[138:141], v[186:189], v[90:93]
	v_mfma_f32_16x16x32_bf16 v[86:89], v[130:133], v[194:197], v[86:89]
	v_mfma_f32_16x16x32_bf16 v[82:85], v[138:141], v[194:197], v[82:85]
	v_mfma_f32_16x16x32_bf16 v[78:81], v[130:133], v[202:205], v[78:81]
	v_mfma_f32_16x16x32_bf16 v[74:77], v[138:141], v[202:205], v[74:77]
	v_mfma_f32_16x16x32_bf16 v[70:73], v[130:133], v[210:213], v[70:73]
	v_mfma_f32_16x16x32_bf16 v[66:69], v[138:141], v[210:213], v[66:69]
	v_mfma_f32_16x16x32_bf16 v[94:97], v[134:137], v[190:193], v[94:97]
	v_mfma_f32_16x16x32_bf16 v[90:93], v[142:145], v[190:193], v[90:93]
	v_mfma_f32_16x16x32_bf16 v[86:89], v[134:137], v[198:201], v[86:89]
	v_mfma_f32_16x16x32_bf16 v[82:85], v[142:145], v[198:201], v[82:85]
	v_mfma_f32_16x16x32_bf16 v[78:81], v[134:137], v[206:209], v[78:81]
	v_mfma_f32_16x16x32_bf16 v[74:77], v[142:145], v[206:209], v[74:77]
	v_mfma_f32_16x16x32_bf16 v[70:73], v[134:137], v[214:217], v[70:73]
	v_mfma_f32_16x16x32_bf16 v[66:69], v[142:145], v[214:217], v[66:69]
	v_mfma_f32_16x16x32_bf16 v[30:33], v[146:149], v[186:189], v[30:33]
	v_mfma_f32_16x16x32_bf16 v[26:29], v[168:171], v[186:189], v[26:29]
	v_mfma_f32_16x16x32_bf16 v[22:25], v[146:149], v[194:197], v[22:25]
	v_mfma_f32_16x16x32_bf16 v[18:21], v[168:171], v[194:197], v[18:21]
	v_mfma_f32_16x16x32_bf16 v[14:17], v[146:149], v[202:205], v[14:17]
	v_mfma_f32_16x16x32_bf16 v[10:13], v[168:171], v[202:205], v[10:13]
	v_mfma_f32_16x16x32_bf16 v[6:9], v[146:149], v[210:213], v[6:9]
	v_mfma_f32_16x16x32_bf16 v[2:5], v[168:171], v[210:213], v[2:5]
	v_mfma_f32_16x16x32_bf16 v[30:33], v[164:167], v[190:193], v[30:33]
	v_mfma_f32_16x16x32_bf16 v[26:29], v[182:185], v[190:193], v[26:29]
	v_mfma_f32_16x16x32_bf16 v[22:25], v[164:167], v[198:201], v[22:25]
	v_mfma_f32_16x16x32_bf16 v[18:21], v[182:185], v[198:201], v[18:21]
	v_mfma_f32_16x16x32_bf16 v[14:17], v[164:167], v[206:209], v[14:17]
	v_mfma_f32_16x16x32_bf16 v[10:13], v[182:185], v[206:209], v[10:13]
	v_mfma_f32_16x16x32_bf16 v[6:9], v[164:167], v[214:217], v[6:9]
	v_mfma_f32_16x16x32_bf16 v[2:5], v[182:185], v[214:217], v[2:5]
	s_barrier
	s_setprio 0
	s_add_i32 s67, s67, 2
	s_addk_i32 s62, 0x100
	s_addk_i32 s63, 0x100
	s_cmp_gt_u32 s67, 29
	s_cbranch_scc0 .LBB0_1274
	s_and_b64 vcc, exec, s[50:51]
	s_cbranch_vccz .LBB0_1277
	s_barrier

; #define PG8_STAGEX(rs, bufoff, soff, voff) do { _Pragma("unroll") for (int _i = 0; _i < 2; ++_i) \
;         __builtin_amdgcn_raw_ptr_buffer_load_lds(rs, (LAS unsigned*)(lds + (bufoff) + ldsw + _i * 8192), 16, (voff)[_i], (soff), 0, 0); } while (0)
; #define PG8_LDA(dst, b, h) do { _Pragma("unroll") for (int m = 0; m < 4; ++m) _Pragma("unroll") for (int k = 0; k < 2; ++k) dst[m][k] = *(const LAS bf16x8*)(lds + PG8_SA(b, h) + aoff + m * 2048 + k * 1024); } while (0)
; #define PG8_LDB(dst, b, h) do { _Pragma("unroll") for (int n = 0; n < 2; ++n) _Pragma("unroll") for (int k = 0; k < 2; ++k) dst[n][k] = *(const LAS bf16x8*)(lds + PG8_SB(b, h) + boff + n * 2048 + k * 1024); } while (0)
; #define PG8_WAIT_V(n) asm volatile("s_waitcnt vmcnt(" #n ")" ::: "memory")
; #define PG8_WAIT_L(n) asm volatile("s_waitcnt lgkmcnt(" #n ")" ::: "memory")
; #define PG8_BAR __builtin_amdgcn_s_barrier()
; #define PG8_SCHED __builtin_amdgcn_sched_barrier(0)
;     ...
;             for (int t = 0; t < nt; t += 2) {
;                 const bool last = (t == nt - 2);
;                 const unsigned a1 = cA + (unsigned)(t + 1) * kstep;
;                 const unsigned a2 = last ? nA : cA + (unsigned)(t + 2) * kstep, b2 = last ? nB : cB + (unsigned)(t + 2) * kstep;
;                 const unsigned a3 = a2 + kstep, b3 = b2 + kstep;
;                 if (w0) { PG8_LDB(B0, 0, 0); PG8_LDB(B1, 0, 1); PG8_SCHED; PG8_LDA(At, 0, 0); }
;                 PG8_WAIT_L(0); PG8_BAR; if (w0) { PG8_MMA(0, 0, At, B0); PG8_MMA(0, 1, At, B1); } PG8_BAR; PG8_SCHED;
;                 PG8_STAGEX(rsB, PG8_SB(0, 0), b2, voffB); PG8_STAGEX(rsB, PG8_SB(0, 1), b2 + hstepB, voffB); PG8_STAGEX(rsA, PG8_SA(0, 0), a2, voffA);
;                 PG8_WAIT_V(6); PG8_BAR; PG8_BAR; PG8_SCHED;
.LBB0_1287:
	v_add_u32_e32 v86, 0x10000, v72
	v_add_u32_e32 v102, 0x14000, v72
	ds_read_b128 v[74:77], v86
	ds_read_b128 v[78:81], v86 offset:1024
	ds_read_b128 v[82:85], v86 offset:2048
	ds_read_b128 v[86:89], v86 offset:3072
	ds_read_b128 v[90:93], v102
	ds_read_b128 v[94:97], v102 offset:1024
	ds_read_b128 v[98:101], v102 offset:2048
	ds_read_b128 v[102:105], v102 offset:3072
	s_cmp_lg_u32 s29, 28
	s_cselect_b32 s30, s28, 0
	s_add_i32 s31, s30, s19
	s_or_b32 s35, s31, 0x80
	s_add_i32 s30, s30, s13
	ds_read_b128 v[106:109], v73
	ds_read_b128 v[110:113], v73 offset:1024
	ds_read_b128 v[114:117], v73 offset:2048
	ds_read_b128 v[118:121], v73 offset:3072
	ds_read_b128 v[122:125], v73 offset:4096
	ds_read_b128 v[126:129], v73 offset:5120
	ds_read_b128 v[130:133], v73 offset:6144
	ds_read_b128 v[134:137], v73 offset:7168
	s_waitcnt lgkmcnt(0)
	s_setprio 1
	s_barrier
	v_mfma_f32_16x16x32_bf16 v[62:65], v[74:77], v[106:109], v[62:65]
	v_mfma_f32_16x16x32_bf16 v[58:61], v[82:85], v[106:109], v[58:61]
	v_mfma_f32_16x16x32_bf16 v[54:57], v[74:77], v[114:117], v[54:57]
	v_mfma_f32_16x16x32_bf16 v[50:53], v[82:85], v[114:117], v[50:53]
	v_mfma_f32_16x16x32_bf16 v[46:49], v[74:77], v[122:125], v[46:49]
	v_mfma_f32_16x16x32_bf16 v[42:45], v[82:85], v[122:125], v[42:45]
	v_mfma_f32_16x16x32_bf16 v[38:41], v[74:77], v[130:133], v[38:41]
	v_mfma_f32_16x16x32_bf16 v[34:37], v[82:85], v[130:133], v[34:37]
	v_mfma_f32_16x16x32_bf16 v[62:65], v[78:81], v[110:113], v[62:65]
	v_mfma_f32_16x16x32_bf16 v[58:61], v[86:89], v[110:113], v[58:61]
	v_mfma_f32_16x16x32_bf16 v[54:57], v[78:81], v[118:121], v[54:57]
	v_mfma_f32_16x16x32_bf16 v[50:53], v[86:89], v[118:121], v[50:53]
	v_mfma_f32_16x16x32_bf16 v[46:49], v[78:81], v[126:129], v[46:49]
	v_mfma_f32_16x16x32_bf16 v[42:45], v[86:89], v[126:129], v[42:45]
	v_mfma_f32_16x16x32_bf16 v[38:41], v[78:81], v[134:137], v[38:41]
	v_mfma_f32_16x16x32_bf16 v[34:37], v[86:89], v[134:137], v[34:37]
	v_mfma_f32_16x16x32_bf16 v[30:33], v[90:93], v[106:109], v[30:33]
	v_mfma_f32_16x16x32_bf16 v[26:29], v[98:101], v[106:109], v[26:29]
	v_mfma_f32_16x16x32_bf16 v[22:25], v[90:93], v[114:117], v[22:25]
	v_mfma_f32_16x16x32_bf16 v[18:21], v[98:101], v[114:117], v[18:21]
	v_mfma_f32_16x16x32_bf16 v[14:17], v[90:93], v[122:125], v[14:17]
	v_mfma_f32_16x16x32_bf16 v[10:13], v[98:101], v[122:125], v[10:13]
	v_mfma_f32_16x16x32_bf16 v[6:9], v[90:93], v[130:133], v[6:9]
	v_mfma_f32_16x16x32_bf16 v[2:5], v[98:101], v[130:133], v[2:5]
	v_mfma_f32_16x16x32_bf16 v[30:33], v[94:97], v[110:113], v[30:33]
	v_mfma_f32_16x16x32_bf16 v[26:29], v[102:105], v[110:113], v[26:29]
	v_mfma_f32_16x16x32_bf16 v[22:25], v[94:97], v[118:121], v[22:25]
	v_mfma_f32_16x16x32_bf16 v[18:21], v[102:105], v[118:121], v[18:21]
	v_mfma_f32_16x16x32_bf16 v[14:17], v[94:97], v[126:129], v[14:17]
	v_mfma_f32_16x16x32_bf16 v[10:13], v[102:105], v[126:129], v[10:13]
	v_mfma_f32_16x16x32_bf16 v[6:9], v[94:97], v[134:137], v[6:9]
	v_mfma_f32_16x16x32_bf16 v[2:5], v[102:105], v[134:137], v[2:5]
	s_barrier
	s_setprio 0
	s_mov_b32 m0, s15
	s_mov_b32 s42, s78
	s_mov_b32 s43, s79
	buffer_load_dwordx4 v67, s[40:43], s30 offen lds
	s_mov_b32 m0, s16
	s_add_i32 s38, s30, 0x80000
	buffer_load_dwordx4 v69, s[40:43], s30 offen lds
	s_mov_b32 m0, s17
	s_nop 0
	buffer_load_dwordx4 v67, s[40:43], s38 offen lds
	s_mov_b32 m0, s18
	s_nop 0
	buffer_load_dwordx4 v69, s[40:43], s38 offen lds
	s_mov_b32 m0, s14
	s_nop 0
	buffer_load_dwordx4 v66, s[76:79], s31 offen lds
	s_mov_b32 m0, s20
	s_nop 0
	buffer_load_dwordx4 v68, s[76:79], s31 offen lds
	s_waitcnt vmcnt(6)
	s_barrier
	s_barrier
; #define PG8_STAGEX(rs, bufoff, soff, voff) do { _Pragma("unroll") for (int _i = 0; _i < 2; ++_i) \
;         __builtin_amdgcn_raw_ptr_buffer_load_lds(rs, (LAS unsigned*)(lds + (bufoff) + ldsw + _i * 8192), 16, (voff)[_i], (soff), 0, 0); } while (0)
; #define PG8_LDA(dst, b, h) do { _Pragma("unroll") for (int m = 0; m < 4; ++m) _Pragma("unroll") for (int k = 0; k < 2; ++k) dst[m][k] = *(const LAS bf16x8*)(lds + PG8_SA(b, h) + aoff + m * 2048 + k * 1024); } while (0)
; #define PG8_LDB(dst, b, h) do { _Pragma("unroll") for (int n = 0; n < 2; ++n) _Pragma("unroll") for (int k = 0; k < 2; ++k) dst[n][k] = *(const LAS bf16x8*)(lds + PG8_SB(b, h) + boff + n * 2048 + k * 1024); } while (0)
; #define PG8_WAIT_V(n) asm volatile("s_waitcnt vmcnt(" #n ")" ::: "memory")
; #define PG8_WAIT_L(n) asm volatile("s_waitcnt lgkmcnt(" #n ")" ::: "memory")
; #define PG8_BAR __builtin_amdgcn_s_barrier()
; #define PG8_SCHED __builtin_amdgcn_sched_barrier(0)
;     ...
;                 if (w0) { PG8_LDB(B0, 1, 0); PG8_LDB(B1, 1, 1); PG8_SCHED; PG8_LDA(At, 1, 0); }
;                 PG8_WAIT_L(0); PG8_BAR; if (w0) { PG8_MMA(0, 0, At, B0); PG8_MMA(0, 1, At, B1); } PG8_BAR; PG8_SCHED;
;                 PG8_STAGEX(rsB, PG8_SB(1, 0), b3, voffB); PG8_STAGEX(rsB, PG8_SB(1, 1), b3 + hstepB, voffB); PG8_STAGEX(rsA, PG8_SA(1, 0), a3, voffA);
;                 PG8_WAIT_V(6); PG8_BAR; PG8_BAR; PG8_SCHED;
;             }
;         }
;         if (wr == 0) PG8_BAR;
	v_add_u32_e32 v86, 0x18000, v72
	v_add_u32_e32 v102, 0x1c000, v72
	ds_read_b128 v[74:77], v86
	ds_read_b128 v[78:81], v86 offset:1024
	ds_read_b128 v[82:85], v86 offset:2048
	ds_read_b128 v[86:89], v86 offset:3072
	ds_read_b128 v[90:93], v102
	ds_read_b128 v[94:97], v102 offset:1024
	ds_read_b128 v[98:101], v102 offset:2048
	ds_read_b128 v[102:105], v102 offset:3072
	ds_read_b128 v[106:109], v73 offset:32768
	ds_read_b128 v[110:113], v73 offset:33792
	ds_read_b128 v[114:117], v73 offset:34816
	ds_read_b128 v[118:121], v73 offset:35840
	ds_read_b128 v[122:125], v73 offset:36864
	ds_read_b128 v[126:129], v73 offset:37888
	ds_read_b128 v[130:133], v73 offset:38912
	ds_read_b128 v[134:137], v73 offset:39936
	s_waitcnt lgkmcnt(0)
	s_setprio 1
	s_barrier
	v_mfma_f32_16x16x32_bf16 v[62:65], v[74:77], v[106:109], v[62:65]
	v_mfma_f32_16x16x32_bf16 v[58:61], v[82:85], v[106:109], v[58:61]
	v_mfma_f32_16x16x32_bf16 v[54:57], v[74:77], v[114:117], v[54:57]
	v_mfma_f32_16x16x32_bf16 v[50:53], v[82:85], v[114:117], v[50:53]
	v_mfma_f32_16x16x32_bf16 v[46:49], v[74:77], v[122:125], v[46:49]
	v_mfma_f32_16x16x32_bf16 v[42:45], v[82:85], v[122:125], v[42:45]
	v_mfma_f32_16x16x32_bf16 v[38:41], v[74:77], v[130:133], v[38:41]
	v_mfma_f32_16x16x32_bf16 v[34:37], v[82:85], v[130:133], v[34:37]
	v_mfma_f32_16x16x32_bf16 v[62:65], v[78:81], v[110:113], v[62:65]
	v_mfma_f32_16x16x32_bf16 v[58:61], v[86:89], v[110:113], v[58:61]
	v_mfma_f32_16x16x32_bf16 v[54:57], v[78:81], v[118:121], v[54:57]
	v_mfma_f32_16x16x32_bf16 v[50:53], v[86:89], v[118:121], v[50:53]
	v_mfma_f32_16x16x32_bf16 v[46:49], v[78:81], v[126:129], v[46:49]
	v_mfma_f32_16x16x32_bf16 v[42:45], v[86:89], v[126:129], v[42:45]
	v_mfma_f32_16x16x32_bf16 v[38:41], v[78:81], v[134:137], v[38:41]
	v_mfma_f32_16x16x32_bf16 v[34:37], v[86:89], v[134:137], v[34:37]
	v_mfma_f32_16x16x32_bf16 v[30:33], v[90:93], v[106:109], v[30:33]
	s_or_b32 s31, s30, 0x80
	v_mfma_f32_16x16x32_bf16 v[26:29], v[98:101], v[106:109], v[26:29]
	v_mfma_f32_16x16x32_bf16 v[22:25], v[90:93], v[114:117], v[22:25]
	v_mfma_f32_16x16x32_bf16 v[18:21], v[98:101], v[114:117], v[18:21]
	v_mfma_f32_16x16x32_bf16 v[14:17], v[90:93], v[122:125], v[14:17]
	v_mfma_f32_16x16x32_bf16 v[10:13], v[98:101], v[122:125], v[10:13]
	v_mfma_f32_16x16x32_bf16 v[6:9], v[90:93], v[130:133], v[6:9]
	v_mfma_f32_16x16x32_bf16 v[2:5], v[98:101], v[130:133], v[2:5]
	v_mfma_f32_16x16x32_bf16 v[30:33], v[94:97], v[110:113], v[30:33]
	v_mfma_f32_16x16x32_bf16 v[26:29], v[102:105], v[110:113], v[26:29]
	v_mfma_f32_16x16x32_bf16 v[22:25], v[94:97], v[118:121], v[22:25]
	v_mfma_f32_16x16x32_bf16 v[18:21], v[102:105], v[118:121], v[18:21]
	v_mfma_f32_16x16x32_bf16 v[14:17], v[94:97], v[126:129], v[14:17]
	v_mfma_f32_16x16x32_bf16 v[10:13], v[102:105], v[126:129], v[10:13]
	v_mfma_f32_16x16x32_bf16 v[6:9], v[94:97], v[134:137], v[6:9]
	v_mfma_f32_16x16x32_bf16 v[2:5], v[102:105], v[134:137], v[2:5]
	s_barrier
	s_setprio 0
	s_mov_b32 m0, s22
	s_add_i32 s30, s30, 0x80080
	buffer_load_dwordx4 v67, s[40:43], s31 offen lds
	s_mov_b32 m0, s23
	s_nop 0
	buffer_load_dwordx4 v69, s[40:43], s31 offen lds
	s_mov_b32 m0, s26
	s_nop 0
	buffer_load_dwordx4 v67, s[40:43], s30 offen lds
	s_mov_b32 m0, s27
	s_nop 0
	buffer_load_dwordx4 v69, s[40:43], s30 offen lds
	s_mov_b32 m0, s24
	s_nop 0
	buffer_load_dwordx4 v66, s[76:79], s35 offen lds
	s_mov_b32 m0, s25
	s_nop 0
	buffer_load_dwordx4 v68, s[76:79], s35 offen lds
	s_waitcnt vmcnt(6)
	s_barrier
	s_barrier
	s_addk_i32 s28, 0x100
	s_add_i32 s29, s29, 2
	s_cmp_gt_u32 s29, 29
	s_cbranch_scc0 .LBB0_1287
	s_cmpk_lt_u32 s12, 0x100
	s_cbranch_scc0 .LBB0_1290
	s_barrier

; #define PG8_STAGEX(rs, bufoff, soff, voff) do { _Pragma("unroll") for (int _i = 0; _i < 2; ++_i) \
;         __builtin_amdgcn_raw_ptr_buffer_load_lds(rs, (LAS unsigned*)(lds + (bufoff) + ldsw + _i * 8192), 16, (voff)[_i], (soff), 0, 0); } while (0)
; #define PG8_LDA(dst, b, h) do { _Pragma("unroll") for (int m = 0; m < 4; ++m) _Pragma("unroll") for (int k = 0; k < 2; ++k) dst[m][k] = *(const LAS bf16x8*)(lds + PG8_SA(b, h) + aoff + m * 2048 + k * 1024); } while (0)
; #define PG8_LDB(dst, b, h) do { _Pragma("unroll") for (int n = 0; n < 2; ++n) _Pragma("unroll") for (int k = 0; k < 2; ++k) dst[n][k] = *(const LAS bf16x8*)(lds + PG8_SB(b, h) + boff + n * 2048 + k * 1024); } while (0)
; #define PG8_WAIT_V(n) asm volatile("s_waitcnt vmcnt(" #n ")" ::: "memory")
; #define PG8_WAIT_L(n) asm volatile("s_waitcnt lgkmcnt(" #n ")" ::: "memory")
; #define PG8_BAR __builtin_amdgcn_s_barrier()
; #define PG8_SCHED __builtin_amdgcn_sched_barrier(0)
;     ...
;             const bool last = (t == nt - 2);
;             const unsigned a1 = cA + (unsigned)(t + 1) * kstep;
;             const unsigned a2 = last ? nA : cA + (unsigned)(t + 2) * kstep, b2 = last ? nB : cB + (unsigned)(t + 2) * kstep;
;             const unsigned a3 = a2 + kstep, b3 = b2 + kstep;
;             PG8_LDB(B0, 0, 0); PG8_LDB(B1, 0, 1); PG8_SCHED; PG8_LDA(At, 0, 0); PG8_STAGEX(rsA, PG8_SA(1, 1), a1 + hstepA, voffA);
;             PG8_WAIT_V(8); PG8_WAIT_L(0); PG8_BAR; PG8_MMA(0, 0, At, B0); PG8_MMA(0, 1, At, B1); PG8_BAR; PG8_SCHED;
;             PG8_LDA(At, 0, 1); PG8_STAGEX(rsB, PG8_SB(0, 0), b2, voffB); PG8_STAGEX(rsB, PG8_SB(0, 1), b2 + hstepB, voffB); PG8_STAGEX(rsA, PG8_SA(0, 0), a2, voffA);
;             PG8_WAIT_V(8); PG8_WAIT_L(0); PG8_BAR; PG8_MMA(1, 0, At, B0); PG8_MMA(1, 1, At, B1); PG8_BAR; PG8_SCHED;
.LBB0_1377:
	v_add_u32_e32 v142, 0x10000, v185
	v_add_u32_e32 v158, 0x14000, v185
	ds_read_b128 v[130:133], v142
	ds_read_b128 v[134:137], v142 offset:1024
	ds_read_b128 v[138:141], v142 offset:2048
	ds_read_b128 v[142:145], v142 offset:3072
	ds_read_b128 v[146:149], v158
	ds_read_b128 v[150:153], v158 offset:1024
	ds_read_b128 v[154:157], v158 offset:2048
	ds_read_b128 v[158:161], v158 offset:3072
	s_add_i32 s50, s43, 0xfff40080
	s_cmp_eq_u32 s60, 12
	s_cselect_b32 s63, s30, s50
	s_cselect_b32 s62, s31, s59
	s_add_i32 s61, s63, 0x80
	s_mov_b32 m0, s23
	ds_read_b128 v[162:165], v186
	ds_read_b128 v[166:169], v186 offset:1024
	ds_read_b128 v[190:193], v186 offset:2048
	ds_read_b128 v[194:197], v186 offset:3072
	ds_read_b128 v[198:201], v186 offset:4096
	ds_read_b128 v[202:205], v186 offset:5120
	ds_read_b128 v[206:209], v186 offset:6144
	ds_read_b128 v[210:213], v186 offset:7168
	buffer_load_dwordx4 v173, s[76:79], s43 offen lds
	s_mov_b32 m0, s24
	s_nop 0
	buffer_load_dwordx4 v178, s[76:79], s43 offen lds
	s_waitcnt vmcnt(8)
	s_waitcnt lgkmcnt(0)
	s_setprio 1
	s_barrier
	v_mfma_f32_16x16x32_bf16 v[126:129], v[130:133], v[162:165], v[126:129]
	v_mfma_f32_16x16x32_bf16 v[122:125], v[138:141], v[162:165], v[122:125]
	v_mfma_f32_16x16x32_bf16 v[118:121], v[130:133], v[190:193], v[118:121]
	v_mfma_f32_16x16x32_bf16 v[114:117], v[138:141], v[190:193], v[114:117]
	v_mfma_f32_16x16x32_bf16 v[110:113], v[130:133], v[198:201], v[110:113]
	v_mfma_f32_16x16x32_bf16 v[106:109], v[138:141], v[198:201], v[106:109]
	v_mfma_f32_16x16x32_bf16 v[102:105], v[130:133], v[206:209], v[102:105]
	v_mfma_f32_16x16x32_bf16 v[98:101], v[138:141], v[206:209], v[98:101]
	v_mfma_f32_16x16x32_bf16 v[126:129], v[134:137], v[166:169], v[126:129]
	v_mfma_f32_16x16x32_bf16 v[122:125], v[142:145], v[166:169], v[122:125]
	v_mfma_f32_16x16x32_bf16 v[118:121], v[134:137], v[194:197], v[118:121]
	v_mfma_f32_16x16x32_bf16 v[114:117], v[142:145], v[194:197], v[114:117]
	v_mfma_f32_16x16x32_bf16 v[110:113], v[134:137], v[202:205], v[110:113]
	v_mfma_f32_16x16x32_bf16 v[106:109], v[142:145], v[202:205], v[106:109]
	v_mfma_f32_16x16x32_bf16 v[102:105], v[134:137], v[210:213], v[102:105]
	v_mfma_f32_16x16x32_bf16 v[98:101], v[142:145], v[210:213], v[98:101]
	v_mfma_f32_16x16x32_bf16 v[94:97], v[146:149], v[162:165], v[94:97]
	v_mfma_f32_16x16x32_bf16 v[90:93], v[154:157], v[162:165], v[90:93]
	v_mfma_f32_16x16x32_bf16 v[86:89], v[146:149], v[190:193], v[86:89]
	v_mfma_f32_16x16x32_bf16 v[82:85], v[154:157], v[190:193], v[82:85]
	v_mfma_f32_16x16x32_bf16 v[78:81], v[146:149], v[198:201], v[78:81]
	v_mfma_f32_16x16x32_bf16 v[74:77], v[154:157], v[198:201], v[74:77]
	v_mfma_f32_16x16x32_bf16 v[70:73], v[146:149], v[206:209], v[70:73]
	v_mfma_f32_16x16x32_bf16 v[66:69], v[154:157], v[206:209], v[66:69]
	v_mfma_f32_16x16x32_bf16 v[94:97], v[150:153], v[166:169], v[94:97]
	v_mfma_f32_16x16x32_bf16 v[90:93], v[158:161], v[166:169], v[90:93]
	v_mfma_f32_16x16x32_bf16 v[86:89], v[150:153], v[194:197], v[86:89]
	v_mfma_f32_16x16x32_bf16 v[82:85], v[158:161], v[194:197], v[82:85]
	v_mfma_f32_16x16x32_bf16 v[78:81], v[150:153], v[202:205], v[78:81]
	v_mfma_f32_16x16x32_bf16 v[74:77], v[158:161], v[202:205], v[74:77]
	v_mfma_f32_16x16x32_bf16 v[70:73], v[150:153], v[210:213], v[70:73]
	v_mfma_f32_16x16x32_bf16 v[66:69], v[158:161], v[210:213], v[66:69]
	s_barrier
	s_setprio 0
	s_mov_b32 m0, s7
	s_mov_b32 s50, s78
	s_mov_b32 s51, s79
	ds_read_b128 v[162:165], v186 offset:16384
	ds_read_b128 v[166:169], v186 offset:17408
	ds_read_b128 v[190:193], v186 offset:18432
	ds_read_b128 v[194:197], v186 offset:19456
	ds_read_b128 v[198:201], v186 offset:20480
	ds_read_b128 v[202:205], v186 offset:21504
	ds_read_b128 v[206:209], v186 offset:22528
	ds_read_b128 v[210:213], v186 offset:23552
	buffer_load_dwordx4 v177, s[48:51], s62 offen lds
	s_mov_b32 m0, s11
	s_add_i32 s64, s62, 0x40000
	buffer_load_dwordx4 v179, s[48:51], s62 offen lds
	s_mov_b32 m0, s12
	s_nop 0
	buffer_load_dwordx4 v177, s[48:51], s64 offen lds
	s_mov_b32 m0, s13
	s_nop 0
	buffer_load_dwordx4 v179, s[48:51], s64 offen lds
	s_mov_b32 m0, s5
	s_nop 0
	buffer_load_dwordx4 v173, s[76:79], s63 offen lds
	s_mov_b32 m0, s14
	s_nop 0
	buffer_load_dwordx4 v178, s[76:79], s63 offen lds
	s_waitcnt vmcnt(8)
	s_waitcnt lgkmcnt(0)
	s_setprio 1
	s_barrier
	v_mfma_f32_16x16x32_bf16 v[62:65], v[130:133], v[162:165], v[62:65]
	v_mfma_f32_16x16x32_bf16 v[58:61], v[138:141], v[162:165], v[58:61]
	v_mfma_f32_16x16x32_bf16 v[54:57], v[130:133], v[190:193], v[54:57]
	v_mfma_f32_16x16x32_bf16 v[50:53], v[138:141], v[190:193], v[50:53]
	v_mfma_f32_16x16x32_bf16 v[46:49], v[130:133], v[198:201], v[46:49]
	v_mfma_f32_16x16x32_bf16 v[42:45], v[138:141], v[198:201], v[42:45]
	v_mfma_f32_16x16x32_bf16 v[38:41], v[130:133], v[206:209], v[38:41]
	v_mfma_f32_16x16x32_bf16 v[34:37], v[138:141], v[206:209], v[34:37]
	v_mfma_f32_16x16x32_bf16 v[62:65], v[134:137], v[166:169], v[62:65]
	v_mfma_f32_16x16x32_bf16 v[58:61], v[142:145], v[166:169], v[58:61]
	v_mfma_f32_16x16x32_bf16 v[54:57], v[134:137], v[194:197], v[54:57]
	v_mfma_f32_16x16x32_bf16 v[50:53], v[142:145], v[194:197], v[50:53]
	v_mfma_f32_16x16x32_bf16 v[46:49], v[134:137], v[202:205], v[46:49]
	v_mfma_f32_16x16x32_bf16 v[42:45], v[142:145], v[202:205], v[42:45]
	v_mfma_f32_16x16x32_bf16 v[38:41], v[134:137], v[210:213], v[38:41]
	v_mfma_f32_16x16x32_bf16 v[34:37], v[142:145], v[210:213], v[34:37]
	v_mfma_f32_16x16x32_bf16 v[30:33], v[146:149], v[162:165], v[30:33]
	v_mfma_f32_16x16x32_bf16 v[26:29], v[154:157], v[162:165], v[26:29]
	v_mfma_f32_16x16x32_bf16 v[22:25], v[146:149], v[190:193], v[22:25]
	v_mfma_f32_16x16x32_bf16 v[18:21], v[154:157], v[190:193], v[18:21]
	v_mfma_f32_16x16x32_bf16 v[14:17], v[146:149], v[198:201], v[14:17]
	v_mfma_f32_16x16x32_bf16 v[10:13], v[154:157], v[198:201], v[10:13]
	v_mfma_f32_16x16x32_bf16 v[6:9], v[146:149], v[206:209], v[6:9]
	v_mfma_f32_16x16x32_bf16 v[2:5], v[154:157], v[206:209], v[2:5]
	v_mfma_f32_16x16x32_bf16 v[30:33], v[150:153], v[166:169], v[30:33]
	v_mfma_f32_16x16x32_bf16 v[26:29], v[158:161], v[166:169], v[26:29]
	v_mfma_f32_16x16x32_bf16 v[22:25], v[150:153], v[194:197], v[22:25]
	v_mfma_f32_16x16x32_bf16 v[18:21], v[158:161], v[194:197], v[18:21]
	v_mfma_f32_16x16x32_bf16 v[14:17], v[150:153], v[202:205], v[14:17]
	v_mfma_f32_16x16x32_bf16 v[10:13], v[158:161], v[202:205], v[10:13]
	v_mfma_f32_16x16x32_bf16 v[6:9], v[150:153], v[210:213], v[6:9]
	v_mfma_f32_16x16x32_bf16 v[2:5], v[158:161], v[210:213], v[2:5]
	s_barrier
; #define PG8_STAGEX(rs, bufoff, soff, voff) do { _Pragma("unroll") for (int _i = 0; _i < 2; ++_i) \
;         __builtin_amdgcn_raw_ptr_buffer_load_lds(rs, (LAS unsigned*)(lds + (bufoff) + ldsw + _i * 8192), 16, (voff)[_i], (soff), 0, 0); } while (0)
; #define PG8_LDA(dst, b, h) do { _Pragma("unroll") for (int m = 0; m < 4; ++m) _Pragma("unroll") for (int k = 0; k < 2; ++k) dst[m][k] = *(const LAS bf16x8*)(lds + PG8_SA(b, h) + aoff + m * 2048 + k * 1024); } while (0)
; #define PG8_LDB(dst, b, h) do { _Pragma("unroll") for (int n = 0; n < 2; ++n) _Pragma("unroll") for (int k = 0; k < 2; ++k) dst[n][k] = *(const LAS bf16x8*)(lds + PG8_SB(b, h) + boff + n * 2048 + k * 1024); } while (0)
; #define PG8_WAIT_V(n) asm volatile("s_waitcnt vmcnt(" #n ")" ::: "memory")
; #define PG8_WAIT_L(n) asm volatile("s_waitcnt lgkmcnt(" #n ")" ::: "memory")
; #define PG8_BAR __builtin_amdgcn_s_barrier()
; #define PG8_SCHED __builtin_amdgcn_sched_barrier(0)
;     ...
;             PG8_WAIT_V(8); PG8_WAIT_L(0); PG8_BAR; PG8_MMA(1, 0, At, B0); PG8_MMA(1, 1, At, B1); PG8_BAR; PG8_SCHED;
;             PG8_LDB(B0, 1, 0); PG8_LDB(B1, 1, 1); PG8_SCHED; PG8_LDA(At, 1, 0); PG8_STAGEX(rsA, PG8_SA(0, 1), a2 + hstepA, voffA);
;             PG8_WAIT_V(8); PG8_WAIT_L(0); PG8_BAR; PG8_MMA(0, 0, At, B0); PG8_MMA(0, 1, At, B1); PG8_BAR; PG8_SCHED;
;             PG8_LDA(At, 1, 1); PG8_STAGEX(rsB, PG8_SB(1, 0), b3, voffB); PG8_STAGEX(rsB, PG8_SB(1, 1), b3 + hstepB, voffB); PG8_STAGEX(rsA, PG8_SA(1, 0), a3, voffA);
;             PG8_WAIT_V(8); PG8_WAIT_L(0); PG8_BAR; PG8_MMA(1, 0, At, B0); PG8_MMA(1, 1, At, B1); PG8_BAR; PG8_SCHED;
;         }
;     ...
;         if (wr == 0) PG8_BAR;
	s_setprio 0
	v_add_u32_e32 v142, 0x18000, v185
	v_add_u32_e32 v158, 0x1c000, v185
	ds_read_b128 v[130:133], v142
	ds_read_b128 v[134:137], v142 offset:1024
	ds_read_b128 v[138:141], v142 offset:2048
	ds_read_b128 v[142:145], v142 offset:3072
	ds_read_b128 v[146:149], v158
	ds_read_b128 v[150:153], v158 offset:1024
	ds_read_b128 v[154:157], v158 offset:2048
	ds_read_b128 v[158:161], v158 offset:3072
	s_add_i32 s63, s63, 0xc0000
	s_mov_b32 m0, s15
	ds_read_b128 v[162:165], v186 offset:32768
	ds_read_b128 v[166:169], v186 offset:33792
	ds_read_b128 v[190:193], v186 offset:34816
	ds_read_b128 v[194:197], v186 offset:35840
	ds_read_b128 v[198:201], v186 offset:36864
	ds_read_b128 v[202:205], v186 offset:37888
	ds_read_b128 v[206:209], v186 offset:38912
	ds_read_b128 v[210:213], v186 offset:39936
	buffer_load_dwordx4 v173, s[76:79], s63 offen lds
	s_mov_b32 m0, s16
	s_nop 0
	buffer_load_dwordx4 v178, s[76:79], s63 offen lds
	s_waitcnt vmcnt(8)
	s_waitcnt lgkmcnt(0)
	s_setprio 1
	s_barrier
	v_mfma_f32_16x16x32_bf16 v[126:129], v[130:133], v[162:165], v[126:129]
	v_mfma_f32_16x16x32_bf16 v[122:125], v[138:141], v[162:165], v[122:125]
	v_mfma_f32_16x16x32_bf16 v[118:121], v[130:133], v[190:193], v[118:121]
	v_mfma_f32_16x16x32_bf16 v[114:117], v[138:141], v[190:193], v[114:117]
	v_mfma_f32_16x16x32_bf16 v[110:113], v[130:133], v[198:201], v[110:113]
	v_mfma_f32_16x16x32_bf16 v[106:109], v[138:141], v[198:201], v[106:109]
	v_mfma_f32_16x16x32_bf16 v[102:105], v[130:133], v[206:209], v[102:105]
	v_mfma_f32_16x16x32_bf16 v[98:101], v[138:141], v[206:209], v[98:101]
	v_mfma_f32_16x16x32_bf16 v[126:129], v[134:137], v[166:169], v[126:129]
	v_mfma_f32_16x16x32_bf16 v[122:125], v[142:145], v[166:169], v[122:125]
	v_mfma_f32_16x16x32_bf16 v[118:121], v[134:137], v[194:197], v[118:121]
	v_mfma_f32_16x16x32_bf16 v[114:117], v[142:145], v[194:197], v[114:117]
	v_mfma_f32_16x16x32_bf16 v[110:113], v[134:137], v[202:205], v[110:113]
	v_mfma_f32_16x16x32_bf16 v[106:109], v[142:145], v[202:205], v[106:109]
	v_mfma_f32_16x16x32_bf16 v[102:105], v[134:137], v[210:213], v[102:105]
	v_mfma_f32_16x16x32_bf16 v[98:101], v[142:145], v[210:213], v[98:101]
	v_mfma_f32_16x16x32_bf16 v[94:97], v[146:149], v[162:165], v[94:97]
	v_mfma_f32_16x16x32_bf16 v[90:93], v[154:157], v[162:165], v[90:93]
	v_mfma_f32_16x16x32_bf16 v[86:89], v[146:149], v[190:193], v[86:89]
	v_mfma_f32_16x16x32_bf16 v[82:85], v[154:157], v[190:193], v[82:85]
	v_mfma_f32_16x16x32_bf16 v[78:81], v[146:149], v[198:201], v[78:81]
	v_mfma_f32_16x16x32_bf16 v[74:77], v[154:157], v[198:201], v[74:77]
	v_mfma_f32_16x16x32_bf16 v[70:73], v[146:149], v[206:209], v[70:73]
	v_mfma_f32_16x16x32_bf16 v[66:69], v[154:157], v[206:209], v[66:69]
	v_mfma_f32_16x16x32_bf16 v[94:97], v[150:153], v[166:169], v[94:97]
	v_mfma_f32_16x16x32_bf16 v[90:93], v[158:161], v[166:169], v[90:93]
	v_mfma_f32_16x16x32_bf16 v[86:89], v[150:153], v[194:197], v[86:89]
	v_mfma_f32_16x16x32_bf16 v[82:85], v[158:161], v[194:197], v[82:85]
	v_mfma_f32_16x16x32_bf16 v[78:81], v[150:153], v[202:205], v[78:81]
	v_mfma_f32_16x16x32_bf16 v[74:77], v[158:161], v[202:205], v[74:77]
	v_mfma_f32_16x16x32_bf16 v[70:73], v[150:153], v[210:213], v[70:73]
	v_mfma_f32_16x16x32_bf16 v[66:69], v[158:161], v[210:213], v[66:69]
	s_barrier
	s_setprio 0
	s_mov_b32 m0, s17
	s_add_i32 s63, s62, 0x80
	ds_read_b128 v[162:165], v186 offset:49152
	ds_read_b128 v[166:169], v186 offset:50176
	ds_read_b128 v[190:193], v186 offset:51200
	ds_read_b128 v[194:197], v186 offset:52224
	ds_read_b128 v[198:201], v186 offset:53248
	ds_read_b128 v[202:205], v186 offset:54272
	ds_read_b128 v[206:209], v186 offset:55296
	ds_read_b128 v[210:213], v186 offset:56320
	buffer_load_dwordx4 v177, s[48:51], s63 offen lds
	s_mov_b32 m0, s18
	s_add_i32 s62, s62, 0x40080
	buffer_load_dwordx4 v179, s[48:51], s63 offen lds
	s_mov_b32 m0, s21
	s_nop 0
	buffer_load_dwordx4 v177, s[48:51], s62 offen lds
	s_mov_b32 m0, s22
	s_nop 0
	buffer_load_dwordx4 v179, s[48:51], s62 offen lds
	s_mov_b32 m0, s19
	s_nop 0
	buffer_load_dwordx4 v173, s[76:79], s61 offen lds
	s_mov_b32 m0, s20
	s_nop 0
	buffer_load_dwordx4 v178, s[76:79], s61 offen lds
	s_waitcnt vmcnt(8)
	s_waitcnt lgkmcnt(0)
	s_setprio 1
	s_barrier
	v_mfma_f32_16x16x32_bf16 v[62:65], v[130:133], v[162:165], v[62:65]
	v_mfma_f32_16x16x32_bf16 v[58:61], v[138:141], v[162:165], v[58:61]
	v_mfma_f32_16x16x32_bf16 v[54:57], v[130:133], v[190:193], v[54:57]
	v_mfma_f32_16x16x32_bf16 v[50:53], v[138:141], v[190:193], v[50:53]
	v_mfma_f32_16x16x32_bf16 v[46:49], v[130:133], v[198:201], v[46:49]
	v_mfma_f32_16x16x32_bf16 v[42:45], v[138:141], v[198:201], v[42:45]
	v_mfma_f32_16x16x32_bf16 v[38:41], v[130:133], v[206:209], v[38:41]
	v_mfma_f32_16x16x32_bf16 v[34:37], v[138:141], v[206:209], v[34:37]
	v_mfma_f32_16x16x32_bf16 v[62:65], v[134:137], v[166:169], v[62:65]
	v_mfma_f32_16x16x32_bf16 v[58:61], v[142:145], v[166:169], v[58:61]
	v_mfma_f32_16x16x32_bf16 v[54:57], v[134:137], v[194:197], v[54:57]
	v_mfma_f32_16x16x32_bf16 v[50:53], v[142:145], v[194:197], v[50:53]
	v_mfma_f32_16x16x32_bf16 v[46:49], v[134:137], v[202:205], v[46:49]
	v_mfma_f32_16x16x32_bf16 v[42:45], v[142:145], v[202:205], v[42:45]
	v_mfma_f32_16x16x32_bf16 v[38:41], v[134:137], v[210:213], v[38:41]
	v_mfma_f32_16x16x32_bf16 v[34:37], v[142:145], v[210:213], v[34:37]
	v_mfma_f32_16x16x32_bf16 v[30:33], v[146:149], v[162:165], v[30:33]
	v_mfma_f32_16x16x32_bf16 v[26:29], v[154:157], v[162:165], v[26:29]
	v_mfma_f32_16x16x32_bf16 v[22:25], v[146:149], v[190:193], v[22:25]
	v_mfma_f32_16x16x32_bf16 v[18:21], v[154:157], v[190:193], v[18:21]
	v_mfma_f32_16x16x32_bf16 v[14:17], v[146:149], v[198:201], v[14:17]
	v_mfma_f32_16x16x32_bf16 v[10:13], v[154:157], v[198:201], v[10:13]
	v_mfma_f32_16x16x32_bf16 v[6:9], v[146:149], v[206:209], v[6:9]
	v_mfma_f32_16x16x32_bf16 v[2:5], v[154:157], v[206:209], v[2:5]
	v_mfma_f32_16x16x32_bf16 v[30:33], v[150:153], v[166:169], v[30:33]
	v_mfma_f32_16x16x32_bf16 v[26:29], v[158:161], v[166:169], v[26:29]
	v_mfma_f32_16x16x32_bf16 v[22:25], v[150:153], v[194:197], v[22:25]
	v_mfma_f32_16x16x32_bf16 v[18:21], v[158:161], v[194:197], v[18:21]
	v_mfma_f32_16x16x32_bf16 v[14:17], v[150:153], v[202:205], v[14:17]
	v_mfma_f32_16x16x32_bf16 v[10:13], v[158:161], v[202:205], v[10:13]
	v_mfma_f32_16x16x32_bf16 v[6:9], v[150:153], v[210:213], v[6:9]
	v_mfma_f32_16x16x32_bf16 v[2:5], v[158:161], v[210:213], v[2:5]
	s_barrier
	s_setprio 0
	s_add_i32 s60, s60, 2
	s_addk_i32 s43, 0x100
	s_addk_i32 s59, 0x100
	s_cmp_gt_u32 s60, 13
	s_cbranch_scc0 .LBB0_1377
	s_and_b64 vcc, exec, s[52:53]
	s_cbranch_vccz .LBB0_1380
	s_barrier

; #define PG8_STAGEX(rs, bufoff, soff, voff) do { _Pragma("unroll") for (int _i = 0; _i < 2; ++_i) \
;         __builtin_amdgcn_raw_ptr_buffer_load_lds(rs, (LAS unsigned*)(lds + (bufoff) + ldsw + _i * 8192), 16, (voff)[_i], (soff), 0, 0); } while (0)
; #define PG8_LDA(dst, b, h) do { _Pragma("unroll") for (int m = 0; m < 4; ++m) _Pragma("unroll") for (int k = 0; k < 2; ++k) dst[m][k] = *(const LAS bf16x8*)(lds + PG8_SA(b, h) + aoff + m * 2048 + k * 1024); } while (0)
; #define PG8_LDB(dst, b, h) do { _Pragma("unroll") for (int n = 0; n < 2; ++n) _Pragma("unroll") for (int k = 0; k < 2; ++k) dst[n][k] = *(const LAS bf16x8*)(lds + PG8_SB(b, h) + boff + n * 2048 + k * 1024); } while (0)
; #define PG8_WAIT_V(n) asm volatile("s_waitcnt vmcnt(" #n ")" ::: "memory")
; #define PG8_WAIT_L(n) asm volatile("s_waitcnt lgkmcnt(" #n ")" ::: "memory")
; #define PG8_BAR __builtin_amdgcn_s_barrier()
; #define PG8_SCHED __builtin_amdgcn_sched_barrier(0)
;     ...
;             for (int t = 0; t < nt; t += 2) {
;                 const bool last = (t == nt - 2);
;                 const unsigned a1 = cA + (unsigned)(t + 1) * kstep;
;                 const unsigned a2 = last ? nA : cA + (unsigned)(t + 2) * kstep, b2 = last ? nB : cB + (unsigned)(t + 2) * kstep;
;                 const unsigned a3 = a2 + kstep, b3 = b2 + kstep;
;                 if (w0) { PG8_LDB(B0, 0, 0); PG8_LDB(B1, 0, 1); PG8_SCHED; PG8_LDA(At, 0, 0); }
;                 PG8_WAIT_L(0); PG8_BAR; if (w0) { PG8_MMA(0, 0, At, B0); PG8_MMA(0, 1, At, B1); } PG8_BAR; PG8_SCHED;
;                 PG8_STAGEX(rsB, PG8_SB(0, 0), b2, voffB); PG8_STAGEX(rsB, PG8_SB(0, 1), b2 + hstepB, voffB); PG8_STAGEX(rsA, PG8_SA(0, 0), a2, voffA);
;                 PG8_WAIT_V(6); PG8_BAR; PG8_BAR; PG8_SCHED;
.LBB0_1429:
	v_add_u32_e32 v78, 0x10000, v95
	v_add_u32_e32 v86, 0x14000, v95
	ds_read_b128 v[66:69], v78
	ds_read_b128 v[70:73], v78 offset:1024
	ds_read_b128 v[74:77], v78 offset:2048
	ds_read_b128 v[78:81], v78 offset:3072
	ds_read_b128 v[82:85], v86
	ds_read_b128 v[100:103], v86 offset:1024
	ds_read_b128 v[104:107], v86 offset:2048
	ds_read_b128 v[108:111], v86 offset:3072
	s_cmp_eq_u32 s40, 12
	s_cselect_b32 s41, s38, s39
	s_cselect_b32 s46, s30, s31
	s_add_i32 s47, s41, 0x80
	ds_read_b128 v[112:115], v96
	ds_read_b128 v[116:119], v96 offset:1024
	ds_read_b128 v[120:123], v96 offset:2048
	ds_read_b128 v[124:127], v96 offset:3072
	ds_read_b128 v[128:131], v96 offset:4096
	ds_read_b128 v[132:135], v96 offset:5120
	ds_read_b128 v[136:139], v96 offset:6144
	ds_read_b128 v[140:143], v96 offset:7168
	s_waitcnt lgkmcnt(0)
	s_setprio 1
	s_barrier
	v_mfma_f32_16x16x32_bf16 v[62:65], v[66:69], v[112:115], v[62:65]
	v_mfma_f32_16x16x32_bf16 v[58:61], v[74:77], v[112:115], v[58:61]
	v_mfma_f32_16x16x32_bf16 v[54:57], v[66:69], v[120:123], v[54:57]
	v_mfma_f32_16x16x32_bf16 v[50:53], v[74:77], v[120:123], v[50:53]
	v_mfma_f32_16x16x32_bf16 v[46:49], v[66:69], v[128:131], v[46:49]
	v_mfma_f32_16x16x32_bf16 v[42:45], v[74:77], v[128:131], v[42:45]
	v_mfma_f32_16x16x32_bf16 v[38:41], v[66:69], v[136:139], v[38:41]
	v_mfma_f32_16x16x32_bf16 v[34:37], v[74:77], v[136:139], v[34:37]
	v_mfma_f32_16x16x32_bf16 v[62:65], v[70:73], v[116:119], v[62:65]
	v_mfma_f32_16x16x32_bf16 v[58:61], v[78:81], v[116:119], v[58:61]
	v_mfma_f32_16x16x32_bf16 v[54:57], v[70:73], v[124:127], v[54:57]
	v_mfma_f32_16x16x32_bf16 v[50:53], v[78:81], v[124:127], v[50:53]
	v_mfma_f32_16x16x32_bf16 v[46:49], v[70:73], v[132:135], v[46:49]
	v_mfma_f32_16x16x32_bf16 v[42:45], v[78:81], v[132:135], v[42:45]
	v_mfma_f32_16x16x32_bf16 v[38:41], v[70:73], v[140:143], v[38:41]
	v_mfma_f32_16x16x32_bf16 v[34:37], v[78:81], v[140:143], v[34:37]
	v_mfma_f32_16x16x32_bf16 v[30:33], v[82:85], v[112:115], v[30:33]
	v_mfma_f32_16x16x32_bf16 v[26:29], v[104:107], v[112:115], v[26:29]
	v_mfma_f32_16x16x32_bf16 v[22:25], v[82:85], v[120:123], v[22:25]
	v_mfma_f32_16x16x32_bf16 v[18:21], v[104:107], v[120:123], v[18:21]
	v_mfma_f32_16x16x32_bf16 v[14:17], v[82:85], v[128:131], v[14:17]
	v_mfma_f32_16x16x32_bf16 v[10:13], v[104:107], v[128:131], v[10:13]
	v_mfma_f32_16x16x32_bf16 v[6:9], v[82:85], v[136:139], v[6:9]
	v_mfma_f32_16x16x32_bf16 v[2:5], v[104:107], v[136:139], v[2:5]
	v_mfma_f32_16x16x32_bf16 v[30:33], v[100:103], v[116:119], v[30:33]
	v_mfma_f32_16x16x32_bf16 v[26:29], v[108:111], v[116:119], v[26:29]
	v_mfma_f32_16x16x32_bf16 v[22:25], v[100:103], v[124:127], v[22:25]
	v_mfma_f32_16x16x32_bf16 v[18:21], v[108:111], v[124:127], v[18:21]
	v_mfma_f32_16x16x32_bf16 v[14:17], v[100:103], v[132:135], v[14:17]
	v_mfma_f32_16x16x32_bf16 v[10:13], v[108:111], v[132:135], v[10:13]
	v_mfma_f32_16x16x32_bf16 v[6:9], v[100:103], v[140:143], v[6:9]
	v_mfma_f32_16x16x32_bf16 v[2:5], v[108:111], v[140:143], v[2:5]
	s_barrier
	s_setprio 0
	s_mov_b32 m0, s5
	s_mov_b32 s50, s78
	s_mov_b32 s51, s79
	buffer_load_dwordx4 v89, s[48:51], s46 offen lds
	s_mov_b32 m0, s7
	s_add_i32 s52, s46, 0x40000
	buffer_load_dwordx4 v91, s[48:51], s46 offen lds
	s_mov_b32 m0, s11
	s_nop 0
	buffer_load_dwordx4 v89, s[48:51], s52 offen lds
	s_mov_b32 m0, s12
	s_nop 0
	buffer_load_dwordx4 v91, s[48:51], s52 offen lds
	s_mov_b32 m0, s3
	s_nop 0
	buffer_load_dwordx4 v88, s[76:79], s41 offen lds
	s_mov_b32 m0, s13
	s_nop 0
	buffer_load_dwordx4 v90, s[76:79], s41 offen lds
	s_waitcnt vmcnt(6)
	s_barrier
	s_barrier
; #define PG8_STAGEX(rs, bufoff, soff, voff) do { _Pragma("unroll") for (int _i = 0; _i < 2; ++_i) \
;         __builtin_amdgcn_raw_ptr_buffer_load_lds(rs, (LAS unsigned*)(lds + (bufoff) + ldsw + _i * 8192), 16, (voff)[_i], (soff), 0, 0); } while (0)
; #define PG8_LDA(dst, b, h) do { _Pragma("unroll") for (int m = 0; m < 4; ++m) _Pragma("unroll") for (int k = 0; k < 2; ++k) dst[m][k] = *(const LAS bf16x8*)(lds + PG8_SA(b, h) + aoff + m * 2048 + k * 1024); } while (0)
; #define PG8_LDB(dst, b, h) do { _Pragma("unroll") for (int n = 0; n < 2; ++n) _Pragma("unroll") for (int k = 0; k < 2; ++k) dst[n][k] = *(const LAS bf16x8*)(lds + PG8_SB(b, h) + boff + n * 2048 + k * 1024); } while (0)
; #define PG8_WAIT_V(n) asm volatile("s_waitcnt vmcnt(" #n ")" ::: "memory")
; #define PG8_WAIT_L(n) asm volatile("s_waitcnt lgkmcnt(" #n ")" ::: "memory")
; #define PG8_BAR __builtin_amdgcn_s_barrier()
; #define PG8_SCHED __builtin_amdgcn_sched_barrier(0)
;     ...
;                 if (w0) { PG8_LDB(B0, 1, 0); PG8_LDB(B1, 1, 1); PG8_SCHED; PG8_LDA(At, 1, 0); }
;                 PG8_WAIT_L(0); PG8_BAR; if (w0) { PG8_MMA(0, 0, At, B0); PG8_MMA(0, 1, At, B1); } PG8_BAR; PG8_SCHED;
;                 PG8_STAGEX(rsB, PG8_SB(1, 0), b3, voffB); PG8_STAGEX(rsB, PG8_SB(1, 1), b3 + hstepB, voffB); PG8_STAGEX(rsA, PG8_SA(1, 0), a3, voffA);
;                 PG8_WAIT_V(6); PG8_BAR; PG8_BAR; PG8_SCHED;
;             }
;         }
;         if (wr == 0) PG8_BAR;
	v_add_u32_e32 v78, 0x18000, v95
	v_add_u32_e32 v86, 0x1c000, v95
	ds_read_b128 v[66:69], v78
	ds_read_b128 v[70:73], v78 offset:1024
	ds_read_b128 v[74:77], v78 offset:2048
	ds_read_b128 v[78:81], v78 offset:3072
	ds_read_b128 v[82:85], v86
	ds_read_b128 v[100:103], v86 offset:1024
	ds_read_b128 v[104:107], v86 offset:2048
	ds_read_b128 v[108:111], v86 offset:3072
	ds_read_b128 v[112:115], v96 offset:32768
	ds_read_b128 v[116:119], v96 offset:33792
	ds_read_b128 v[120:123], v96 offset:34816
	ds_read_b128 v[124:127], v96 offset:35840
	ds_read_b128 v[128:131], v96 offset:36864
	ds_read_b128 v[132:135], v96 offset:37888
	ds_read_b128 v[136:139], v96 offset:38912
	ds_read_b128 v[140:143], v96 offset:39936
	s_waitcnt lgkmcnt(0)
	s_setprio 1
	s_barrier
	v_mfma_f32_16x16x32_bf16 v[62:65], v[66:69], v[112:115], v[62:65]
	v_mfma_f32_16x16x32_bf16 v[58:61], v[74:77], v[112:115], v[58:61]
	v_mfma_f32_16x16x32_bf16 v[54:57], v[66:69], v[120:123], v[54:57]
	v_mfma_f32_16x16x32_bf16 v[50:53], v[74:77], v[120:123], v[50:53]
	v_mfma_f32_16x16x32_bf16 v[46:49], v[66:69], v[128:131], v[46:49]
	v_mfma_f32_16x16x32_bf16 v[42:45], v[74:77], v[128:131], v[42:45]
	v_mfma_f32_16x16x32_bf16 v[38:41], v[66:69], v[136:139], v[38:41]
	v_mfma_f32_16x16x32_bf16 v[34:37], v[74:77], v[136:139], v[34:37]
	v_mfma_f32_16x16x32_bf16 v[62:65], v[70:73], v[116:119], v[62:65]
	v_mfma_f32_16x16x32_bf16 v[58:61], v[78:81], v[116:119], v[58:61]
	v_mfma_f32_16x16x32_bf16 v[54:57], v[70:73], v[124:127], v[54:57]
	v_mfma_f32_16x16x32_bf16 v[50:53], v[78:81], v[124:127], v[50:53]
	v_mfma_f32_16x16x32_bf16 v[46:49], v[70:73], v[132:135], v[46:49]
	v_mfma_f32_16x16x32_bf16 v[42:45], v[78:81], v[132:135], v[42:45]
	v_mfma_f32_16x16x32_bf16 v[38:41], v[70:73], v[140:143], v[38:41]
	v_mfma_f32_16x16x32_bf16 v[34:37], v[78:81], v[140:143], v[34:37]
	v_mfma_f32_16x16x32_bf16 v[30:33], v[82:85], v[112:115], v[30:33]
	s_add_i32 s41, s46, 0x80
	v_mfma_f32_16x16x32_bf16 v[26:29], v[104:107], v[112:115], v[26:29]
	v_mfma_f32_16x16x32_bf16 v[22:25], v[82:85], v[120:123], v[22:25]
	v_mfma_f32_16x16x32_bf16 v[18:21], v[104:107], v[120:123], v[18:21]
	v_mfma_f32_16x16x32_bf16 v[14:17], v[82:85], v[128:131], v[14:17]
	v_mfma_f32_16x16x32_bf16 v[10:13], v[104:107], v[128:131], v[10:13]
	v_mfma_f32_16x16x32_bf16 v[6:9], v[82:85], v[136:139], v[6:9]
	v_mfma_f32_16x16x32_bf16 v[2:5], v[104:107], v[136:139], v[2:5]
	v_mfma_f32_16x16x32_bf16 v[30:33], v[100:103], v[116:119], v[30:33]
	v_mfma_f32_16x16x32_bf16 v[26:29], v[108:111], v[116:119], v[26:29]
	v_mfma_f32_16x16x32_bf16 v[22:25], v[100:103], v[124:127], v[22:25]
	v_mfma_f32_16x16x32_bf16 v[18:21], v[108:111], v[124:127], v[18:21]
	v_mfma_f32_16x16x32_bf16 v[14:17], v[100:103], v[132:135], v[14:17]
	v_mfma_f32_16x16x32_bf16 v[10:13], v[108:111], v[132:135], v[10:13]
	v_mfma_f32_16x16x32_bf16 v[6:9], v[100:103], v[140:143], v[6:9]
	v_mfma_f32_16x16x32_bf16 v[2:5], v[108:111], v[140:143], v[2:5]
	s_barrier
	s_setprio 0
	s_mov_b32 m0, s14
	s_add_i32 s46, s46, 0x40080
	buffer_load_dwordx4 v89, s[48:51], s41 offen lds
	s_mov_b32 m0, s15
	s_nop 0
	buffer_load_dwordx4 v91, s[48:51], s41 offen lds
	s_mov_b32 m0, s18
	s_nop 0
	buffer_load_dwordx4 v89, s[48:51], s46 offen lds
	s_mov_b32 m0, s19
	s_nop 0
	buffer_load_dwordx4 v91, s[48:51], s46 offen lds
	s_mov_b32 m0, s16
	s_nop 0
	buffer_load_dwordx4 v88, s[76:79], s47 offen lds
	s_mov_b32 m0, s17
	s_nop 0
	buffer_load_dwordx4 v90, s[76:79], s47 offen lds
	s_waitcnt vmcnt(6)
	s_barrier
	s_barrier
	s_add_i32 s40, s40, 2
	s_addk_i32 s31, 0x100
	s_addk_i32 s39, 0x100
	s_cmp_gt_u32 s40, 13
	s_cbranch_scc0 .LBB0_1429
	s_and_b64 vcc, exec, s[42:43]
	s_cbranch_vccz .LBB0_1432
	s_barrier

; #define PG8_STAGEX(rs, bufoff, soff, voff) do { _Pragma("unroll") for (int _i = 0; _i < 2; ++_i) \
;         __builtin_amdgcn_raw_ptr_buffer_load_lds(rs, (LAS unsigned*)(lds + (bufoff) + ldsw + _i * 8192), 16, (voff)[_i], (soff), 0, 0); } while (0)
; #define PG8_LDA(dst, b, h) do { _Pragma("unroll") for (int m = 0; m < 4; ++m) _Pragma("unroll") for (int k = 0; k < 2; ++k) dst[m][k] = *(const LAS bf16x8*)(lds + PG8_SA(b, h) + aoff + m * 2048 + k * 1024); } while (0)
; #define PG8_LDB(dst, b, h) do { _Pragma("unroll") for (int n = 0; n < 2; ++n) _Pragma("unroll") for (int k = 0; k < 2; ++k) dst[n][k] = *(const LAS bf16x8*)(lds + PG8_SB(b, h) + boff + n * 2048 + k * 1024); } while (0)
; #define PG8_WAIT_V(n) asm volatile("s_waitcnt vmcnt(" #n ")" ::: "memory")
; #define PG8_WAIT_L(n) asm volatile("s_waitcnt lgkmcnt(" #n ")" ::: "memory")
; #define PG8_BAR __builtin_amdgcn_s_barrier()
; #define PG8_SCHED __builtin_amdgcn_sched_barrier(0)
;     ...
;             const bool last = (t == nt - 2);
;             const unsigned a1 = cA + (unsigned)(t + 1) * kstep;
;             const unsigned a2 = last ? nA : cA + (unsigned)(t + 2) * kstep, b2 = last ? nB : cB + (unsigned)(t + 2) * kstep;
;             const unsigned a3 = a2 + kstep, b3 = b2 + kstep;
;             PG8_LDB(B0, 0, 0); PG8_LDB(B1, 0, 1); PG8_SCHED; PG8_LDA(At, 0, 0); PG8_STAGEX(rsA, PG8_SA(1, 1), a1 + hstepA, voffA);
;             PG8_WAIT_V(8); PG8_WAIT_L(0); PG8_BAR; PG8_MMA(0, 0, At, B0); PG8_MMA(0, 1, At, B1); PG8_BAR; PG8_SCHED;
;             PG8_LDA(At, 0, 1); PG8_STAGEX(rsB, PG8_SB(0, 0), b2, voffB); PG8_STAGEX(rsB, PG8_SB(0, 1), b2 + hstepB, voffB); PG8_STAGEX(rsA, PG8_SA(0, 0), a2, voffA);
;             PG8_WAIT_V(8); PG8_WAIT_L(0); PG8_BAR; PG8_MMA(1, 0, At, B0); PG8_MMA(1, 1, At, B1); PG8_BAR; PG8_SCHED;
.LBB0_1529:
	v_add_u32_e32 v118, 0x10000, v210
	v_add_u32_e32 v142, 0x14000, v210
	ds_read_b128 v[106:109], v118
	ds_read_b128 v[110:113], v118 offset:1024
	ds_read_b128 v[114:117], v118 offset:2048
	ds_read_b128 v[118:121], v118 offset:3072
	ds_read_b128 v[122:125], v142
	ds_read_b128 v[126:129], v142 offset:1024
	ds_read_b128 v[130:133], v142 offset:2048
	ds_read_b128 v[142:145], v142 offset:3072
	s_add_i32 s46, s59, 0xfff80080
	s_cmp_eq_u32 s64, 28
	s_cselect_b32 s67, s30, s46
	s_cselect_b32 s66, s31, s63
	s_or_b32 s65, s67, 0x80
	s_mov_b32 m0, s76
	ds_read_b128 v[164:167], v211
	ds_read_b128 v[168:171], v211 offset:1024
	ds_read_b128 v[182:185], v211 offset:2048
	ds_read_b128 v[186:189], v211 offset:3072
	ds_read_b128 v[190:193], v211 offset:4096
	ds_read_b128 v[194:197], v211 offset:5120
	ds_read_b128 v[198:201], v211 offset:6144
	ds_read_b128 v[202:205], v211 offset:7168
	buffer_load_dwordx4 v178, s[40:43], s59 offen lds
	s_mov_b32 m0, s77
	s_nop 0
	buffer_load_dwordx4 v206, s[40:43], s59 offen lds
	s_waitcnt vmcnt(8)
	s_waitcnt lgkmcnt(0)
	s_setprio 1
	s_barrier
	v_mfma_f32_16x16x32_bf16 v[158:161], v[106:109], v[164:167], v[158:161]
	v_mfma_f32_16x16x32_bf16 v[154:157], v[114:117], v[164:167], v[154:157]
	v_mfma_f32_16x16x32_bf16 v[150:153], v[106:109], v[182:185], v[150:153]
	v_mfma_f32_16x16x32_bf16 v[146:149], v[114:117], v[182:185], v[146:149]
	v_mfma_f32_16x16x32_bf16 v[138:141], v[106:109], v[190:193], v[138:141]
	v_mfma_f32_16x16x32_bf16 v[134:137], v[114:117], v[190:193], v[134:137]
	v_mfma_f32_16x16x32_bf16 v[102:105], v[106:109], v[198:201], v[102:105]
	v_mfma_f32_16x16x32_bf16 v[98:101], v[114:117], v[198:201], v[98:101]
	v_mfma_f32_16x16x32_bf16 v[158:161], v[110:113], v[168:171], v[158:161]
	v_mfma_f32_16x16x32_bf16 v[154:157], v[118:121], v[168:171], v[154:157]
	v_mfma_f32_16x16x32_bf16 v[150:153], v[110:113], v[186:189], v[150:153]
	v_mfma_f32_16x16x32_bf16 v[146:149], v[118:121], v[186:189], v[146:149]
	v_mfma_f32_16x16x32_bf16 v[138:141], v[110:113], v[194:197], v[138:141]
	v_mfma_f32_16x16x32_bf16 v[134:137], v[118:121], v[194:197], v[134:137]
	v_mfma_f32_16x16x32_bf16 v[102:105], v[110:113], v[202:205], v[102:105]
	v_mfma_f32_16x16x32_bf16 v[98:101], v[118:121], v[202:205], v[98:101]
	v_mfma_f32_16x16x32_bf16 v[62:65], v[122:125], v[164:167], v[62:65]
	v_mfma_f32_16x16x32_bf16 v[58:61], v[130:133], v[164:167], v[58:61]
	v_mfma_f32_16x16x32_bf16 v[54:57], v[122:125], v[182:185], v[54:57]
	v_mfma_f32_16x16x32_bf16 v[50:53], v[130:133], v[182:185], v[50:53]
	v_mfma_f32_16x16x32_bf16 v[46:49], v[122:125], v[190:193], v[46:49]
	v_mfma_f32_16x16x32_bf16 v[42:45], v[130:133], v[190:193], v[42:45]
	v_mfma_f32_16x16x32_bf16 v[38:41], v[122:125], v[198:201], v[38:41]
	v_mfma_f32_16x16x32_bf16 v[34:37], v[130:133], v[198:201], v[34:37]
	v_mfma_f32_16x16x32_bf16 v[62:65], v[126:129], v[168:171], v[62:65]
	v_mfma_f32_16x16x32_bf16 v[58:61], v[142:145], v[168:171], v[58:61]
	v_mfma_f32_16x16x32_bf16 v[54:57], v[126:129], v[186:189], v[54:57]
	v_mfma_f32_16x16x32_bf16 v[50:53], v[142:145], v[186:189], v[50:53]
	v_mfma_f32_16x16x32_bf16 v[46:49], v[126:129], v[194:197], v[46:49]
	v_mfma_f32_16x16x32_bf16 v[42:45], v[142:145], v[194:197], v[42:45]
	v_mfma_f32_16x16x32_bf16 v[38:41], v[126:129], v[202:205], v[38:41]
	v_mfma_f32_16x16x32_bf16 v[34:37], v[142:145], v[202:205], v[34:37]
	s_barrier
	s_setprio 0
	s_mov_b32 m0, s17
	s_mov_b32 s46, s42
	s_mov_b32 s47, s43
	ds_read_b128 v[164:167], v211 offset:16384
	ds_read_b128 v[168:171], v211 offset:17408
	ds_read_b128 v[182:185], v211 offset:18432
	ds_read_b128 v[186:189], v211 offset:19456
	ds_read_b128 v[190:193], v211 offset:20480
	ds_read_b128 v[194:197], v211 offset:21504
	ds_read_b128 v[198:201], v211 offset:22528
	ds_read_b128 v[202:205], v211 offset:23552
	buffer_load_dwordx4 v179, s[44:47], s66 offen lds
	s_mov_b32 m0, s18
	s_add_i32 s68, s66, 0x80000
	buffer_load_dwordx4 v207, s[44:47], s66 offen lds
	s_mov_b32 m0, s19
	s_nop 0
	buffer_load_dwordx4 v179, s[44:47], s68 offen lds
	s_mov_b32 m0, s20
	s_nop 0
	buffer_load_dwordx4 v207, s[44:47], s68 offen lds
	s_mov_b32 m0, s16
	s_nop 0
	buffer_load_dwordx4 v178, s[40:43], s67 offen lds
	s_mov_b32 m0, s21
	s_nop 0
	buffer_load_dwordx4 v206, s[40:43], s67 offen lds
	s_waitcnt vmcnt(8)
	s_waitcnt lgkmcnt(0)
	s_setprio 1
	s_barrier
	v_mfma_f32_16x16x32_bf16 v[94:97], v[106:109], v[164:167], v[94:97]
	v_mfma_f32_16x16x32_bf16 v[90:93], v[114:117], v[164:167], v[90:93]
	v_mfma_f32_16x16x32_bf16 v[86:89], v[106:109], v[182:185], v[86:89]
	v_mfma_f32_16x16x32_bf16 v[82:85], v[114:117], v[182:185], v[82:85]
	v_mfma_f32_16x16x32_bf16 v[78:81], v[106:109], v[190:193], v[78:81]
	v_mfma_f32_16x16x32_bf16 v[74:77], v[114:117], v[190:193], v[74:77]
	v_mfma_f32_16x16x32_bf16 v[70:73], v[106:109], v[198:201], v[70:73]
	v_mfma_f32_16x16x32_bf16 v[66:69], v[114:117], v[198:201], v[66:69]
	v_mfma_f32_16x16x32_bf16 v[94:97], v[110:113], v[168:171], v[94:97]
	v_mfma_f32_16x16x32_bf16 v[90:93], v[118:121], v[168:171], v[90:93]
	v_mfma_f32_16x16x32_bf16 v[86:89], v[110:113], v[186:189], v[86:89]
	v_mfma_f32_16x16x32_bf16 v[82:85], v[118:121], v[186:189], v[82:85]
	v_mfma_f32_16x16x32_bf16 v[78:81], v[110:113], v[194:197], v[78:81]
	v_mfma_f32_16x16x32_bf16 v[74:77], v[118:121], v[194:197], v[74:77]
	v_mfma_f32_16x16x32_bf16 v[70:73], v[110:113], v[202:205], v[70:73]
	v_mfma_f32_16x16x32_bf16 v[66:69], v[118:121], v[202:205], v[66:69]
	v_mfma_f32_16x16x32_bf16 v[30:33], v[122:125], v[164:167], v[30:33]
	v_mfma_f32_16x16x32_bf16 v[26:29], v[130:133], v[164:167], v[26:29]
	v_mfma_f32_16x16x32_bf16 v[22:25], v[122:125], v[182:185], v[22:25]
	v_mfma_f32_16x16x32_bf16 v[18:21], v[130:133], v[182:185], v[18:21]
	v_mfma_f32_16x16x32_bf16 v[14:17], v[122:125], v[190:193], v[14:17]
	v_mfma_f32_16x16x32_bf16 v[10:13], v[130:133], v[190:193], v[10:13]
	v_mfma_f32_16x16x32_bf16 v[6:9], v[122:125], v[198:201], v[6:9]
	v_mfma_f32_16x16x32_bf16 v[2:5], v[130:133], v[198:201], v[2:5]
	v_mfma_f32_16x16x32_bf16 v[30:33], v[126:129], v[168:171], v[30:33]
	v_mfma_f32_16x16x32_bf16 v[26:29], v[142:145], v[168:171], v[26:29]
	v_mfma_f32_16x16x32_bf16 v[22:25], v[126:129], v[186:189], v[22:25]
	v_mfma_f32_16x16x32_bf16 v[18:21], v[142:145], v[186:189], v[18:21]
	v_mfma_f32_16x16x32_bf16 v[14:17], v[126:129], v[194:197], v[14:17]
	v_mfma_f32_16x16x32_bf16 v[10:13], v[142:145], v[194:197], v[10:13]
	v_mfma_f32_16x16x32_bf16 v[6:9], v[126:129], v[202:205], v[6:9]
	v_mfma_f32_16x16x32_bf16 v[2:5], v[142:145], v[202:205], v[2:5]
	s_barrier
; #define PG8_STAGEX(rs, bufoff, soff, voff) do { _Pragma("unroll") for (int _i = 0; _i < 2; ++_i) \
;         __builtin_amdgcn_raw_ptr_buffer_load_lds(rs, (LAS unsigned*)(lds + (bufoff) + ldsw + _i * 8192), 16, (voff)[_i], (soff), 0, 0); } while (0)
; #define PG8_LDA(dst, b, h) do { _Pragma("unroll") for (int m = 0; m < 4; ++m) _Pragma("unroll") for (int k = 0; k < 2; ++k) dst[m][k] = *(const LAS bf16x8*)(lds + PG8_SA(b, h) + aoff + m * 2048 + k * 1024); } while (0)
; #define PG8_LDB(dst, b, h) do { _Pragma("unroll") for (int n = 0; n < 2; ++n) _Pragma("unroll") for (int k = 0; k < 2; ++k) dst[n][k] = *(const LAS bf16x8*)(lds + PG8_SB(b, h) + boff + n * 2048 + k * 1024); } while (0)
; #define PG8_WAIT_V(n) asm volatile("s_waitcnt vmcnt(" #n ")" ::: "memory")
; #define PG8_WAIT_L(n) asm volatile("s_waitcnt lgkmcnt(" #n ")" ::: "memory")
; #define PG8_BAR __builtin_amdgcn_s_barrier()
; #define PG8_SCHED __builtin_amdgcn_sched_barrier(0)
;     ...
;             PG8_WAIT_V(8); PG8_WAIT_L(0); PG8_BAR; PG8_MMA(1, 0, At, B0); PG8_MMA(1, 1, At, B1); PG8_BAR; PG8_SCHED;
;             PG8_LDB(B0, 1, 0); PG8_LDB(B1, 1, 1); PG8_SCHED; PG8_LDA(At, 1, 0); PG8_STAGEX(rsA, PG8_SA(0, 1), a2 + hstepA, voffA);
;             PG8_WAIT_V(8); PG8_WAIT_L(0); PG8_BAR; PG8_MMA(0, 0, At, B0); PG8_MMA(0, 1, At, B1); PG8_BAR; PG8_SCHED;
;             PG8_LDA(At, 1, 1); PG8_STAGEX(rsB, PG8_SB(1, 0), b3, voffB); PG8_STAGEX(rsB, PG8_SB(1, 1), b3 + hstepB, voffB); PG8_STAGEX(rsA, PG8_SA(1, 0), a3, voffA);
;             PG8_WAIT_V(8); PG8_WAIT_L(0); PG8_BAR; PG8_MMA(1, 0, At, B0); PG8_MMA(1, 1, At, B1); PG8_BAR; PG8_SCHED;
;         }
;     ...
;         if (wr == 0) PG8_BAR;
	s_setprio 0
	v_add_u32_e32 v118, 0x18000, v210
	v_add_u32_e32 v142, 0x1c000, v210
	ds_read_b128 v[106:109], v118
	ds_read_b128 v[110:113], v118 offset:1024
	ds_read_b128 v[114:117], v118 offset:2048
	ds_read_b128 v[118:121], v118 offset:3072
	ds_read_b128 v[122:125], v142
	ds_read_b128 v[126:129], v142 offset:1024
	ds_read_b128 v[130:133], v142 offset:2048
	ds_read_b128 v[142:145], v142 offset:3072
	s_add_i32 s67, s67, 0x80000
	s_mov_b32 m0, s22
	ds_read_b128 v[164:167], v211 offset:32768
	ds_read_b128 v[168:171], v211 offset:33792
	ds_read_b128 v[182:185], v211 offset:34816
	ds_read_b128 v[186:189], v211 offset:35840
	ds_read_b128 v[190:193], v211 offset:36864
	ds_read_b128 v[194:197], v211 offset:37888
	ds_read_b128 v[198:201], v211 offset:38912
	ds_read_b128 v[202:205], v211 offset:39936
	buffer_load_dwordx4 v178, s[40:43], s67 offen lds
	s_mov_b32 m0, s23
	s_nop 0
	buffer_load_dwordx4 v206, s[40:43], s67 offen lds
	s_waitcnt vmcnt(8)
	s_waitcnt lgkmcnt(0)
	s_setprio 1
	s_barrier
	v_mfma_f32_16x16x32_bf16 v[158:161], v[106:109], v[164:167], v[158:161]
	v_mfma_f32_16x16x32_bf16 v[154:157], v[114:117], v[164:167], v[154:157]
	v_mfma_f32_16x16x32_bf16 v[150:153], v[106:109], v[182:185], v[150:153]
	v_mfma_f32_16x16x32_bf16 v[146:149], v[114:117], v[182:185], v[146:149]
	v_mfma_f32_16x16x32_bf16 v[138:141], v[106:109], v[190:193], v[138:141]
	v_mfma_f32_16x16x32_bf16 v[134:137], v[114:117], v[190:193], v[134:137]
	v_mfma_f32_16x16x32_bf16 v[102:105], v[106:109], v[198:201], v[102:105]
	v_mfma_f32_16x16x32_bf16 v[98:101], v[114:117], v[198:201], v[98:101]
	v_mfma_f32_16x16x32_bf16 v[158:161], v[110:113], v[168:171], v[158:161]
	v_mfma_f32_16x16x32_bf16 v[154:157], v[118:121], v[168:171], v[154:157]
	v_mfma_f32_16x16x32_bf16 v[150:153], v[110:113], v[186:189], v[150:153]
	v_mfma_f32_16x16x32_bf16 v[146:149], v[118:121], v[186:189], v[146:149]
	v_mfma_f32_16x16x32_bf16 v[138:141], v[110:113], v[194:197], v[138:141]
	v_mfma_f32_16x16x32_bf16 v[134:137], v[118:121], v[194:197], v[134:137]
	v_mfma_f32_16x16x32_bf16 v[102:105], v[110:113], v[202:205], v[102:105]
	v_mfma_f32_16x16x32_bf16 v[98:101], v[118:121], v[202:205], v[98:101]
	v_mfma_f32_16x16x32_bf16 v[62:65], v[122:125], v[164:167], v[62:65]
	v_mfma_f32_16x16x32_bf16 v[58:61], v[130:133], v[164:167], v[58:61]
	v_mfma_f32_16x16x32_bf16 v[54:57], v[122:125], v[182:185], v[54:57]
	v_mfma_f32_16x16x32_bf16 v[50:53], v[130:133], v[182:185], v[50:53]
	v_mfma_f32_16x16x32_bf16 v[46:49], v[122:125], v[190:193], v[46:49]
	v_mfma_f32_16x16x32_bf16 v[42:45], v[130:133], v[190:193], v[42:45]
	v_mfma_f32_16x16x32_bf16 v[38:41], v[122:125], v[198:201], v[38:41]
	v_mfma_f32_16x16x32_bf16 v[34:37], v[130:133], v[198:201], v[34:37]
	v_mfma_f32_16x16x32_bf16 v[62:65], v[126:129], v[168:171], v[62:65]
	v_mfma_f32_16x16x32_bf16 v[58:61], v[142:145], v[168:171], v[58:61]
	v_mfma_f32_16x16x32_bf16 v[54:57], v[126:129], v[186:189], v[54:57]
	v_mfma_f32_16x16x32_bf16 v[50:53], v[142:145], v[186:189], v[50:53]
	v_mfma_f32_16x16x32_bf16 v[46:49], v[126:129], v[194:197], v[46:49]
	v_mfma_f32_16x16x32_bf16 v[42:45], v[142:145], v[194:197], v[42:45]
	v_mfma_f32_16x16x32_bf16 v[38:41], v[126:129], v[202:205], v[38:41]
	v_mfma_f32_16x16x32_bf16 v[34:37], v[142:145], v[202:205], v[34:37]
	s_barrier
	s_setprio 0
	s_mov_b32 m0, s54
	s_or_b32 s67, s66, 0x80
	ds_read_b128 v[164:167], v211 offset:49152
	ds_read_b128 v[168:171], v211 offset:50176
	ds_read_b128 v[182:185], v211 offset:51200
	ds_read_b128 v[186:189], v211 offset:52224
	ds_read_b128 v[190:193], v211 offset:53248
	ds_read_b128 v[194:197], v211 offset:54272
	ds_read_b128 v[198:201], v211 offset:55296
	ds_read_b128 v[202:205], v211 offset:56320
	buffer_load_dwordx4 v179, s[44:47], s67 offen lds
	s_mov_b32 m0, s55
	s_add_i32 s66, s66, 0x80080
	buffer_load_dwordx4 v207, s[44:47], s67 offen lds
	s_mov_b32 m0, s74
	s_nop 0
	buffer_load_dwordx4 v179, s[44:47], s66 offen lds
	s_mov_b32 m0, s75
	s_nop 0
	buffer_load_dwordx4 v207, s[44:47], s66 offen lds
	s_mov_b32 m0, s72
	s_nop 0
	buffer_load_dwordx4 v178, s[40:43], s65 offen lds
	s_mov_b32 m0, s73
	s_nop 0
	buffer_load_dwordx4 v206, s[40:43], s65 offen lds
	s_waitcnt vmcnt(8)
	s_waitcnt lgkmcnt(0)
	s_setprio 1
	s_barrier
	v_mfma_f32_16x16x32_bf16 v[94:97], v[106:109], v[164:167], v[94:97]
	v_mfma_f32_16x16x32_bf16 v[90:93], v[114:117], v[164:167], v[90:93]
	v_mfma_f32_16x16x32_bf16 v[86:89], v[106:109], v[182:185], v[86:89]
	v_mfma_f32_16x16x32_bf16 v[82:85], v[114:117], v[182:185], v[82:85]
	v_mfma_f32_16x16x32_bf16 v[78:81], v[106:109], v[190:193], v[78:81]
	v_mfma_f32_16x16x32_bf16 v[74:77], v[114:117], v[190:193], v[74:77]
	v_mfma_f32_16x16x32_bf16 v[70:73], v[106:109], v[198:201], v[70:73]
	v_mfma_f32_16x16x32_bf16 v[66:69], v[114:117], v[198:201], v[66:69]
	v_mfma_f32_16x16x32_bf16 v[94:97], v[110:113], v[168:171], v[94:97]
	v_mfma_f32_16x16x32_bf16 v[90:93], v[118:121], v[168:171], v[90:93]
	v_mfma_f32_16x16x32_bf16 v[86:89], v[110:113], v[186:189], v[86:89]
	v_mfma_f32_16x16x32_bf16 v[82:85], v[118:121], v[186:189], v[82:85]
	v_mfma_f32_16x16x32_bf16 v[78:81], v[110:113], v[194:197], v[78:81]
	v_mfma_f32_16x16x32_bf16 v[74:77], v[118:121], v[194:197], v[74:77]
	v_mfma_f32_16x16x32_bf16 v[70:73], v[110:113], v[202:205], v[70:73]
	v_mfma_f32_16x16x32_bf16 v[66:69], v[118:121], v[202:205], v[66:69]
	v_mfma_f32_16x16x32_bf16 v[30:33], v[122:125], v[164:167], v[30:33]
	v_mfma_f32_16x16x32_bf16 v[26:29], v[130:133], v[164:167], v[26:29]
	v_mfma_f32_16x16x32_bf16 v[22:25], v[122:125], v[182:185], v[22:25]
	v_mfma_f32_16x16x32_bf16 v[18:21], v[130:133], v[182:185], v[18:21]
	v_mfma_f32_16x16x32_bf16 v[14:17], v[122:125], v[190:193], v[14:17]
	v_mfma_f32_16x16x32_bf16 v[10:13], v[130:133], v[190:193], v[10:13]
	v_mfma_f32_16x16x32_bf16 v[6:9], v[122:125], v[198:201], v[6:9]
	v_mfma_f32_16x16x32_bf16 v[2:5], v[130:133], v[198:201], v[2:5]
	v_mfma_f32_16x16x32_bf16 v[30:33], v[126:129], v[168:171], v[30:33]
	v_mfma_f32_16x16x32_bf16 v[26:29], v[142:145], v[168:171], v[26:29]
	v_mfma_f32_16x16x32_bf16 v[22:25], v[126:129], v[186:189], v[22:25]
	v_mfma_f32_16x16x32_bf16 v[18:21], v[142:145], v[186:189], v[18:21]
	v_mfma_f32_16x16x32_bf16 v[14:17], v[126:129], v[194:197], v[14:17]
	v_mfma_f32_16x16x32_bf16 v[10:13], v[142:145], v[194:197], v[10:13]
	v_mfma_f32_16x16x32_bf16 v[6:9], v[126:129], v[202:205], v[6:9]
	v_mfma_f32_16x16x32_bf16 v[2:5], v[142:145], v[202:205], v[2:5]
	s_barrier
	s_setprio 0
	s_add_i32 s64, s64, 2
	s_addk_i32 s59, 0x100
	s_addk_i32 s63, 0x100
	s_cmp_gt_u32 s64, 29
	s_cbranch_scc0 .LBB0_1529
	s_and_b64 vcc, exec, s[52:53]
	s_cbranch_vccz .LBB0_1532
	s_barrier

; #define PG8_STAGEX(rs, bufoff, soff, voff) do { _Pragma("unroll") for (int _i = 0; _i < 2; ++_i) \
;         __builtin_amdgcn_raw_ptr_buffer_load_lds(rs, (LAS unsigned*)(lds + (bufoff) + ldsw + _i * 8192), 16, (voff)[_i], (soff), 0, 0); } while (0)
; #define PG8_LDA(dst, b, h) do { _Pragma("unroll") for (int m = 0; m < 4; ++m) _Pragma("unroll") for (int k = 0; k < 2; ++k) dst[m][k] = *(const LAS bf16x8*)(lds + PG8_SA(b, h) + aoff + m * 2048 + k * 1024); } while (0)
; #define PG8_LDB(dst, b, h) do { _Pragma("unroll") for (int n = 0; n < 2; ++n) _Pragma("unroll") for (int k = 0; k < 2; ++k) dst[n][k] = *(const LAS bf16x8*)(lds + PG8_SB(b, h) + boff + n * 2048 + k * 1024); } while (0)
; #define PG8_WAIT_V(n) asm volatile("s_waitcnt vmcnt(" #n ")" ::: "memory")
; #define PG8_WAIT_L(n) asm volatile("s_waitcnt lgkmcnt(" #n ")" ::: "memory")
; #define PG8_BAR __builtin_amdgcn_s_barrier()
; #define PG8_SCHED __builtin_amdgcn_sched_barrier(0)
;     ...
;             const bool last = (t == nt - 2);
;             const unsigned a1 = cA + (unsigned)(t + 1) * kstep;
;             const unsigned a2 = last ? nA : cA + (unsigned)(t + 2) * kstep, b2 = last ? nB : cB + (unsigned)(t + 2) * kstep;
;             const unsigned a3 = a2 + kstep, b3 = b2 + kstep;
;             PG8_LDB(B0, 0, 0); PG8_LDB(B1, 0, 1); PG8_SCHED; PG8_LDA(At, 0, 0); PG8_STAGEX(rsA, PG8_SA(1, 1), a1 + hstepA, voffA);
;             PG8_WAIT_V(8); PG8_WAIT_L(0); PG8_BAR; PG8_MMA(0, 0, At, B0); PG8_MMA(0, 1, At, B1); PG8_BAR; PG8_SCHED;
;             PG8_LDA(At, 0, 1); PG8_STAGEX(rsB, PG8_SB(0, 0), b2, voffB); PG8_STAGEX(rsB, PG8_SB(0, 1), b2 + hstepB, voffB); PG8_STAGEX(rsA, PG8_SA(0, 0), a2, voffA);
;             PG8_WAIT_V(8); PG8_WAIT_L(0); PG8_BAR; PG8_MMA(1, 0, At, B0); PG8_MMA(1, 1, At, B1); PG8_BAR; PG8_SCHED;
.LBB0_1651:
	v_add_u32_e32 v102, 0x10000, v172
	v_add_u32_e32 v146, 0x14000, v172
	ds_read_b128 v[82:85], v102
	ds_read_b128 v[86:89], v102 offset:1024
	ds_read_b128 v[98:101], v102 offset:2048
	ds_read_b128 v[102:105], v102 offset:3072
	ds_read_b128 v[150:153], v146
	ds_read_b128 v[154:157], v146 offset:1024
	ds_read_b128 v[182:185], v146 offset:2048
	ds_read_b128 v[186:189], v146 offset:3072
	s_add_i32 s42, s61, 0xfff80080
	s_cmp_eq_u32 s63, 28
	s_cselect_b32 s66, s30, s42
	s_cselect_b32 s65, s31, s62
	s_or_b32 s64, s66, 0x80
	s_mov_b32 m0, s29
	ds_read_b128 v[190:193], v173
	ds_read_b128 v[194:197], v173 offset:1024
	ds_read_b128 v[198:201], v173 offset:2048
	ds_read_b128 v[202:205], v173 offset:3072
	ds_read_b128 v[206:209], v173 offset:4096
	ds_read_b128 v[210:213], v173 offset:5120
	ds_read_b128 v[214:217], v173 offset:6144
	ds_read_b128 v[218:221], v173 offset:7168
	buffer_load_dwordx4 v159, s[76:79], s61 offen lds
	s_mov_b32 m0, s50
	s_nop 0
	buffer_load_dwordx4 v163, s[76:79], s61 offen lds
	s_waitcnt vmcnt(8)
	s_waitcnt lgkmcnt(0)
	s_setprio 1
	s_barrier
	v_mfma_f32_16x16x32_bf16 v[142:145], v[82:85], v[190:193], v[142:145]
	v_mfma_f32_16x16x32_bf16 v[134:137], v[98:101], v[190:193], v[134:137]
	v_mfma_f32_16x16x32_bf16 v[126:129], v[82:85], v[198:201], v[126:129]
	v_mfma_f32_16x16x32_bf16 v[118:121], v[98:101], v[198:201], v[118:121]
	v_mfma_f32_16x16x32_bf16 v[110:113], v[82:85], v[206:209], v[110:113]
	v_mfma_f32_16x16x32_bf16 v[94:97], v[98:101], v[206:209], v[94:97]
	v_mfma_f32_16x16x32_bf16 v[78:81], v[82:85], v[214:217], v[78:81]
	v_mfma_f32_16x16x32_bf16 v[70:73], v[98:101], v[214:217], v[70:73]
	v_mfma_f32_16x16x32_bf16 v[142:145], v[86:89], v[194:197], v[142:145]
	v_mfma_f32_16x16x32_bf16 v[134:137], v[102:105], v[194:197], v[134:137]
	v_mfma_f32_16x16x32_bf16 v[126:129], v[86:89], v[202:205], v[126:129]
	v_mfma_f32_16x16x32_bf16 v[118:121], v[102:105], v[202:205], v[118:121]
	v_mfma_f32_16x16x32_bf16 v[110:113], v[86:89], v[210:213], v[110:113]
	v_mfma_f32_16x16x32_bf16 v[94:97], v[102:105], v[210:213], v[94:97]
	v_mfma_f32_16x16x32_bf16 v[78:81], v[86:89], v[218:221], v[78:81]
	v_mfma_f32_16x16x32_bf16 v[70:73], v[102:105], v[218:221], v[70:73]
	v_mfma_f32_16x16x32_bf16 v[138:141], v[150:153], v[190:193], v[138:141]
	v_mfma_f32_16x16x32_bf16 v[130:133], v[182:185], v[190:193], v[130:133]
	v_mfma_f32_16x16x32_bf16 v[122:125], v[150:153], v[198:201], v[122:125]
	v_mfma_f32_16x16x32_bf16 v[114:117], v[182:185], v[198:201], v[114:117]
	v_mfma_f32_16x16x32_bf16 v[106:109], v[150:153], v[206:209], v[106:109]
	v_mfma_f32_16x16x32_bf16 v[90:93], v[182:185], v[206:209], v[90:93]
	v_mfma_f32_16x16x32_bf16 v[74:77], v[150:153], v[214:217], v[74:77]
	v_mfma_f32_16x16x32_bf16 v[66:69], v[182:185], v[214:217], v[66:69]
	v_mfma_f32_16x16x32_bf16 v[138:141], v[154:157], v[194:197], v[138:141]
	v_mfma_f32_16x16x32_bf16 v[130:133], v[186:189], v[194:197], v[130:133]
	v_mfma_f32_16x16x32_bf16 v[122:125], v[154:157], v[202:205], v[122:125]
	v_mfma_f32_16x16x32_bf16 v[114:117], v[186:189], v[202:205], v[114:117]
	v_mfma_f32_16x16x32_bf16 v[106:109], v[154:157], v[210:213], v[106:109]
	v_mfma_f32_16x16x32_bf16 v[90:93], v[186:189], v[210:213], v[90:93]
	v_mfma_f32_16x16x32_bf16 v[74:77], v[154:157], v[218:221], v[74:77]
	v_mfma_f32_16x16x32_bf16 v[66:69], v[186:189], v[218:221], v[66:69]
	s_barrier
	s_setprio 0
	s_mov_b32 m0, s16
	s_mov_b32 s42, s78
	s_mov_b32 s43, s79
	ds_read_b128 v[190:193], v173 offset:16384
	ds_read_b128 v[194:197], v173 offset:17408
	ds_read_b128 v[198:201], v173 offset:18432
	ds_read_b128 v[202:205], v173 offset:19456
	ds_read_b128 v[206:209], v173 offset:20480
	ds_read_b128 v[210:213], v173 offset:21504
	ds_read_b128 v[214:217], v173 offset:22528
	ds_read_b128 v[218:221], v173 offset:23552
	buffer_load_dwordx4 v161, s[40:43], s65 offen lds
	s_mov_b32 m0, s17
	s_add_i32 s67, s65, 0x80000
	buffer_load_dwordx4 v165, s[40:43], s65 offen lds
	s_mov_b32 m0, s18
	s_nop 0
	buffer_load_dwordx4 v161, s[40:43], s67 offen lds
	s_mov_b32 m0, s19
	s_nop 0
	buffer_load_dwordx4 v165, s[40:43], s67 offen lds
	s_mov_b32 m0, s15
	s_nop 0
	buffer_load_dwordx4 v159, s[76:79], s66 offen lds
	s_mov_b32 m0, s20
	s_nop 0
	buffer_load_dwordx4 v163, s[76:79], s66 offen lds
	s_waitcnt vmcnt(8)
	s_waitcnt lgkmcnt(0)
	s_setprio 1
	s_barrier
	v_mfma_f32_16x16x32_bf16 v[62:65], v[82:85], v[190:193], v[62:65]
	v_mfma_f32_16x16x32_bf16 v[54:57], v[98:101], v[190:193], v[54:57]
	v_mfma_f32_16x16x32_bf16 v[46:49], v[82:85], v[198:201], v[46:49]
	v_mfma_f32_16x16x32_bf16 v[38:41], v[98:101], v[198:201], v[38:41]
	v_mfma_f32_16x16x32_bf16 v[30:33], v[82:85], v[206:209], v[30:33]
	v_mfma_f32_16x16x32_bf16 v[22:25], v[98:101], v[206:209], v[22:25]
	v_mfma_f32_16x16x32_bf16 v[14:17], v[82:85], v[214:217], v[14:17]
	v_mfma_f32_16x16x32_bf16 v[6:9], v[98:101], v[214:217], v[6:9]
	v_mfma_f32_16x16x32_bf16 v[62:65], v[86:89], v[194:197], v[62:65]
	v_mfma_f32_16x16x32_bf16 v[54:57], v[102:105], v[194:197], v[54:57]
	v_mfma_f32_16x16x32_bf16 v[46:49], v[86:89], v[202:205], v[46:49]
	v_mfma_f32_16x16x32_bf16 v[38:41], v[102:105], v[202:205], v[38:41]
	v_mfma_f32_16x16x32_bf16 v[30:33], v[86:89], v[210:213], v[30:33]
	v_mfma_f32_16x16x32_bf16 v[22:25], v[102:105], v[210:213], v[22:25]
	v_mfma_f32_16x16x32_bf16 v[14:17], v[86:89], v[218:221], v[14:17]
	v_mfma_f32_16x16x32_bf16 v[6:9], v[102:105], v[218:221], v[6:9]
	v_mfma_f32_16x16x32_bf16 v[58:61], v[150:153], v[190:193], v[58:61]
	v_mfma_f32_16x16x32_bf16 v[50:53], v[182:185], v[190:193], v[50:53]
	v_mfma_f32_16x16x32_bf16 v[42:45], v[150:153], v[198:201], v[42:45]
	v_mfma_f32_16x16x32_bf16 v[34:37], v[182:185], v[198:201], v[34:37]
	v_mfma_f32_16x16x32_bf16 v[26:29], v[150:153], v[206:209], v[26:29]
	v_mfma_f32_16x16x32_bf16 v[18:21], v[182:185], v[206:209], v[18:21]
	v_mfma_f32_16x16x32_bf16 v[10:13], v[150:153], v[214:217], v[10:13]
	v_mfma_f32_16x16x32_bf16 v[2:5], v[182:185], v[214:217], v[2:5]
	v_mfma_f32_16x16x32_bf16 v[58:61], v[154:157], v[194:197], v[58:61]
	v_mfma_f32_16x16x32_bf16 v[50:53], v[186:189], v[194:197], v[50:53]
	v_mfma_f32_16x16x32_bf16 v[42:45], v[154:157], v[202:205], v[42:45]
	v_mfma_f32_16x16x32_bf16 v[34:37], v[186:189], v[202:205], v[34:37]
	v_mfma_f32_16x16x32_bf16 v[26:29], v[154:157], v[210:213], v[26:29]
	v_mfma_f32_16x16x32_bf16 v[18:21], v[186:189], v[210:213], v[18:21]
	v_mfma_f32_16x16x32_bf16 v[10:13], v[154:157], v[218:221], v[10:13]
	v_mfma_f32_16x16x32_bf16 v[2:5], v[186:189], v[218:221], v[2:5]
	s_barrier
; #define PG8_STAGEX(rs, bufoff, soff, voff) do { _Pragma("unroll") for (int _i = 0; _i < 2; ++_i) \
;         __builtin_amdgcn_raw_ptr_buffer_load_lds(rs, (LAS unsigned*)(lds + (bufoff) + ldsw + _i * 8192), 16, (voff)[_i], (soff), 0, 0); } while (0)
; #define PG8_LDA(dst, b, h) do { _Pragma("unroll") for (int m = 0; m < 4; ++m) _Pragma("unroll") for (int k = 0; k < 2; ++k) dst[m][k] = *(const LAS bf16x8*)(lds + PG8_SA(b, h) + aoff + m * 2048 + k * 1024); } while (0)
; #define PG8_LDB(dst, b, h) do { _Pragma("unroll") for (int n = 0; n < 2; ++n) _Pragma("unroll") for (int k = 0; k < 2; ++k) dst[n][k] = *(const LAS bf16x8*)(lds + PG8_SB(b, h) + boff + n * 2048 + k * 1024); } while (0)
; #define PG8_WAIT_V(n) asm volatile("s_waitcnt vmcnt(" #n ")" ::: "memory")
; #define PG8_WAIT_L(n) asm volatile("s_waitcnt lgkmcnt(" #n ")" ::: "memory")
; #define PG8_BAR __builtin_amdgcn_s_barrier()
; #define PG8_SCHED __builtin_amdgcn_sched_barrier(0)
;     ...
;             PG8_WAIT_V(8); PG8_WAIT_L(0); PG8_BAR; PG8_MMA(1, 0, At, B0); PG8_MMA(1, 1, At, B1); PG8_BAR; PG8_SCHED;
;             PG8_LDB(B0, 1, 0); PG8_LDB(B1, 1, 1); PG8_SCHED; PG8_LDA(At, 1, 0); PG8_STAGEX(rsA, PG8_SA(0, 1), a2 + hstepA, voffA);
;             PG8_WAIT_V(8); PG8_WAIT_L(0); PG8_BAR; PG8_MMA(0, 0, At, B0); PG8_MMA(0, 1, At, B1); PG8_BAR; PG8_SCHED;
;             PG8_LDA(At, 1, 1); PG8_STAGEX(rsB, PG8_SB(1, 0), b3, voffB); PG8_STAGEX(rsB, PG8_SB(1, 1), b3 + hstepB, voffB); PG8_STAGEX(rsA, PG8_SA(1, 0), a3, voffA);
;             PG8_WAIT_V(8); PG8_WAIT_L(0); PG8_BAR; PG8_MMA(1, 0, At, B0); PG8_MMA(1, 1, At, B1); PG8_BAR; PG8_SCHED;
;         }
;     ...
;         if (wr == 0) PG8_BAR;
	s_setprio 0
	v_add_u32_e32 v102, 0x18000, v172
	v_add_u32_e32 v146, 0x1c000, v172
	ds_read_b128 v[82:85], v102
	ds_read_b128 v[86:89], v102 offset:1024
	ds_read_b128 v[98:101], v102 offset:2048
	ds_read_b128 v[102:105], v102 offset:3072
	ds_read_b128 v[150:153], v146
	ds_read_b128 v[154:157], v146 offset:1024
	ds_read_b128 v[182:185], v146 offset:2048
	ds_read_b128 v[186:189], v146 offset:3072
	s_add_i32 s66, s66, 0x80000
	s_mov_b32 m0, s21
	ds_read_b128 v[190:193], v173 offset:32768
	ds_read_b128 v[194:197], v173 offset:33792
	ds_read_b128 v[198:201], v173 offset:34816
	ds_read_b128 v[202:205], v173 offset:35840
	ds_read_b128 v[206:209], v173 offset:36864
	ds_read_b128 v[210:213], v173 offset:37888
	ds_read_b128 v[214:217], v173 offset:38912
	ds_read_b128 v[218:221], v173 offset:39936
	buffer_load_dwordx4 v159, s[76:79], s66 offen lds
	s_mov_b32 m0, s22
	s_nop 0
	buffer_load_dwordx4 v163, s[76:79], s66 offen lds
	s_waitcnt vmcnt(8)
	s_waitcnt lgkmcnt(0)
	s_setprio 1
	s_barrier
	v_mfma_f32_16x16x32_bf16 v[142:145], v[82:85], v[190:193], v[142:145]
	v_mfma_f32_16x16x32_bf16 v[134:137], v[98:101], v[190:193], v[134:137]
	v_mfma_f32_16x16x32_bf16 v[126:129], v[82:85], v[198:201], v[126:129]
	v_mfma_f32_16x16x32_bf16 v[118:121], v[98:101], v[198:201], v[118:121]
	v_mfma_f32_16x16x32_bf16 v[110:113], v[82:85], v[206:209], v[110:113]
	v_mfma_f32_16x16x32_bf16 v[94:97], v[98:101], v[206:209], v[94:97]
	v_mfma_f32_16x16x32_bf16 v[78:81], v[82:85], v[214:217], v[78:81]
	v_mfma_f32_16x16x32_bf16 v[70:73], v[98:101], v[214:217], v[70:73]
	v_mfma_f32_16x16x32_bf16 v[142:145], v[86:89], v[194:197], v[142:145]
	v_mfma_f32_16x16x32_bf16 v[134:137], v[102:105], v[194:197], v[134:137]
	v_mfma_f32_16x16x32_bf16 v[126:129], v[86:89], v[202:205], v[126:129]
	v_mfma_f32_16x16x32_bf16 v[118:121], v[102:105], v[202:205], v[118:121]
	v_mfma_f32_16x16x32_bf16 v[110:113], v[86:89], v[210:213], v[110:113]
	v_mfma_f32_16x16x32_bf16 v[94:97], v[102:105], v[210:213], v[94:97]
	v_mfma_f32_16x16x32_bf16 v[78:81], v[86:89], v[218:221], v[78:81]
	v_mfma_f32_16x16x32_bf16 v[70:73], v[102:105], v[218:221], v[70:73]
	v_mfma_f32_16x16x32_bf16 v[138:141], v[150:153], v[190:193], v[138:141]
	v_mfma_f32_16x16x32_bf16 v[130:133], v[182:185], v[190:193], v[130:133]
	v_mfma_f32_16x16x32_bf16 v[122:125], v[150:153], v[198:201], v[122:125]
	v_mfma_f32_16x16x32_bf16 v[114:117], v[182:185], v[198:201], v[114:117]
	v_mfma_f32_16x16x32_bf16 v[106:109], v[150:153], v[206:209], v[106:109]
	v_mfma_f32_16x16x32_bf16 v[90:93], v[182:185], v[206:209], v[90:93]
	v_mfma_f32_16x16x32_bf16 v[74:77], v[150:153], v[214:217], v[74:77]
	v_mfma_f32_16x16x32_bf16 v[66:69], v[182:185], v[214:217], v[66:69]
	v_mfma_f32_16x16x32_bf16 v[138:141], v[154:157], v[194:197], v[138:141]
	v_mfma_f32_16x16x32_bf16 v[130:133], v[186:189], v[194:197], v[130:133]
	v_mfma_f32_16x16x32_bf16 v[122:125], v[154:157], v[202:205], v[122:125]
	v_mfma_f32_16x16x32_bf16 v[114:117], v[186:189], v[202:205], v[114:117]
	v_mfma_f32_16x16x32_bf16 v[106:109], v[154:157], v[210:213], v[106:109]
	v_mfma_f32_16x16x32_bf16 v[90:93], v[186:189], v[210:213], v[90:93]
	v_mfma_f32_16x16x32_bf16 v[74:77], v[154:157], v[218:221], v[74:77]
	v_mfma_f32_16x16x32_bf16 v[66:69], v[186:189], v[218:221], v[66:69]
	s_barrier
	s_setprio 0
	s_mov_b32 m0, s23
	s_or_b32 s66, s65, 0x80
	ds_read_b128 v[190:193], v173 offset:49152
	ds_read_b128 v[194:197], v173 offset:50176
	ds_read_b128 v[198:201], v173 offset:51200
	ds_read_b128 v[202:205], v173 offset:52224
	ds_read_b128 v[206:209], v173 offset:53248
	ds_read_b128 v[210:213], v173 offset:54272
	ds_read_b128 v[214:217], v173 offset:55296
	ds_read_b128 v[218:221], v173 offset:56320
	buffer_load_dwordx4 v161, s[40:43], s66 offen lds
	s_mov_b32 m0, s24
	s_add_i32 s65, s65, 0x80080
	buffer_load_dwordx4 v165, s[40:43], s66 offen lds
	s_mov_b32 m0, s27
	s_nop 0
	buffer_load_dwordx4 v161, s[40:43], s65 offen lds
	s_mov_b32 m0, s28
	s_nop 0
	buffer_load_dwordx4 v165, s[40:43], s65 offen lds
	s_mov_b32 m0, s25
	s_nop 0
	buffer_load_dwordx4 v159, s[76:79], s64 offen lds
	s_mov_b32 m0, s26
	s_nop 0
	buffer_load_dwordx4 v163, s[76:79], s64 offen lds
	s_waitcnt vmcnt(8)
	s_waitcnt lgkmcnt(0)
	s_setprio 1
	s_barrier
	v_mfma_f32_16x16x32_bf16 v[62:65], v[82:85], v[190:193], v[62:65]
	v_mfma_f32_16x16x32_bf16 v[54:57], v[98:101], v[190:193], v[54:57]
	v_mfma_f32_16x16x32_bf16 v[46:49], v[82:85], v[198:201], v[46:49]
	v_mfma_f32_16x16x32_bf16 v[38:41], v[98:101], v[198:201], v[38:41]
	v_mfma_f32_16x16x32_bf16 v[30:33], v[82:85], v[206:209], v[30:33]
	v_mfma_f32_16x16x32_bf16 v[22:25], v[98:101], v[206:209], v[22:25]
	v_mfma_f32_16x16x32_bf16 v[14:17], v[82:85], v[214:217], v[14:17]
	v_mfma_f32_16x16x32_bf16 v[6:9], v[98:101], v[214:217], v[6:9]
	v_mfma_f32_16x16x32_bf16 v[62:65], v[86:89], v[194:197], v[62:65]
	v_mfma_f32_16x16x32_bf16 v[54:57], v[102:105], v[194:197], v[54:57]
	v_mfma_f32_16x16x32_bf16 v[46:49], v[86:89], v[202:205], v[46:49]
	v_mfma_f32_16x16x32_bf16 v[38:41], v[102:105], v[202:205], v[38:41]
	v_mfma_f32_16x16x32_bf16 v[30:33], v[86:89], v[210:213], v[30:33]
	v_mfma_f32_16x16x32_bf16 v[22:25], v[102:105], v[210:213], v[22:25]
	v_mfma_f32_16x16x32_bf16 v[14:17], v[86:89], v[218:221], v[14:17]
	v_mfma_f32_16x16x32_bf16 v[6:9], v[102:105], v[218:221], v[6:9]
	v_mfma_f32_16x16x32_bf16 v[58:61], v[150:153], v[190:193], v[58:61]
	v_mfma_f32_16x16x32_bf16 v[50:53], v[182:185], v[190:193], v[50:53]
	v_mfma_f32_16x16x32_bf16 v[42:45], v[150:153], v[198:201], v[42:45]
	v_mfma_f32_16x16x32_bf16 v[34:37], v[182:185], v[198:201], v[34:37]
	v_mfma_f32_16x16x32_bf16 v[26:29], v[150:153], v[206:209], v[26:29]
	v_mfma_f32_16x16x32_bf16 v[18:21], v[182:185], v[206:209], v[18:21]
	v_mfma_f32_16x16x32_bf16 v[10:13], v[150:153], v[214:217], v[10:13]
	v_mfma_f32_16x16x32_bf16 v[2:5], v[182:185], v[214:217], v[2:5]
	v_mfma_f32_16x16x32_bf16 v[58:61], v[154:157], v[194:197], v[58:61]
	v_mfma_f32_16x16x32_bf16 v[50:53], v[186:189], v[194:197], v[50:53]
	v_mfma_f32_16x16x32_bf16 v[42:45], v[154:157], v[202:205], v[42:45]
	v_mfma_f32_16x16x32_bf16 v[34:37], v[186:189], v[202:205], v[34:37]
	v_mfma_f32_16x16x32_bf16 v[26:29], v[154:157], v[210:213], v[26:29]
	v_mfma_f32_16x16x32_bf16 v[18:21], v[186:189], v[210:213], v[18:21]
	v_mfma_f32_16x16x32_bf16 v[10:13], v[154:157], v[218:221], v[10:13]
	v_mfma_f32_16x16x32_bf16 v[2:5], v[186:189], v[218:221], v[2:5]
	s_barrier
	s_setprio 0
	s_add_i32 s63, s63, 2
	s_addk_i32 s61, 0x100
	s_addk_i32 s62, 0x100
	s_cmp_gt_u32 s63, 29
	s_cbranch_scc0 .LBB0_1651
	s_and_b64 vcc, exec, s[48:49]
	s_cbranch_vccz .LBB0_1654
	s_barrier

; #define PG8_STAGEX(rs, bufoff, soff, voff) do { _Pragma("unroll") for (int _i = 0; _i < 2; ++_i) \
;         __builtin_amdgcn_raw_ptr_buffer_load_lds(rs, (LAS unsigned*)(lds + (bufoff) + ldsw + _i * 8192), 16, (voff)[_i], (soff), 0, 0); } while (0)
; #define PG8_LDA(dst, b, h) do { _Pragma("unroll") for (int m = 0; m < 4; ++m) _Pragma("unroll") for (int k = 0; k < 2; ++k) dst[m][k] = *(const LAS bf16x8*)(lds + PG8_SA(b, h) + aoff + m * 2048 + k * 1024); } while (0)
; #define PG8_LDB(dst, b, h) do { _Pragma("unroll") for (int n = 0; n < 2; ++n) _Pragma("unroll") for (int k = 0; k < 2; ++k) dst[n][k] = *(const LAS bf16x8*)(lds + PG8_SB(b, h) + boff + n * 2048 + k * 1024); } while (0)
; #define PG8_WAIT_V(n) asm volatile("s_waitcnt vmcnt(" #n ")" ::: "memory")
; #define PG8_WAIT_L(n) asm volatile("s_waitcnt lgkmcnt(" #n ")" ::: "memory")
; #define PG8_BAR __builtin_amdgcn_s_barrier()
; #define PG8_SCHED __builtin_amdgcn_sched_barrier(0)
;     ...
;             for (int t = 0; t < nt; t += 2) {
;                 const bool last = (t == nt - 2);
;                 const unsigned a1 = cA + (unsigned)(t + 1) * kstep;
;                 const unsigned a2 = last ? nA : cA + (unsigned)(t + 2) * kstep, b2 = last ? nB : cB + (unsigned)(t + 2) * kstep;
;                 const unsigned a3 = a2 + kstep, b3 = b2 + kstep;
;                 if (w0) { PG8_LDB(B0, 0, 0); PG8_LDB(B1, 0, 1); PG8_SCHED; PG8_LDA(At, 0, 0); }
;                 PG8_WAIT_L(0); PG8_BAR; if (w0) { PG8_MMA(0, 0, At, B0); PG8_MMA(0, 1, At, B1); } PG8_BAR; PG8_SCHED;
;                 PG8_STAGEX(rsB, PG8_SB(0, 0), b2, voffB); PG8_STAGEX(rsB, PG8_SB(0, 1), b2 + hstepB, voffB); PG8_STAGEX(rsA, PG8_SA(0, 0), a2, voffA);
;                 PG8_WAIT_V(6); PG8_BAR; PG8_BAR; PG8_SCHED;
.LBB0_1668:
	v_add_u32_e32 v86, 0x10000, v72
	v_add_u32_e32 v102, 0x14000, v72
	ds_read_b128 v[74:77], v86
	ds_read_b128 v[78:81], v86 offset:1024
	ds_read_b128 v[82:85], v86 offset:2048
	ds_read_b128 v[86:89], v86 offset:3072
	ds_read_b128 v[90:93], v102
	ds_read_b128 v[94:97], v102 offset:1024
	ds_read_b128 v[98:101], v102 offset:2048
	ds_read_b128 v[102:105], v102 offset:3072
	s_cmp_lg_u32 s27, 28
	s_cselect_b32 s28, s26, 0
	s_add_i32 s29, s28, s17
	s_or_b32 s30, s29, 0x80
	s_add_i32 s28, s28, s10
	ds_read_b128 v[106:109], v73
	ds_read_b128 v[110:113], v73 offset:1024
	ds_read_b128 v[114:117], v73 offset:2048
	ds_read_b128 v[118:121], v73 offset:3072
	ds_read_b128 v[122:125], v73 offset:4096
	ds_read_b128 v[126:129], v73 offset:5120
	ds_read_b128 v[130:133], v73 offset:6144
	ds_read_b128 v[134:137], v73 offset:7168
	s_waitcnt lgkmcnt(0)
	s_setprio 1
	s_barrier
	v_mfma_f32_16x16x32_bf16 v[62:65], v[74:77], v[106:109], v[62:65]
	v_mfma_f32_16x16x32_bf16 v[58:61], v[82:85], v[106:109], v[58:61]
	v_mfma_f32_16x16x32_bf16 v[54:57], v[74:77], v[114:117], v[54:57]
	v_mfma_f32_16x16x32_bf16 v[38:41], v[82:85], v[114:117], v[38:41]
	v_mfma_f32_16x16x32_bf16 v[30:33], v[74:77], v[122:125], v[30:33]
	v_mfma_f32_16x16x32_bf16 v[22:25], v[82:85], v[122:125], v[22:25]
	v_mfma_f32_16x16x32_bf16 v[14:17], v[74:77], v[130:133], v[14:17]
	v_mfma_f32_16x16x32_bf16 v[6:9], v[82:85], v[130:133], v[6:9]
	v_mfma_f32_16x16x32_bf16 v[62:65], v[78:81], v[110:113], v[62:65]
	v_mfma_f32_16x16x32_bf16 v[58:61], v[86:89], v[110:113], v[58:61]
	v_mfma_f32_16x16x32_bf16 v[54:57], v[78:81], v[118:121], v[54:57]
	v_mfma_f32_16x16x32_bf16 v[38:41], v[86:89], v[118:121], v[38:41]
	v_mfma_f32_16x16x32_bf16 v[30:33], v[78:81], v[126:129], v[30:33]
	v_mfma_f32_16x16x32_bf16 v[22:25], v[86:89], v[126:129], v[22:25]
	v_mfma_f32_16x16x32_bf16 v[14:17], v[78:81], v[134:137], v[14:17]
	v_mfma_f32_16x16x32_bf16 v[6:9], v[86:89], v[134:137], v[6:9]
	v_mfma_f32_16x16x32_bf16 v[50:53], v[90:93], v[106:109], v[50:53]
	v_mfma_f32_16x16x32_bf16 v[46:49], v[98:101], v[106:109], v[46:49]
	v_mfma_f32_16x16x32_bf16 v[42:45], v[90:93], v[114:117], v[42:45]
	v_mfma_f32_16x16x32_bf16 v[34:37], v[98:101], v[114:117], v[34:37]
	v_mfma_f32_16x16x32_bf16 v[26:29], v[90:93], v[122:125], v[26:29]
	v_mfma_f32_16x16x32_bf16 v[18:21], v[98:101], v[122:125], v[18:21]
	v_mfma_f32_16x16x32_bf16 v[10:13], v[90:93], v[130:133], v[10:13]
	v_mfma_f32_16x16x32_bf16 v[2:5], v[98:101], v[130:133], v[2:5]
	v_mfma_f32_16x16x32_bf16 v[50:53], v[94:97], v[110:113], v[50:53]
	v_mfma_f32_16x16x32_bf16 v[46:49], v[102:105], v[110:113], v[46:49]
	v_mfma_f32_16x16x32_bf16 v[42:45], v[94:97], v[118:121], v[42:45]
	v_mfma_f32_16x16x32_bf16 v[34:37], v[102:105], v[118:121], v[34:37]
	v_mfma_f32_16x16x32_bf16 v[26:29], v[94:97], v[126:129], v[26:29]
	v_mfma_f32_16x16x32_bf16 v[18:21], v[102:105], v[126:129], v[18:21]
	v_mfma_f32_16x16x32_bf16 v[10:13], v[94:97], v[134:137], v[10:13]
	v_mfma_f32_16x16x32_bf16 v[2:5], v[102:105], v[134:137], v[2:5]
	s_barrier
	s_setprio 0
	s_mov_b32 m0, s13
	s_mov_b32 s42, s78
	s_mov_b32 s43, s79
	buffer_load_dwordx4 v67, s[40:43], s28 offen lds
	s_mov_b32 m0, s14
	s_add_i32 s31, s28, 0x80000
	buffer_load_dwordx4 v69, s[40:43], s28 offen lds
	s_mov_b32 m0, s15
	s_nop 0
	buffer_load_dwordx4 v67, s[40:43], s31 offen lds
	s_mov_b32 m0, s16
	s_nop 0
	buffer_load_dwordx4 v69, s[40:43], s31 offen lds
	s_mov_b32 m0, s12
	s_nop 0
	buffer_load_dwordx4 v66, s[76:79], s29 offen lds
	s_mov_b32 m0, s18
	s_nop 0
	buffer_load_dwordx4 v68, s[76:79], s29 offen lds
	s_waitcnt vmcnt(6)
	s_barrier
	s_barrier
; #define PG8_STAGEX(rs, bufoff, soff, voff) do { _Pragma("unroll") for (int _i = 0; _i < 2; ++_i) \
;         __builtin_amdgcn_raw_ptr_buffer_load_lds(rs, (LAS unsigned*)(lds + (bufoff) + ldsw + _i * 8192), 16, (voff)[_i], (soff), 0, 0); } while (0)
; #define PG8_LDA(dst, b, h) do { _Pragma("unroll") for (int m = 0; m < 4; ++m) _Pragma("unroll") for (int k = 0; k < 2; ++k) dst[m][k] = *(const LAS bf16x8*)(lds + PG8_SA(b, h) + aoff + m * 2048 + k * 1024); } while (0)
; #define PG8_LDB(dst, b, h) do { _Pragma("unroll") for (int n = 0; n < 2; ++n) _Pragma("unroll") for (int k = 0; k < 2; ++k) dst[n][k] = *(const LAS bf16x8*)(lds + PG8_SB(b, h) + boff + n * 2048 + k * 1024); } while (0)
; #define PG8_WAIT_V(n) asm volatile("s_waitcnt vmcnt(" #n ")" ::: "memory")
; #define PG8_WAIT_L(n) asm volatile("s_waitcnt lgkmcnt(" #n ")" ::: "memory")
; #define PG8_BAR __builtin_amdgcn_s_barrier()
; #define PG8_SCHED __builtin_amdgcn_sched_barrier(0)
;     ...
;                 if (w0) { PG8_LDB(B0, 1, 0); PG8_LDB(B1, 1, 1); PG8_SCHED; PG8_LDA(At, 1, 0); }
;                 PG8_WAIT_L(0); PG8_BAR; if (w0) { PG8_MMA(0, 0, At, B0); PG8_MMA(0, 1, At, B1); } PG8_BAR; PG8_SCHED;
;                 PG8_STAGEX(rsB, PG8_SB(1, 0), b3, voffB); PG8_STAGEX(rsB, PG8_SB(1, 1), b3 + hstepB, voffB); PG8_STAGEX(rsA, PG8_SA(1, 0), a3, voffA);
;                 PG8_WAIT_V(6); PG8_BAR; PG8_BAR; PG8_SCHED;
;             }
;         }
;         if (wr == 0) PG8_BAR;
	v_add_u32_e32 v86, 0x18000, v72
	v_add_u32_e32 v102, 0x1c000, v72
	ds_read_b128 v[74:77], v86
	ds_read_b128 v[78:81], v86 offset:1024
	ds_read_b128 v[82:85], v86 offset:2048
	ds_read_b128 v[86:89], v86 offset:3072
	ds_read_b128 v[90:93], v102
	ds_read_b128 v[94:97], v102 offset:1024
	ds_read_b128 v[98:101], v102 offset:2048
	ds_read_b128 v[102:105], v102 offset:3072
	ds_read_b128 v[106:109], v73 offset:32768
	ds_read_b128 v[110:113], v73 offset:33792
	ds_read_b128 v[114:117], v73 offset:34816
	ds_read_b128 v[118:121], v73 offset:35840
	ds_read_b128 v[122:125], v73 offset:36864
	ds_read_b128 v[126:129], v73 offset:37888
	ds_read_b128 v[130:133], v73 offset:38912
	ds_read_b128 v[134:137], v73 offset:39936
	s_waitcnt lgkmcnt(0)
	s_setprio 1
	s_barrier
	v_mfma_f32_16x16x32_bf16 v[62:65], v[74:77], v[106:109], v[62:65]
	v_mfma_f32_16x16x32_bf16 v[58:61], v[82:85], v[106:109], v[58:61]
	v_mfma_f32_16x16x32_bf16 v[54:57], v[74:77], v[114:117], v[54:57]
	v_mfma_f32_16x16x32_bf16 v[38:41], v[82:85], v[114:117], v[38:41]
	v_mfma_f32_16x16x32_bf16 v[30:33], v[74:77], v[122:125], v[30:33]
	v_mfma_f32_16x16x32_bf16 v[22:25], v[82:85], v[122:125], v[22:25]
	v_mfma_f32_16x16x32_bf16 v[14:17], v[74:77], v[130:133], v[14:17]
	v_mfma_f32_16x16x32_bf16 v[6:9], v[82:85], v[130:133], v[6:9]
	v_mfma_f32_16x16x32_bf16 v[62:65], v[78:81], v[110:113], v[62:65]
	v_mfma_f32_16x16x32_bf16 v[58:61], v[86:89], v[110:113], v[58:61]
	v_mfma_f32_16x16x32_bf16 v[54:57], v[78:81], v[118:121], v[54:57]
	v_mfma_f32_16x16x32_bf16 v[38:41], v[86:89], v[118:121], v[38:41]
	v_mfma_f32_16x16x32_bf16 v[30:33], v[78:81], v[126:129], v[30:33]
	v_mfma_f32_16x16x32_bf16 v[22:25], v[86:89], v[126:129], v[22:25]
	v_mfma_f32_16x16x32_bf16 v[14:17], v[78:81], v[134:137], v[14:17]
	v_mfma_f32_16x16x32_bf16 v[6:9], v[86:89], v[134:137], v[6:9]
	v_mfma_f32_16x16x32_bf16 v[50:53], v[90:93], v[106:109], v[50:53]
	s_or_b32 s29, s28, 0x80
	v_mfma_f32_16x16x32_bf16 v[46:49], v[98:101], v[106:109], v[46:49]
	v_mfma_f32_16x16x32_bf16 v[42:45], v[90:93], v[114:117], v[42:45]
	v_mfma_f32_16x16x32_bf16 v[34:37], v[98:101], v[114:117], v[34:37]
	v_mfma_f32_16x16x32_bf16 v[26:29], v[90:93], v[122:125], v[26:29]
	v_mfma_f32_16x16x32_bf16 v[18:21], v[98:101], v[122:125], v[18:21]
	v_mfma_f32_16x16x32_bf16 v[10:13], v[90:93], v[130:133], v[10:13]
	v_mfma_f32_16x16x32_bf16 v[2:5], v[98:101], v[130:133], v[2:5]
	v_mfma_f32_16x16x32_bf16 v[50:53], v[94:97], v[110:113], v[50:53]
	v_mfma_f32_16x16x32_bf16 v[46:49], v[102:105], v[110:113], v[46:49]
	v_mfma_f32_16x16x32_bf16 v[42:45], v[94:97], v[118:121], v[42:45]
	v_mfma_f32_16x16x32_bf16 v[34:37], v[102:105], v[118:121], v[34:37]
	v_mfma_f32_16x16x32_bf16 v[26:29], v[94:97], v[126:129], v[26:29]
	v_mfma_f32_16x16x32_bf16 v[18:21], v[102:105], v[126:129], v[18:21]
	v_mfma_f32_16x16x32_bf16 v[10:13], v[94:97], v[134:137], v[10:13]
	v_mfma_f32_16x16x32_bf16 v[2:5], v[102:105], v[134:137], v[2:5]
	s_barrier
	s_setprio 0
	s_mov_b32 m0, s20
	s_add_i32 s28, s28, 0x80080
	buffer_load_dwordx4 v67, s[40:43], s29 offen lds
	s_mov_b32 m0, s21
	s_nop 0
	buffer_load_dwordx4 v69, s[40:43], s29 offen lds
	s_mov_b32 m0, s24
	s_nop 0
	buffer_load_dwordx4 v67, s[40:43], s28 offen lds
	s_mov_b32 m0, s25
	s_nop 0
	buffer_load_dwordx4 v69, s[40:43], s28 offen lds
	s_mov_b32 m0, s22
	s_nop 0
	buffer_load_dwordx4 v66, s[76:79], s30 offen lds
	s_mov_b32 m0, s23
	s_nop 0
	buffer_load_dwordx4 v68, s[76:79], s30 offen lds
	s_waitcnt vmcnt(6)
	s_barrier
	s_barrier
	s_addk_i32 s26, 0x100
	s_add_i32 s27, s27, 2
	s_cmp_gt_u32 s27, 29
	s_cbranch_scc0 .LBB0_1668
	s_cmpk_lt_u32 s11, 0x100
	s_cbranch_scc0 .LBB0_1671
	s_barrier

; #define PG8_STAGEX(rs, bufoff, soff, voff) do { _Pragma("unroll") for (int _i = 0; _i < 2; ++_i) \
;         __builtin_amdgcn_raw_ptr_buffer_load_lds(rs, (LAS unsigned*)(lds + (bufoff) + ldsw + _i * 8192), 16, (voff)[_i], (soff), 0, 0); } while (0)
; #define PG8_LDA(dst, b, h) do { _Pragma("unroll") for (int m = 0; m < 4; ++m) _Pragma("unroll") for (int k = 0; k < 2; ++k) dst[m][k] = *(const LAS bf16x8*)(lds + PG8_SA(b, h) + aoff + m * 2048 + k * 1024); } while (0)
; #define PG8_LDB(dst, b, h) do { _Pragma("unroll") for (int n = 0; n < 2; ++n) _Pragma("unroll") for (int k = 0; k < 2; ++k) dst[n][k] = *(const LAS bf16x8*)(lds + PG8_SB(b, h) + boff + n * 2048 + k * 1024); } while (0)
; #define PG8_WAIT_V(n) asm volatile("s_waitcnt vmcnt(" #n ")" ::: "memory")
; #define PG8_WAIT_L(n) asm volatile("s_waitcnt lgkmcnt(" #n ")" ::: "memory")
; #define PG8_BAR __builtin_amdgcn_s_barrier()
; #define PG8_SCHED __builtin_amdgcn_sched_barrier(0)
;     ...
;             const bool last = (t == nt - 2);
;             const unsigned a1 = cA + (unsigned)(t + 1) * kstep;
;             const unsigned a2 = last ? nA : cA + (unsigned)(t + 2) * kstep, b2 = last ? nB : cB + (unsigned)(t + 2) * kstep;
;             const unsigned a3 = a2 + kstep, b3 = b2 + kstep;
;             PG8_LDB(B0, 0, 0); PG8_LDB(B1, 0, 1); PG8_SCHED; PG8_LDA(At, 0, 0); PG8_STAGEX(rsA, PG8_SA(1, 1), a1 + hstepA, voffA);
;             PG8_WAIT_V(8); PG8_WAIT_L(0); PG8_BAR; PG8_MMA(0, 0, At, B0); PG8_MMA(0, 1, At, B1); PG8_BAR; PG8_SCHED;
;             PG8_LDA(At, 0, 1); PG8_STAGEX(rsB, PG8_SB(0, 0), b2, voffB); PG8_STAGEX(rsB, PG8_SB(0, 1), b2 + hstepB, voffB); PG8_STAGEX(rsA, PG8_SA(0, 0), a2, voffA);
;             PG8_WAIT_V(8); PG8_WAIT_L(0); PG8_BAR; PG8_MMA(1, 0, At, B0); PG8_MMA(1, 1, At, B1); PG8_BAR; PG8_SCHED;
.LBB0_1750:
	v_add_u32_e32 v70, 0x10000, v241
	ds_read_b128 v[134:137], v70
	ds_read_b128 v[138:141], v70 offset:1024
	ds_read_b128 v[142:145], v70 offset:2048
	ds_read_b128 v[146:149], v70 offset:3072
	v_add_u32_e32 v70, 0x14000, v241
	ds_read_b128 v[150:153], v70
	ds_read_b128 v[154:157], v70 offset:1024
	ds_read_b128 v[158:161], v70 offset:2048
	ds_read_b128 v[162:165], v70 offset:3072
	s_add_i32 s46, s40, 0xffea8080
	s_cmpk_eq_i32 s60, 0x52
	s_cselect_b32 s63, s30, s46
	s_cselect_b32 s62, s31, s41
	s_or_b32 s61, s63, 0x80
	s_mov_b32 m0, s72
	ds_read_b128 v[166:169], v242
	ds_read_b128 v[170:173], v242 offset:1024
	ds_read_b128 v[184:187], v242 offset:2048
	ds_read_b128 v[188:191], v242 offset:3072
	ds_read_b128 v[192:195], v242 offset:4096
	ds_read_b128 v[196:199], v242 offset:5120
	ds_read_b128 v[200:203], v242 offset:6144
	ds_read_b128 v[204:207], v242 offset:7168
	buffer_load_dwordx4 v178, s[76:79], s40 offen lds
	s_mov_b32 m0, s73
	s_nop 0
	buffer_load_dwordx4 v237, s[76:79], s40 offen lds
	s_waitcnt vmcnt(8)
	s_waitcnt lgkmcnt(0)
	s_setprio 1
	s_barrier
	v_mfma_f32_16x16x32_bf16 v[130:133], v[134:137], v[166:169], v[130:133]
	v_mfma_f32_16x16x32_bf16 v[126:129], v[142:145], v[166:169], v[126:129]
	v_mfma_f32_16x16x32_bf16 v[122:125], v[134:137], v[184:187], v[122:125]
	v_mfma_f32_16x16x32_bf16 v[118:121], v[142:145], v[184:187], v[118:121]
	v_mfma_f32_16x16x32_bf16 v[114:117], v[134:137], v[192:195], v[114:117]
	v_mfma_f32_16x16x32_bf16 v[110:113], v[142:145], v[192:195], v[110:113]
	v_mfma_f32_16x16x32_bf16 v[106:109], v[134:137], v[200:203], v[106:109]
	v_mfma_f32_16x16x32_bf16 v[102:105], v[142:145], v[200:203], v[102:105]
	v_mfma_f32_16x16x32_bf16 v[130:133], v[138:141], v[170:173], v[130:133]
	v_mfma_f32_16x16x32_bf16 v[126:129], v[146:149], v[170:173], v[126:129]
	v_mfma_f32_16x16x32_bf16 v[122:125], v[138:141], v[188:191], v[122:125]
	v_mfma_f32_16x16x32_bf16 v[118:121], v[146:149], v[188:191], v[118:121]
	v_mfma_f32_16x16x32_bf16 v[114:117], v[138:141], v[196:199], v[114:117]
	v_mfma_f32_16x16x32_bf16 v[110:113], v[146:149], v[196:199], v[110:113]
	v_mfma_f32_16x16x32_bf16 v[106:109], v[138:141], v[204:207], v[106:109]
	v_mfma_f32_16x16x32_bf16 v[102:105], v[146:149], v[204:207], v[102:105]
	v_mfma_f32_16x16x32_bf16 v[62:65], v[150:153], v[166:169], v[62:65]
	v_mfma_f32_16x16x32_bf16 v[58:61], v[158:161], v[166:169], v[58:61]
	v_mfma_f32_16x16x32_bf16 v[54:57], v[150:153], v[184:187], v[54:57]
	v_mfma_f32_16x16x32_bf16 v[50:53], v[158:161], v[184:187], v[50:53]
	v_mfma_f32_16x16x32_bf16 v[46:49], v[150:153], v[192:195], v[46:49]
	v_mfma_f32_16x16x32_bf16 v[42:45], v[158:161], v[192:195], v[42:45]
	v_mfma_f32_16x16x32_bf16 v[38:41], v[150:153], v[200:203], v[38:41]
	v_mfma_f32_16x16x32_bf16 v[34:37], v[158:161], v[200:203], v[34:37]
	v_mfma_f32_16x16x32_bf16 v[62:65], v[154:157], v[170:173], v[62:65]
	v_mfma_f32_16x16x32_bf16 v[58:61], v[162:165], v[170:173], v[58:61]
	v_mfma_f32_16x16x32_bf16 v[54:57], v[154:157], v[188:191], v[54:57]
	v_mfma_f32_16x16x32_bf16 v[50:53], v[162:165], v[188:191], v[50:53]
	v_mfma_f32_16x16x32_bf16 v[46:49], v[154:157], v[196:199], v[46:49]
	v_mfma_f32_16x16x32_bf16 v[42:45], v[162:165], v[196:199], v[42:45]
	v_mfma_f32_16x16x32_bf16 v[38:41], v[154:157], v[204:207], v[38:41]
	v_mfma_f32_16x16x32_bf16 v[34:37], v[162:165], v[204:207], v[34:37]
	s_barrier
	s_setprio 0
	s_mov_b32 m0, s17
	s_mov_b32 s46, s78
	s_mov_b32 s47, s79
	ds_read_b128 v[166:169], v242 offset:16384
	ds_read_b128 v[170:173], v242 offset:17408
	ds_read_b128 v[184:187], v242 offset:18432
	ds_read_b128 v[188:191], v242 offset:19456
	ds_read_b128 v[192:195], v242 offset:20480
	ds_read_b128 v[196:199], v242 offset:21504
	ds_read_b128 v[200:203], v242 offset:22528
	ds_read_b128 v[204:207], v242 offset:23552
	buffer_load_dwordx4 v179, s[44:47], s62 offen lds
	s_mov_b32 m0, s18
	s_add_i32 s64, s62, 0x158000
	buffer_load_dwordx4 v238, s[44:47], s62 offen lds
	s_mov_b32 m0, s19
	s_nop 0
	buffer_load_dwordx4 v179, s[44:47], s64 offen lds
	s_mov_b32 m0, s20
	s_nop 0
	buffer_load_dwordx4 v238, s[44:47], s64 offen lds
	s_mov_b32 m0, s16
	s_nop 0
	buffer_load_dwordx4 v178, s[76:79], s63 offen lds
	s_mov_b32 m0, s21
	s_nop 0
	buffer_load_dwordx4 v237, s[76:79], s63 offen lds
	s_waitcnt vmcnt(8)
	s_waitcnt lgkmcnt(0)
	s_setprio 1
	s_barrier
	v_mfma_f32_16x16x32_bf16 v[98:101], v[134:137], v[166:169], v[98:101]
	v_mfma_f32_16x16x32_bf16 v[94:97], v[142:145], v[166:169], v[94:97]
	v_mfma_f32_16x16x32_bf16 v[90:93], v[134:137], v[184:187], v[90:93]
	v_mfma_f32_16x16x32_bf16 v[86:89], v[142:145], v[184:187], v[86:89]
	v_mfma_f32_16x16x32_bf16 v[82:85], v[134:137], v[192:195], v[82:85]
	v_mfma_f32_16x16x32_bf16 v[76:79], v[142:145], v[192:195], v[78:81]
	v_mfma_f32_16x16x32_bf16 v[70:73], v[134:137], v[200:203], v[72:75]
	v_mfma_f32_16x16x32_bf16 v[66:69], v[142:145], v[200:203], v[66:69]
	v_mfma_f32_16x16x32_bf16 v[98:101], v[138:141], v[170:173], v[98:101]
	v_mfma_f32_16x16x32_bf16 v[94:97], v[146:149], v[170:173], v[94:97]
	v_mfma_f32_16x16x32_bf16 v[90:93], v[138:141], v[188:191], v[90:93]
	v_mfma_f32_16x16x32_bf16 v[86:89], v[146:149], v[188:191], v[86:89]
	v_mfma_f32_16x16x32_bf16 v[82:85], v[138:141], v[196:199], v[82:85]
	v_mfma_f32_16x16x32_bf16 v[76:79], v[146:149], v[196:199], v[76:79]
	v_mfma_f32_16x16x32_bf16 v[70:73], v[138:141], v[204:207], v[70:73]
	v_mfma_f32_16x16x32_bf16 v[66:69], v[146:149], v[204:207], v[66:69]
	v_mfma_f32_16x16x32_bf16 v[30:33], v[150:153], v[166:169], v[30:33]
	v_mfma_f32_16x16x32_bf16 v[26:29], v[158:161], v[166:169], v[26:29]
	v_mfma_f32_16x16x32_bf16 v[22:25], v[150:153], v[184:187], v[22:25]
	v_mfma_f32_16x16x32_bf16 v[18:21], v[158:161], v[184:187], v[18:21]
	v_mfma_f32_16x16x32_bf16 v[14:17], v[150:153], v[192:195], v[14:17]
	v_mfma_f32_16x16x32_bf16 v[10:13], v[158:161], v[192:195], v[10:13]
	v_mfma_f32_16x16x32_bf16 v[6:9], v[150:153], v[200:203], v[6:9]
	v_mfma_f32_16x16x32_bf16 v[2:5], v[158:161], v[200:203], v[2:5]
	v_mfma_f32_16x16x32_bf16 v[30:33], v[154:157], v[170:173], v[30:33]
	v_mfma_f32_16x16x32_bf16 v[26:29], v[162:165], v[170:173], v[26:29]
	v_mfma_f32_16x16x32_bf16 v[22:25], v[154:157], v[188:191], v[22:25]
	v_mfma_f32_16x16x32_bf16 v[18:21], v[162:165], v[188:191], v[18:21]
	v_mfma_f32_16x16x32_bf16 v[14:17], v[154:157], v[196:199], v[14:17]
	v_mfma_f32_16x16x32_bf16 v[10:13], v[162:165], v[196:199], v[10:13]
	v_mfma_f32_16x16x32_bf16 v[6:9], v[154:157], v[204:207], v[6:9]
	v_mfma_f32_16x16x32_bf16 v[2:5], v[162:165], v[204:207], v[2:5]
	s_barrier
; #define PG8_STAGEX(rs, bufoff, soff, voff) do { _Pragma("unroll") for (int _i = 0; _i < 2; ++_i) \
;         __builtin_amdgcn_raw_ptr_buffer_load_lds(rs, (LAS unsigned*)(lds + (bufoff) + ldsw + _i * 8192), 16, (voff)[_i], (soff), 0, 0); } while (0)
; #define PG8_LDA(dst, b, h) do { _Pragma("unroll") for (int m = 0; m < 4; ++m) _Pragma("unroll") for (int k = 0; k < 2; ++k) dst[m][k] = *(const LAS bf16x8*)(lds + PG8_SA(b, h) + aoff + m * 2048 + k * 1024); } while (0)
; #define PG8_LDB(dst, b, h) do { _Pragma("unroll") for (int n = 0; n < 2; ++n) _Pragma("unroll") for (int k = 0; k < 2; ++k) dst[n][k] = *(const LAS bf16x8*)(lds + PG8_SB(b, h) + boff + n * 2048 + k * 1024); } while (0)
; #define PG8_WAIT_V(n) asm volatile("s_waitcnt vmcnt(" #n ")" ::: "memory")
; #define PG8_WAIT_L(n) asm volatile("s_waitcnt lgkmcnt(" #n ")" ::: "memory")
; #define PG8_BAR __builtin_amdgcn_s_barrier()
; #define PG8_SCHED __builtin_amdgcn_sched_barrier(0)
;     ...
;             PG8_WAIT_V(8); PG8_WAIT_L(0); PG8_BAR; PG8_MMA(1, 0, At, B0); PG8_MMA(1, 1, At, B1); PG8_BAR; PG8_SCHED;
;             PG8_LDB(B0, 1, 0); PG8_LDB(B1, 1, 1); PG8_SCHED; PG8_LDA(At, 1, 0); PG8_STAGEX(rsA, PG8_SA(0, 1), a2 + hstepA, voffA);
;             PG8_WAIT_V(8); PG8_WAIT_L(0); PG8_BAR; PG8_MMA(0, 0, At, B0); PG8_MMA(0, 1, At, B1); PG8_BAR; PG8_SCHED;
;             PG8_LDA(At, 1, 1); PG8_STAGEX(rsB, PG8_SB(1, 0), b3, voffB); PG8_STAGEX(rsB, PG8_SB(1, 1), b3 + hstepB, voffB); PG8_STAGEX(rsA, PG8_SA(1, 0), a3, voffA);
;             PG8_WAIT_V(8); PG8_WAIT_L(0); PG8_BAR; PG8_MMA(1, 0, At, B0); PG8_MMA(1, 1, At, B1); PG8_BAR; PG8_SCHED;
;         }
;     ...
;         if (wr == 0) PG8_BAR;
	s_setprio 0
	v_add_u32_e32 v74, 0x18000, v241
	ds_read_b128 v[134:137], v74
	ds_read_b128 v[138:141], v74 offset:1024
	ds_read_b128 v[142:145], v74 offset:2048
	ds_read_b128 v[146:149], v74 offset:3072
	v_add_u32_e32 v74, 0x1c000, v241
	ds_read_b128 v[150:153], v74
	ds_read_b128 v[154:157], v74 offset:1024
	ds_read_b128 v[158:161], v74 offset:2048
	ds_read_b128 v[162:165], v74 offset:3072
	s_add_i32 s63, s63, 0x158000
	s_mov_b32 m0, s22
	ds_read_b128 v[166:169], v242 offset:32768
	ds_read_b128 v[170:173], v242 offset:33792
	ds_read_b128 v[184:187], v242 offset:34816
	ds_read_b128 v[188:191], v242 offset:35840
	ds_read_b128 v[192:195], v242 offset:36864
	ds_read_b128 v[196:199], v242 offset:37888
	ds_read_b128 v[200:203], v242 offset:38912
	ds_read_b128 v[204:207], v242 offset:39936
	buffer_load_dwordx4 v178, s[76:79], s63 offen lds
	s_mov_b32 m0, s23
	s_nop 0
	buffer_load_dwordx4 v237, s[76:79], s63 offen lds
	s_waitcnt vmcnt(8)
	s_waitcnt lgkmcnt(0)
	s_setprio 1
	s_barrier
	v_mfma_f32_16x16x32_bf16 v[130:133], v[134:137], v[166:169], v[130:133]
	v_mfma_f32_16x16x32_bf16 v[126:129], v[142:145], v[166:169], v[126:129]
	v_mfma_f32_16x16x32_bf16 v[122:125], v[134:137], v[184:187], v[122:125]
	v_mfma_f32_16x16x32_bf16 v[118:121], v[142:145], v[184:187], v[118:121]
	v_mfma_f32_16x16x32_bf16 v[114:117], v[134:137], v[192:195], v[114:117]
	v_mfma_f32_16x16x32_bf16 v[110:113], v[142:145], v[192:195], v[110:113]
	v_mfma_f32_16x16x32_bf16 v[106:109], v[134:137], v[200:203], v[106:109]
	v_mfma_f32_16x16x32_bf16 v[102:105], v[142:145], v[200:203], v[102:105]
	v_mfma_f32_16x16x32_bf16 v[130:133], v[138:141], v[170:173], v[130:133]
	v_mfma_f32_16x16x32_bf16 v[126:129], v[146:149], v[170:173], v[126:129]
	v_mfma_f32_16x16x32_bf16 v[122:125], v[138:141], v[188:191], v[122:125]
	v_mfma_f32_16x16x32_bf16 v[118:121], v[146:149], v[188:191], v[118:121]
	v_mfma_f32_16x16x32_bf16 v[114:117], v[138:141], v[196:199], v[114:117]
	v_mfma_f32_16x16x32_bf16 v[110:113], v[146:149], v[196:199], v[110:113]
	v_mfma_f32_16x16x32_bf16 v[106:109], v[138:141], v[204:207], v[106:109]
	v_mfma_f32_16x16x32_bf16 v[102:105], v[146:149], v[204:207], v[102:105]
	v_mfma_f32_16x16x32_bf16 v[62:65], v[150:153], v[166:169], v[62:65]
	v_mfma_f32_16x16x32_bf16 v[58:61], v[158:161], v[166:169], v[58:61]
	v_mfma_f32_16x16x32_bf16 v[54:57], v[150:153], v[184:187], v[54:57]
	v_mfma_f32_16x16x32_bf16 v[50:53], v[158:161], v[184:187], v[50:53]
	v_mfma_f32_16x16x32_bf16 v[46:49], v[150:153], v[192:195], v[46:49]
	v_mfma_f32_16x16x32_bf16 v[42:45], v[158:161], v[192:195], v[42:45]
	v_mfma_f32_16x16x32_bf16 v[38:41], v[150:153], v[200:203], v[38:41]
	v_mfma_f32_16x16x32_bf16 v[34:37], v[158:161], v[200:203], v[34:37]
	v_mfma_f32_16x16x32_bf16 v[62:65], v[154:157], v[170:173], v[62:65]
	v_mfma_f32_16x16x32_bf16 v[58:61], v[162:165], v[170:173], v[58:61]
	v_mfma_f32_16x16x32_bf16 v[54:57], v[154:157], v[188:191], v[54:57]
	v_mfma_f32_16x16x32_bf16 v[50:53], v[162:165], v[188:191], v[50:53]
	v_mfma_f32_16x16x32_bf16 v[46:49], v[154:157], v[196:199], v[46:49]
	v_mfma_f32_16x16x32_bf16 v[42:45], v[162:165], v[196:199], v[42:45]
	v_mfma_f32_16x16x32_bf16 v[38:41], v[154:157], v[204:207], v[38:41]
	v_mfma_f32_16x16x32_bf16 v[34:37], v[162:165], v[204:207], v[34:37]
	s_barrier
	s_setprio 0
	s_mov_b32 m0, s54
	s_or_b32 s63, s62, 0x80
	ds_read_b128 v[166:169], v242 offset:49152
	ds_read_b128 v[170:173], v242 offset:50176
	ds_read_b128 v[184:187], v242 offset:51200
	ds_read_b128 v[188:191], v242 offset:52224
	ds_read_b128 v[192:195], v242 offset:53248
	ds_read_b128 v[196:199], v242 offset:54272
	ds_read_b128 v[200:203], v242 offset:55296
	ds_read_b128 v[204:207], v242 offset:56320
	buffer_load_dwordx4 v179, s[44:47], s63 offen lds
	s_mov_b32 m0, s55
	s_add_i32 s62, s62, 0x158080
	buffer_load_dwordx4 v238, s[44:47], s63 offen lds
	s_mov_b32 m0, s70
	s_nop 0
	buffer_load_dwordx4 v179, s[44:47], s62 offen lds
	s_mov_b32 m0, s71
	s_nop 0
	buffer_load_dwordx4 v238, s[44:47], s62 offen lds
	s_mov_b32 m0, s68
	s_nop 0
	buffer_load_dwordx4 v178, s[76:79], s61 offen lds
	s_mov_b32 m0, s69
	s_nop 0
	buffer_load_dwordx4 v237, s[76:79], s61 offen lds
	s_waitcnt vmcnt(8)
	s_waitcnt lgkmcnt(0)
	s_setprio 1
	s_barrier
	v_mfma_f32_16x16x32_bf16 v[98:101], v[134:137], v[166:169], v[98:101]
	v_mfma_f32_16x16x32_bf16 v[94:97], v[142:145], v[166:169], v[94:97]
	v_mfma_f32_16x16x32_bf16 v[90:93], v[134:137], v[184:187], v[90:93]
	v_mfma_f32_16x16x32_bf16 v[86:89], v[142:145], v[184:187], v[86:89]
	v_mfma_f32_16x16x32_bf16 v[80:83], v[134:137], v[192:195], v[82:85]
	v_mfma_f32_16x16x32_bf16 v[74:77], v[142:145], v[192:195], v[76:79]
	v_mfma_f32_16x16x32_bf16 v[70:73], v[134:137], v[200:203], v[70:73]
	v_mfma_f32_16x16x32_bf16 v[66:69], v[142:145], v[200:203], v[66:69]
	v_mfma_f32_16x16x32_bf16 v[98:101], v[138:141], v[170:173], v[98:101]
	v_mfma_f32_16x16x32_bf16 v[94:97], v[146:149], v[170:173], v[94:97]
	v_mfma_f32_16x16x32_bf16 v[90:93], v[138:141], v[188:191], v[90:93]
	v_mfma_f32_16x16x32_bf16 v[86:89], v[146:149], v[188:191], v[86:89]
	v_mfma_f32_16x16x32_bf16 v[82:85], v[138:141], v[196:199], v[80:83]
	v_mfma_f32_16x16x32_bf16 v[78:81], v[146:149], v[196:199], v[74:77]
	v_mfma_f32_16x16x32_bf16 v[72:75], v[138:141], v[204:207], v[70:73]
	v_mfma_f32_16x16x32_bf16 v[66:69], v[146:149], v[204:207], v[66:69]
	v_mfma_f32_16x16x32_bf16 v[30:33], v[150:153], v[166:169], v[30:33]
	v_mfma_f32_16x16x32_bf16 v[26:29], v[158:161], v[166:169], v[26:29]
	v_mfma_f32_16x16x32_bf16 v[22:25], v[150:153], v[184:187], v[22:25]
	v_mfma_f32_16x16x32_bf16 v[18:21], v[158:161], v[184:187], v[18:21]
	v_mfma_f32_16x16x32_bf16 v[14:17], v[150:153], v[192:195], v[14:17]
	v_mfma_f32_16x16x32_bf16 v[10:13], v[158:161], v[192:195], v[10:13]
	v_mfma_f32_16x16x32_bf16 v[6:9], v[150:153], v[200:203], v[6:9]
	v_mfma_f32_16x16x32_bf16 v[2:5], v[158:161], v[200:203], v[2:5]
	v_mfma_f32_16x16x32_bf16 v[30:33], v[154:157], v[170:173], v[30:33]
	v_mfma_f32_16x16x32_bf16 v[26:29], v[162:165], v[170:173], v[26:29]
	v_mfma_f32_16x16x32_bf16 v[22:25], v[154:157], v[188:191], v[22:25]
	v_mfma_f32_16x16x32_bf16 v[18:21], v[162:165], v[188:191], v[18:21]
	v_mfma_f32_16x16x32_bf16 v[14:17], v[154:157], v[196:199], v[14:17]
	v_mfma_f32_16x16x32_bf16 v[10:13], v[162:165], v[196:199], v[10:13]
	v_mfma_f32_16x16x32_bf16 v[6:9], v[154:157], v[204:207], v[6:9]
	v_mfma_f32_16x16x32_bf16 v[2:5], v[162:165], v[204:207], v[2:5]
	s_barrier
	s_setprio 0
	s_add_i32 s60, s60, 2
	s_addk_i32 s40, 0x100
	s_addk_i32 s41, 0x100
	s_cmpk_gt_u32 s60, 0x53
	s_cbranch_scc0 .LBB0_1750
	s_and_b64 vcc, exec, s[50:51]
	s_cbranch_vccz .LBB0_1753
	s_barrier
